# v70 + seams 5 and 7 XCD-local too: P3 cross-K units batch-aligned, write-through (sc1) stores for PROJ/ATT/CO, cross-XCD progress waits before a region is re-used (only seam 0 stays a grid barrier)
# speedup vs baseline: 1.0449x; 1.0171x over previous
; __global__ void __launch_bounds__(NWAVES * 64, 2) mk_fwd(Params P) {
;     ...
;             float pre = inc - p[7];
;             for (int w = 0; w < wave; ++w) pre += wt[w];
;             const float c = -1.4426950408889634f;
;             *(f32x4*)dst = (f32x4){(pre + p[0]) * c, (pre + p[1]) * c, (pre + p[2]) * c, (pre + p[3]) * c};
;             *(f32x4*)(dst + 4) = (f32x4){(pre + p[4]) * c, (pre + p[5]) * c, (pre + p[6]) * c, (pre + p[7]) * c};
;             __syncthreads();
.LBB0_223:
	s_and_b32 s0, s88, 7
	s_lshl_b32 s0, s0, 3
	s_lshr_b32 s1, s88, 3
	s_or_b32 s0, s0, s1
	s_lshl_b32 s0, s0, 14
	s_mov_b32 s1, 0
	s_add_u32 s0, s72, s0
	s_addc_u32 s1, s73, s1
	v_lshl_add_u64 v[4:5], v[4:5], 2, s[0:1]
	s_mov_b64 s[0:1], 0x1bf00000
	v_lshl_add_u64 v[16:17], v[4:5], 0, s[0:1]
	v_pk_add_f32 v[0:1], v[0:1], v[10:11] op_sel_hi:[1,0]
	v_pk_add_f32 v[8:9], v[8:9], v[10:11] op_sel_hi:[1,0]
	s_mov_b32 s0, 0xbfb8aa3b
	v_pk_mul_f32 v[14:15], v[8:9], s[0:1] op_sel_hi:[1,0]
	v_pk_mul_f32 v[12:13], v[0:1], s[0:1] op_sel_hi:[1,0]
	s_mov_b32 s1, 0x1bf00000
	v_add_co_u32_e32 v0, vcc, s1, v4
	v_pk_add_f32 v[2:3], v[2:3], v[10:11] op_sel_hi:[1,0]
	s_nop 0
	v_addc_co_u32_e32 v1, vcc, 0, v5, vcc
	global_store_dwordx4 v[0:1], v[12:15], off sc1
	v_pk_add_f32 v[0:1], v[6:7], v[10:11] op_sel_hi:[1,0]
	v_pk_mul_f32 v[2:3], v[2:3], s[0:1] op_sel_hi:[1,0]
	v_pk_mul_f32 v[0:1], v[0:1], s[0:1] op_sel_hi:[1,0]
	global_store_dwordx4 v[16:17], v[0:3], off offset:16 sc1
	s_barrier

; __device__ __forceinline__ unsigned cvt_pk_bf16(float lo, float hi) { unsigned r; asm volatile("v_cvt_pk_bf16_f32 %0, %1, %2" : "=v"(r) : "v"(lo), "v"(hi)); return r; }
;     __device__ __forceinline__ void operator()(const f32x4 (&acc)[2][2][4][2], const Unit& u, int wr, int wc, int fr, int fq) const {
;     ...
;                 bf16_t* rowp = O + (size_t)row * 3072 + col0;
;                 const float scr = sc * (slot >= 0 ? tab[slot * 256 + (row - u.pm * BM)] : row_rstd(ssp, row, 1e-6f));
;                 f32x4 c0 = {1.f, 1.f, 1.f, 1.f}, c1 = c0, s0 = {0.f, 0.f, 0.f, 0.f}, s1 = s0;
;                 if (ropew) { c0 = rc[m][0]; c1 = rc[m][1]; s0 = rc[m][2]; s1 = rc[m][3]; if (fq == 0) { s0 = -s0; s1 = -s1; } if (fq >= 2) { c0 = (f32x4){1.f, 1.f, 1.f, 1.f}; c1 = c0; s0 = (f32x4){0.f, 0.f, 0.f, 0.f}; s1 = s0; } }
; #pragma unroll
;                 for (int bj = 0; bj < 2; ++bj) {
;                     f32x4 v0 = acc[ai][bj][m][0], v1 = acc[ai][bj][m][1];
;                     if (ropew) {
;                         f32x4 p0, p1;
; #pragma unroll
;                         for (int e = 0; e < 4; ++e) { p0[e] = __shfl_xor(v0[e], 16); p1[e] = __shfl_xor(v1[e], 16); }
;                         v0 = v0 * c0 + p0 * s0; v1 = v1 * c1 + p1 * s1;
;                     }
;                     v0 = v0 * scr; v1 = v1 * scr;
;                     if (nrmw) { float q = (v0[0] * v0[0] + v0[1] * v0[1]) + (v0[2] * v0[2] + v0[3] * v0[3]) + (v1[0] * v1[0] + v1[1] * v1[1]) + (v1[2] * v1[2] + v1[3] * v1[3]);
;                         q += __shfl_xor(q, 16); q += __shfl_xor(q, 32); mxn[bj] = fmaxf(mxn[bj], q); }
;                     u32x4 w; w.x = cvt_pk_bf16(v0[0], v0[1]); w.y = cvt_pk_bf16(v0[2], v0[3]); w.z = cvt_pk_bf16(v1[0], v1[1]); w.w = cvt_pk_bf16(v1[2], v1[3]);
;                     *(u32x4*)(rowp + bj * HALF) = w;
.LBB0_296:
	s_lshl_b32 s49, s16, 8
	v_or_b32_e32 v184, s49, v241
	v_mov_b64_e32 v[186:187], s[28:29]
	v_ashrrev_i32_e32 v185, 31, v184
	v_mad_i64_i32 v[186:187], s[0:1], v208, s86, v[186:187]
	v_lshl_add_u64 v[186:187], v[184:185], 1, v[186:187]
	s_and_b64 vcc, exec, s[12:13]
	v_cvt_pk_bf16_f32 v188, v188, v189
	v_cvt_pk_bf16_f32 v189, v190, v191
	v_cvt_pk_bf16_f32 v190, v232, v233
	v_cvt_pk_bf16_f32 v191, v230, v231
	global_store_dwordx4 v[186:187], v[188:191], off sc1
	s_cbranch_vccnz .LBB0_298
	ds_bpermute_b32 v188, v235, v180
	ds_bpermute_b32 v189, v235, v181
	ds_bpermute_b32 v190, v235, v176
	ds_bpermute_b32 v204, v235, v182
	ds_bpermute_b32 v205, v235, v183
	ds_bpermute_b32 v191, v235, v177
	ds_bpermute_b32 v230, v235, v178
	ds_bpermute_b32 v231, v235, v179
	s_waitcnt lgkmcnt(0)
	v_pk_mul_f32 v[188:189], v[220:221], v[188:189]
	v_pk_mul_f32 v[204:205], v[222:223], v[204:205]
	v_pk_fma_f32 v[180:181], v[180:181], v[226:227], v[188:189]
	v_pk_mul_f32 v[188:189], v[216:217], v[190:191]
	v_pk_mul_f32 v[190:191], v[214:215], v[230:231]
	v_pk_fma_f32 v[182:183], v[182:183], v[224:225], v[204:205]
	v_pk_fma_f32 v[178:179], v[178:179], v[210:211], v[190:191]
	v_pk_fma_f32 v[176:177], v[176:177], v[218:219], v[188:189]

; __device__ __forceinline__ unsigned cvt_pk_bf16(float lo, float hi) { unsigned r; asm volatile("v_cvt_pk_bf16_f32 %0, %1, %2" : "=v"(r) : "v"(lo), "v"(hi)); return r; }
; __device__ __forceinline__ float row_rstd(const float* part, int row, float eps) {
;     const f32x4* p = (const f32x4*)(part + (size_t)row * 16);
;     const f32x4 a = p[0], b = p[1], c = p[2], d = p[3];
;     const float s = ((a[0] + a[1]) + (a[2] + a[3])) + ((b[0] + b[1]) + (b[2] + b[3])) + ((c[0] + c[1]) + (c[2] + c[3])) + ((d[0] + d[1]) + (d[2] + d[3]));
;     return 1.0f / sqrtf(s * (1.0f / 1024.0f) + eps);
; }
;     __device__ __forceinline__ void operator()(const f32x4 (&acc)[2][2][4][2], const Unit& u, int wr, int wc, int fr, int fq) const {
;     ...
;                 const int row = row0 + ai * HALF + m * 16;
;                 bf16_t* rowp = O + (size_t)row * 3072 + col0;
;                 const float scr = sc * (slot >= 0 ? tab[slot * 256 + (row - u.pm * BM)] : row_rstd(ssp, row, 1e-6f));
;                 f32x4 c0 = {1.f, 1.f, 1.f, 1.f}, c1 = c0, s0 = {0.f, 0.f, 0.f, 0.f}, s1 = s0;
;                 if (ropew) { c0 = rc[m][0]; c1 = rc[m][1]; s0 = rc[m][2]; s1 = rc[m][3]; if (fq == 0) { s0 = -s0; s1 = -s1; } if (fq >= 2) { c0 = (f32x4){1.f, 1.f, 1.f, 1.f}; c1 = c0; s0 = (f32x4){0.f, 0.f, 0.f, 0.f}; s1 = s0; } }
; #pragma unroll
;                 for (int bj = 0; bj < 2; ++bj) {
;                     f32x4 v0 = acc[ai][bj][m][0], v1 = acc[ai][bj][m][1];
;                     if (ropew) {
;                         f32x4 p0, p1;
; #pragma unroll
;                         for (int e = 0; e < 4; ++e) { p0[e] = __shfl_xor(v0[e], 16); p1[e] = __shfl_xor(v1[e], 16); }
;                         v0 = v0 * c0 + p0 * s0; v1 = v1 * c1 + p1 * s1;
;                     }
;                     v0 = v0 * scr; v1 = v1 * scr;
;                     if (nrmw) { float q = (v0[0] * v0[0] + v0[1] * v0[1]) + (v0[2] * v0[2] + v0[3] * v0[3]) + (v1[0] * v1[0] + v1[1] * v1[1]) + (v1[2] * v1[2] + v1[3] * v1[3]);
;                         q += __shfl_xor(q, 16); q += __shfl_xor(q, 32); mxn[bj] = fmaxf(mxn[bj], q); }
;                     u32x4 w; w.x = cvt_pk_bf16(v0[0], v0[1]); w.y = cvt_pk_bf16(v0[2], v0[3]); w.z = cvt_pk_bf16(v1[0], v1[1]); w.w = cvt_pk_bf16(v1[2], v1[3]);
;                     *(u32x4*)(rowp + bj * HALF) = w;
.LBB0_302:
	v_cvt_pk_bf16_f32 v180, v180, v181
	v_cvt_pk_bf16_f32 v181, v182, v183
	v_cvt_pk_bf16_f32 v182, v176, v177
	v_cvt_pk_bf16_f32 v183, v178, v179
	v_or_b32_e32 v176, 16, v208
	v_cndmask_b32_e64 v178, 0, 1, s[18:19]
	v_ashrrev_i32_e32 v177, 31, v176
	v_cmp_ne_u32_e64 s[16:17], 1, v178
	s_andn2_b64 vcc, exec, s[18:19]
	s_mov_b64 s[0:1], -1
	global_store_dwordx4 v[186:187], v[180:183], off offset:256 sc1
	v_and_b32_e32 v226, 15, v212
	v_lshrrev_b32_e32 v227, 2, v212
	v_sub_u32_e32 v227, v227, v226
	v_lshrrev_b32_e32 v226, 4, v212
	v_and_b32_e32 v253, 3, v212
	v_sub_u32_e32 v226, v253, v226
	v_lshlrev_b32_e32 v226, 4, v226
	v_mul_i32_i24_e32 v228, 0x1800, v227
	v_add_u32_e32 v228, v228, v226
	v_ashrrev_i32_e32 v229, 31, v228
	v_lshlrev_b32_e32 v253, 4, v253
	v_lshrrev_b32_e32 v226, 2, v212
	v_add_u32_e32 v253, v253, v226
	v_lshlrev_b32_e32 v253, 2, v253
	s_cbranch_vccnz .LBB0_308
	v_lshlrev_b64 v[178:179], 6, v[176:177]
	v_lshl_add_u64 v[182:183], s[22:23], 0, v[178:179]
	global_load_dwordx4 v[178:181], v[182:183], off offset:48
	global_load_dwordx4 v[186:189], v[182:183], off offset:32
	global_load_dwordx4 v[214:217], v[182:183], off offset:16
	global_load_dwordx4 v[222:225], v[182:183], off
	s_waitcnt vmcnt(0)
	v_add_f32_e32 v186, v186, v187
	v_mov_b32_e32 v190, v215
	v_mov_b32_e32 v182, v223
	v_mov_b32_e32 v183, v224
	v_mov_b32_e32 v223, v225
	v_mov_b32_e32 v191, v216
	v_mov_b32_e32 v215, v217
	v_pk_add_f32 v[182:183], v[182:183], v[222:223]
	v_pk_add_f32 v[190:191], v[190:191], v[214:215]
	v_pk_add_f32 v[182:183], v[182:183], v[182:183] op_sel:[0,1] op_sel_hi:[1,0]
	v_pk_add_f32 v[190:191], v[190:191], v[190:191] op_sel:[0,1] op_sel_hi:[1,0]
	v_add_f32_e32 v188, v188, v189
	v_mov_b32_e32 v183, v178
	v_mov_b32_e32 v191, v179
	v_mov_b32_e32 v187, v180
	v_mov_b32_e32 v189, v181
	v_pk_add_f32 v[178:179], v[182:183], v[190:191]
	v_pk_add_f32 v[180:181], v[186:187], v[188:189]
	s_nop 0
	v_pk_add_f32 v[178:179], v[178:179], v[180:181]
	s_nop 0
	v_add_f32_e32 v177, v178, v179
	v_fmamk_f32 v177, v177, 0x3a800000, v246
	v_cmp_gt_f32_e32 vcc, s83, v177
	v_mul_f32_e32 v178, 0x4f800000, v177
	s_nop 0
	v_cndmask_b32_e32 v177, v177, v178, vcc
	v_sqrt_f32_e32 v178, v177
	s_nop 0
	v_add_u32_e32 v179, -1, v178
	v_fma_f32 v180, -v179, v178, v177
	v_cmp_ge_f32_e64 s[0:1], 0, v180
	v_add_u32_e32 v180, 1, v178
	s_nop 0
	v_cndmask_b32_e64 v179, v178, v179, s[0:1]
	v_fma_f32 v178, -v180, v178, v177
	v_cmp_lt_f32_e64 s[0:1], 0, v178
	s_nop 1
	v_cndmask_b32_e64 v178, v179, v180, s[0:1]
	v_mul_f32_e32 v179, 0x37800000, v178
	v_cndmask_b32_e32 v178, v178, v179, vcc
	v_cmp_class_f32_e32 vcc, v177, v247
	s_nop 1
	v_cndmask_b32_e32 v177, v178, v177, vcc
	v_div_scale_f32 v178, s[0:1], v177, v177, 1.0
	v_rcp_f32_e32 v179, v178
	s_nop 0
	v_fma_f32 v180, -v178, v179, 1.0
	v_fmac_f32_e32 v179, v180, v179
	v_div_scale_f32 v180, vcc, 1.0, v177, 1.0
	v_mul_f32_e32 v181, v180, v179
	v_fma_f32 v182, -v178, v181, v180
	v_fmac_f32_e32 v181, v182, v179
	v_fma_f32 v178, -v178, v181, v180
	v_div_fmas_f32 v178, v178, v179, v181
	v_div_fixup_f32 v216, v178, v177, 1.0
	s_cbranch_execz .LBB0_309

; __device__ __forceinline__ unsigned cvt_pk_bf16(float lo, float hi) { unsigned r; asm volatile("v_cvt_pk_bf16_f32 %0, %1, %2" : "=v"(r) : "v"(lo), "v"(hi)); return r; }
; __device__ __forceinline__ float row_rstd(const float* part, int row, float eps) {
;     const f32x4* p = (const f32x4*)(part + (size_t)row * 16);
;     const f32x4 a = p[0], b = p[1], c = p[2], d = p[3];
;     const float s = ((a[0] + a[1]) + (a[2] + a[3])) + ((b[0] + b[1]) + (b[2] + b[3])) + ((c[0] + c[1]) + (c[2] + c[3])) + ((d[0] + d[1]) + (d[2] + d[3]));
;     return 1.0f / sqrtf(s * (1.0f / 1024.0f) + eps);
; }
;     __device__ __forceinline__ void operator()(const f32x4 (&acc)[2][2][4][2], const Unit& u, int wr, int wc, int fr, int fq) const {
;     ...
;                 const int row = row0 + ai * HALF + m * 16;
;                 bf16_t* rowp = O + (size_t)row * 3072 + col0;
;                 const float scr = sc * (slot >= 0 ? tab[slot * 256 + (row - u.pm * BM)] : row_rstd(ssp, row, 1e-6f));
;                 f32x4 c0 = {1.f, 1.f, 1.f, 1.f}, c1 = c0, s0 = {0.f, 0.f, 0.f, 0.f}, s1 = s0;
;                 if (ropew) { c0 = rc[m][0]; c1 = rc[m][1]; s0 = rc[m][2]; s1 = rc[m][3]; if (fq == 0) { s0 = -s0; s1 = -s1; } if (fq >= 2) { c0 = (f32x4){1.f, 1.f, 1.f, 1.f}; c1 = c0; s0 = (f32x4){0.f, 0.f, 0.f, 0.f}; s1 = s0; } }
; #pragma unroll
;                 for (int bj = 0; bj < 2; ++bj) {
;                     f32x4 v0 = acc[ai][bj][m][0], v1 = acc[ai][bj][m][1];
;                     if (ropew) {
;                         f32x4 p0, p1;
; #pragma unroll
;                         for (int e = 0; e < 4; ++e) { p0[e] = __shfl_xor(v0[e], 16); p1[e] = __shfl_xor(v1[e], 16); }
;                         v0 = v0 * c0 + p0 * s0; v1 = v1 * c1 + p1 * s1;
;                     }
;                     v0 = v0 * scr; v1 = v1 * scr;
;                     if (nrmw) { float q = (v0[0] * v0[0] + v0[1] * v0[1]) + (v0[2] * v0[2] + v0[3] * v0[3]) + (v1[0] * v1[0] + v1[1] * v1[1]) + (v1[2] * v1[2] + v1[3] * v1[3]);
;                         q += __shfl_xor(q, 16); q += __shfl_xor(q, 32); mxn[bj] = fmaxf(mxn[bj], q); }
;                     u32x4 w; w.x = cvt_pk_bf16(v0[0], v0[1]); w.y = cvt_pk_bf16(v0[2], v0[3]); w.z = cvt_pk_bf16(v1[0], v1[1]); w.w = cvt_pk_bf16(v1[2], v1[3]);
;                     *(u32x4*)(rowp + bj * HALF) = w;
.LBB0_322:
	v_cvt_pk_bf16_f32 v164, v164, v165
	v_cvt_pk_bf16_f32 v165, v166, v167
	v_cvt_pk_bf16_f32 v166, v160, v161
	v_or_b32_e32 v160, 32, v208
	v_ashrrev_i32_e32 v161, 31, v160
	s_and_b64 vcc, exec, s[16:17]
	s_mov_b64 s[0:1], -1
	v_cvt_pk_bf16_f32 v167, v162, v163
	ds_bpermute_b32 v214, v253, v164
	ds_bpermute_b32 v215, v253, v165
	ds_bpermute_b32 v216, v253, v166
	ds_bpermute_b32 v217, v253, v167
	v_lshl_add_u64 v[218:219], v[168:169], 0, v[228:229]
	s_waitcnt lgkmcnt(4)
	global_store_dwordx4 v[226:227], v[222:225], off sc1
	s_cbranch_vccnz .LBB0_328
	v_lshlrev_b64 v[162:163], 6, v[160:161]
	v_lshl_add_u64 v[174:175], s[22:23], 0, v[162:163]
	global_load_dwordx4 v[162:165], v[174:175], off offset:48
	global_load_dwordx4 v[166:169], v[174:175], off offset:32
	global_load_dwordx4 v[170:173], v[174:175], off offset:16
	s_nop 0
	global_load_dwordx4 v[174:177], v[174:175], off
	s_waitcnt vmcnt(0)
	v_add_f32_e32 v166, v166, v167
	v_add_f32_e32 v168, v168, v169
	v_mov_b32_e32 v178, v175
	v_mov_b32_e32 v179, v176
	v_mov_b32_e32 v175, v177
	v_mov_b32_e32 v176, v171
	v_mov_b32_e32 v177, v172
	v_mov_b32_e32 v171, v173
	v_pk_add_f32 v[174:175], v[178:179], v[174:175]
	v_pk_add_f32 v[170:171], v[176:177], v[170:171]
	v_pk_add_f32 v[174:175], v[174:175], v[174:175] op_sel:[0,1] op_sel_hi:[1,0]
	v_pk_add_f32 v[170:171], v[170:171], v[170:171] op_sel:[0,1] op_sel_hi:[1,0]
	v_mov_b32_e32 v175, v162
	v_mov_b32_e32 v171, v163
	v_mov_b32_e32 v167, v164
	v_mov_b32_e32 v169, v165
	v_pk_add_f32 v[162:163], v[174:175], v[170:171]
	v_pk_add_f32 v[164:165], v[166:167], v[168:169]
	s_nop 0
	v_pk_add_f32 v[162:163], v[162:163], v[164:165]
	s_nop 0
	v_add_f32_e32 v161, v162, v163
	v_fmamk_f32 v161, v161, 0x3a800000, v246
	v_cmp_gt_f32_e32 vcc, s83, v161
	v_mul_f32_e32 v162, 0x4f800000, v161
	s_nop 0
	v_cndmask_b32_e32 v161, v161, v162, vcc
	v_sqrt_f32_e32 v162, v161
	s_nop 0
	v_add_u32_e32 v163, -1, v162
	v_fma_f32 v164, -v163, v162, v161
	v_cmp_ge_f32_e64 s[0:1], 0, v164
	v_add_u32_e32 v164, 1, v162
	s_nop 0
	v_cndmask_b32_e64 v163, v162, v163, s[0:1]
	v_fma_f32 v162, -v164, v162, v161
	v_cmp_lt_f32_e64 s[0:1], 0, v162
	s_nop 1
	v_cndmask_b32_e64 v162, v163, v164, s[0:1]
	v_mul_f32_e32 v163, 0x37800000, v162
	v_cndmask_b32_e32 v162, v162, v163, vcc
	v_cmp_class_f32_e32 vcc, v161, v247
	s_nop 1
	v_cndmask_b32_e32 v161, v162, v161, vcc
	v_div_scale_f32 v162, s[0:1], v161, v161, 1.0
	v_rcp_f32_e32 v163, v162
	s_nop 0
	v_fma_f32 v164, -v162, v163, 1.0
	v_fmac_f32_e32 v163, v164, v163
	v_div_scale_f32 v164, vcc, 1.0, v161, 1.0
	v_mul_f32_e32 v165, v164, v163
	v_fma_f32 v166, -v162, v165, v164
	v_fmac_f32_e32 v165, v166, v163
	v_fma_f32 v162, -v162, v165, v164
	v_div_fmas_f32 v162, v162, v163, v165
	v_div_fixup_f32 v178, v162, v161, 1.0
	s_cbranch_execz .LBB0_329

; __device__ __forceinline__ unsigned cvt_pk_bf16(float lo, float hi) { unsigned r; asm volatile("v_cvt_pk_bf16_f32 %0, %1, %2" : "=v"(r) : "v"(lo), "v"(hi)); return r; }
;     __device__ __forceinline__ void operator()(const f32x4 (&acc)[2][2][4][2], const Unit& u, int wr, int wc, int fr, int fq) const {
;     ...
;                 bf16_t* rowp = O + (size_t)row * 3072 + col0;
;                 const float scr = sc * (slot >= 0 ? tab[slot * 256 + (row - u.pm * BM)] : row_rstd(ssp, row, 1e-6f));
;                 f32x4 c0 = {1.f, 1.f, 1.f, 1.f}, c1 = c0, s0 = {0.f, 0.f, 0.f, 0.f}, s1 = s0;
;                 if (ropew) { c0 = rc[m][0]; c1 = rc[m][1]; s0 = rc[m][2]; s1 = rc[m][3]; if (fq == 0) { s0 = -s0; s1 = -s1; } if (fq >= 2) { c0 = (f32x4){1.f, 1.f, 1.f, 1.f}; c1 = c0; s0 = (f32x4){0.f, 0.f, 0.f, 0.f}; s1 = s0; } }
; #pragma unroll
;                 for (int bj = 0; bj < 2; ++bj) {
;                     f32x4 v0 = acc[ai][bj][m][0], v1 = acc[ai][bj][m][1];
;                     if (ropew) {
;                         f32x4 p0, p1;
; #pragma unroll
;                         for (int e = 0; e < 4; ++e) { p0[e] = __shfl_xor(v0[e], 16); p1[e] = __shfl_xor(v1[e], 16); }
;                         v0 = v0 * c0 + p0 * s0; v1 = v1 * c1 + p1 * s1;
;                     }
;                     v0 = v0 * scr; v1 = v1 * scr;
;                     if (nrmw) { float q = (v0[0] * v0[0] + v0[1] * v0[1]) + (v0[2] * v0[2] + v0[3] * v0[3]) + (v1[0] * v1[0] + v1[1] * v1[1]) + (v1[2] * v1[2] + v1[3] * v1[3]);
;                         q += __shfl_xor(q, 16); q += __shfl_xor(q, 32); mxn[bj] = fmaxf(mxn[bj], q); }
;                     u32x4 w; w.x = cvt_pk_bf16(v0[0], v0[1]); w.y = cvt_pk_bf16(v0[2], v0[3]); w.z = cvt_pk_bf16(v1[0], v1[1]); w.w = cvt_pk_bf16(v1[2], v1[3]);
;                     *(u32x4*)(rowp + bj * HALF) = w;
.LBB0_336:
	v_mov_b64_e32 v[148:149], s[28:29]
	v_mad_i64_i32 v[148:149], s[0:1], v160, s86, v[148:149]
	v_lshl_add_u64 v[148:149], v[184:185], 1, v[148:149]
	s_and_b64 vcc, exec, s[12:13]
	v_cvt_pk_bf16_f32 v156, v156, v157
	v_cvt_pk_bf16_f32 v157, v158, v159
	v_cvt_pk_bf16_f32 v158, v180, v181
	v_cvt_pk_bf16_f32 v159, v150, v151
	ds_bpermute_b32 v222, v253, v156
	ds_bpermute_b32 v223, v253, v157
	ds_bpermute_b32 v224, v253, v158
	ds_bpermute_b32 v225, v253, v159
	v_lshl_add_u64 v[226:227], v[148:149], 0, v[228:229]
	s_waitcnt lgkmcnt(4)
	global_store_dwordx4 v[218:219], v[214:217], off offset:256 sc1
	s_cbranch_vccnz .LBB0_338
	ds_bpermute_b32 v150, v235, v140
	ds_bpermute_b32 v151, v235, v141
	ds_bpermute_b32 v156, v235, v136
	ds_bpermute_b32 v158, v235, v142
	ds_bpermute_b32 v159, v235, v143
	ds_bpermute_b32 v157, v235, v137
	ds_bpermute_b32 v160, v235, v138
	ds_bpermute_b32 v161, v235, v139
	s_waitcnt lgkmcnt(0)
	v_pk_mul_f32 v[150:151], v[170:171], v[150:151]
	v_pk_mul_f32 v[158:159], v[172:173], v[158:159]
	v_pk_fma_f32 v[140:141], v[140:141], v[176:177], v[150:151]
	v_pk_mul_f32 v[150:151], v[166:167], v[156:157]
	v_pk_mul_f32 v[156:157], v[164:165], v[160:161]
	v_pk_fma_f32 v[142:143], v[142:143], v[174:175], v[158:159]
	v_pk_fma_f32 v[138:139], v[138:139], v[162:163], v[156:157]
	v_pk_fma_f32 v[136:137], v[136:137], v[168:169], v[150:151]

; __device__ __forceinline__ unsigned cvt_pk_bf16(float lo, float hi) { unsigned r; asm volatile("v_cvt_pk_bf16_f32 %0, %1, %2" : "=v"(r) : "v"(lo), "v"(hi)); return r; }
; __device__ __forceinline__ float row_rstd(const float* part, int row, float eps) {
;     const f32x4* p = (const f32x4*)(part + (size_t)row * 16);
;     const f32x4 a = p[0], b = p[1], c = p[2], d = p[3];
;     const float s = ((a[0] + a[1]) + (a[2] + a[3])) + ((b[0] + b[1]) + (b[2] + b[3])) + ((c[0] + c[1]) + (c[2] + c[3])) + ((d[0] + d[1]) + (d[2] + d[3]));
;     return 1.0f / sqrtf(s * (1.0f / 1024.0f) + eps);
; }
;     __device__ __forceinline__ void operator()(const f32x4 (&acc)[2][2][4][2], const Unit& u, int wr, int wc, int fr, int fq) const {
;     ...
;                 const int row = row0 + ai * HALF + m * 16;
;                 bf16_t* rowp = O + (size_t)row * 3072 + col0;
;                 const float scr = sc * (slot >= 0 ? tab[slot * 256 + (row - u.pm * BM)] : row_rstd(ssp, row, 1e-6f));
;                 f32x4 c0 = {1.f, 1.f, 1.f, 1.f}, c1 = c0, s0 = {0.f, 0.f, 0.f, 0.f}, s1 = s0;
;                 if (ropew) { c0 = rc[m][0]; c1 = rc[m][1]; s0 = rc[m][2]; s1 = rc[m][3]; if (fq == 0) { s0 = -s0; s1 = -s1; } if (fq >= 2) { c0 = (f32x4){1.f, 1.f, 1.f, 1.f}; c1 = c0; s0 = (f32x4){0.f, 0.f, 0.f, 0.f}; s1 = s0; } }
; #pragma unroll
;                 for (int bj = 0; bj < 2; ++bj) {
;                     f32x4 v0 = acc[ai][bj][m][0], v1 = acc[ai][bj][m][1];
;                     if (ropew) {
;                         f32x4 p0, p1;
; #pragma unroll
;                         for (int e = 0; e < 4; ++e) { p0[e] = __shfl_xor(v0[e], 16); p1[e] = __shfl_xor(v1[e], 16); }
;                         v0 = v0 * c0 + p0 * s0; v1 = v1 * c1 + p1 * s1;
;                     }
;                     v0 = v0 * scr; v1 = v1 * scr;
;                     if (nrmw) { float q = (v0[0] * v0[0] + v0[1] * v0[1]) + (v0[2] * v0[2] + v0[3] * v0[3]) + (v1[0] * v1[0] + v1[1] * v1[1]) + (v1[2] * v1[2] + v1[3] * v1[3]);
;                         q += __shfl_xor(q, 16); q += __shfl_xor(q, 32); mxn[bj] = fmaxf(mxn[bj], q); }
;                     u32x4 w; w.x = cvt_pk_bf16(v0[0], v0[1]); w.y = cvt_pk_bf16(v0[2], v0[3]); w.z = cvt_pk_bf16(v1[0], v1[1]); w.w = cvt_pk_bf16(v1[2], v1[3]);
;                     *(u32x4*)(rowp + bj * HALF) = w;
.LBB0_342:
	v_cvt_pk_bf16_f32 v140, v140, v141
	v_cvt_pk_bf16_f32 v141, v142, v143
	v_cvt_pk_bf16_f32 v142, v136, v137
	v_or_b32_e32 v136, 48, v208
	v_ashrrev_i32_e32 v137, 31, v136
	s_and_b64 vcc, exec, s[16:17]
	s_mov_b64 s[0:1], -1
	v_cvt_pk_bf16_f32 v143, v138, v139
	ds_bpermute_b32 v214, v253, v140
	ds_bpermute_b32 v215, v253, v141
	ds_bpermute_b32 v216, v253, v142
	ds_bpermute_b32 v217, v253, v143
	v_lshl_add_u64 v[218:219], v[148:149], 0, v[228:229]
	s_waitcnt lgkmcnt(4)
	global_store_dwordx4 v[226:227], v[222:225], off sc1
	s_cbranch_vccnz .LBB0_348
	v_lshlrev_b64 v[138:139], 6, v[136:137]
	v_lshl_add_u64 v[142:143], s[22:23], 0, v[138:139]
	global_load_dwordx4 v[138:141], v[142:143], off offset:48
	global_load_dwordx4 v[148:151], v[142:143], off offset:32
	global_load_dwordx4 v[156:159], v[142:143], off offset:16
	global_load_dwordx4 v[160:163], v[142:143], off
	s_waitcnt vmcnt(0)
	v_add_f32_e32 v148, v148, v149
	v_add_f32_e32 v150, v150, v151
	v_mov_b32_e32 v142, v161
	v_mov_b32_e32 v143, v162
	v_mov_b32_e32 v161, v163
	v_pk_add_f32 v[142:143], v[142:143], v[160:161]
	v_mov_b32_e32 v160, v157
	v_mov_b32_e32 v161, v158
	v_mov_b32_e32 v157, v159
	v_pk_add_f32 v[156:157], v[160:161], v[156:157]
	v_pk_add_f32 v[142:143], v[142:143], v[142:143] op_sel:[0,1] op_sel_hi:[1,0]
	v_pk_add_f32 v[156:157], v[156:157], v[156:157] op_sel:[0,1] op_sel_hi:[1,0]
	v_mov_b32_e32 v143, v138
	v_mov_b32_e32 v157, v139
	v_mov_b32_e32 v149, v140
	v_mov_b32_e32 v151, v141
	v_pk_add_f32 v[138:139], v[142:143], v[156:157]
	v_pk_add_f32 v[140:141], v[148:149], v[150:151]
	s_nop 0
	v_pk_add_f32 v[138:139], v[138:139], v[140:141]
	s_nop 0
	v_add_f32_e32 v137, v138, v139
	v_fmamk_f32 v137, v137, 0x3a800000, v246
	v_cmp_gt_f32_e32 vcc, s83, v137
	v_mul_f32_e32 v138, 0x4f800000, v137
	s_nop 0
	v_cndmask_b32_e32 v137, v137, v138, vcc
	v_sqrt_f32_e32 v138, v137
	s_nop 0
	v_add_u32_e32 v139, -1, v138
	v_fma_f32 v140, -v139, v138, v137
	v_cmp_ge_f32_e64 s[0:1], 0, v140
	v_add_u32_e32 v140, 1, v138
	s_nop 0
	v_cndmask_b32_e64 v139, v138, v139, s[0:1]
	v_fma_f32 v138, -v140, v138, v137
	v_cmp_lt_f32_e64 s[0:1], 0, v138
	s_nop 1
	v_cndmask_b32_e64 v138, v139, v140, s[0:1]
	v_mul_f32_e32 v139, 0x37800000, v138
	v_cndmask_b32_e32 v138, v138, v139, vcc
	v_cmp_class_f32_e32 vcc, v137, v247
	s_nop 1
	v_cndmask_b32_e32 v137, v138, v137, vcc
	v_div_scale_f32 v138, s[0:1], v137, v137, 1.0
	v_rcp_f32_e32 v139, v138
	s_nop 0
	v_fma_f32 v140, -v138, v139, 1.0
	v_fmac_f32_e32 v139, v140, v139
	v_div_scale_f32 v140, vcc, 1.0, v137, 1.0
	v_mul_f32_e32 v141, v140, v139
	v_fma_f32 v142, -v138, v141, v140
	v_fmac_f32_e32 v141, v142, v139
	v_fma_f32 v138, -v138, v141, v140
	v_div_fmas_f32 v138, v138, v139, v141
	v_div_fixup_f32 v162, v138, v137, 1.0
	s_cbranch_execz .LBB0_349

; __device__ __forceinline__ unsigned cvt_pk_bf16(float lo, float hi) { unsigned r; asm volatile("v_cvt_pk_bf16_f32 %0, %1, %2" : "=v"(r) : "v"(lo), "v"(hi)); return r; }
;     __device__ __forceinline__ void operator()(const f32x4 (&acc)[2][2][4][2], const Unit& u, int wr, int wc, int fr, int fq) const {
;     ...
;                 bf16_t* rowp = O + (size_t)row * 3072 + col0;
;                 const float scr = sc * (slot >= 0 ? tab[slot * 256 + (row - u.pm * BM)] : row_rstd(ssp, row, 1e-6f));
;                 f32x4 c0 = {1.f, 1.f, 1.f, 1.f}, c1 = c0, s0 = {0.f, 0.f, 0.f, 0.f}, s1 = s0;
;                 if (ropew) { c0 = rc[m][0]; c1 = rc[m][1]; s0 = rc[m][2]; s1 = rc[m][3]; if (fq == 0) { s0 = -s0; s1 = -s1; } if (fq >= 2) { c0 = (f32x4){1.f, 1.f, 1.f, 1.f}; c1 = c0; s0 = (f32x4){0.f, 0.f, 0.f, 0.f}; s1 = s0; } }
; #pragma unroll
;                 for (int bj = 0; bj < 2; ++bj) {
;                     f32x4 v0 = acc[ai][bj][m][0], v1 = acc[ai][bj][m][1];
;                     if (ropew) {
;                         f32x4 p0, p1;
; #pragma unroll
;                         for (int e = 0; e < 4; ++e) { p0[e] = __shfl_xor(v0[e], 16); p1[e] = __shfl_xor(v1[e], 16); }
;                         v0 = v0 * c0 + p0 * s0; v1 = v1 * c1 + p1 * s1;
;                     }
;                     v0 = v0 * scr; v1 = v1 * scr;
;                     if (nrmw) { float q = (v0[0] * v0[0] + v0[1] * v0[1]) + (v0[2] * v0[2] + v0[3] * v0[3]) + (v1[0] * v1[0] + v1[1] * v1[1]) + (v1[2] * v1[2] + v1[3] * v1[3]);
;                         q += __shfl_xor(q, 16); q += __shfl_xor(q, 32); mxn[bj] = fmaxf(mxn[bj], q); }
;                     u32x4 w; w.x = cvt_pk_bf16(v0[0], v0[1]); w.y = cvt_pk_bf16(v0[2], v0[3]); w.z = cvt_pk_bf16(v1[0], v1[1]); w.w = cvt_pk_bf16(v1[2], v1[3]);
;                     *(u32x4*)(rowp + bj * HALF) = w;
.LBB0_356:
	v_mov_b64_e32 v[112:113], s[28:29]
	v_mad_i64_i32 v[112:113], s[0:1], v136, s86, v[112:113]
	v_lshl_add_u64 v[112:113], v[184:185], 1, v[112:113]
	s_and_b64 vcc, exec, s[12:13]
	v_cvt_pk_bf16_f32 v116, v116, v117
	v_cvt_pk_bf16_f32 v117, v118, v119
	v_cvt_pk_bf16_f32 v118, v164, v165
	v_cvt_pk_bf16_f32 v119, v114, v115
	ds_bpermute_b32 v222, v253, v116
	ds_bpermute_b32 v223, v253, v117
	ds_bpermute_b32 v224, v253, v118
	ds_bpermute_b32 v225, v253, v119
	v_lshl_add_u64 v[226:227], v[112:113], 0, v[228:229]
	s_waitcnt lgkmcnt(4)
	global_store_dwordx4 v[218:219], v[214:217], off offset:256 sc1
	s_cbranch_vccnz .LBB0_358
	ds_bpermute_b32 v114, v235, v108
	ds_bpermute_b32 v115, v235, v109
	ds_bpermute_b32 v116, v235, v104
	ds_bpermute_b32 v118, v235, v110
	ds_bpermute_b32 v119, v235, v111
	ds_bpermute_b32 v117, v235, v105
	ds_bpermute_b32 v136, v235, v106
	ds_bpermute_b32 v137, v235, v107
	s_waitcnt lgkmcnt(0)
	v_pk_mul_f32 v[114:115], v[150:151], v[114:115]
	v_pk_mul_f32 v[118:119], v[156:157], v[118:119]
	v_pk_fma_f32 v[108:109], v[108:109], v[160:161], v[114:115]
	v_pk_mul_f32 v[114:115], v[142:143], v[116:117]
	v_pk_mul_f32 v[116:117], v[140:141], v[136:137]
	v_pk_fma_f32 v[110:111], v[110:111], v[158:159], v[118:119]
	v_pk_fma_f32 v[106:107], v[106:107], v[138:139], v[116:117]
	v_pk_fma_f32 v[104:105], v[104:105], v[148:149], v[114:115]

;     __device__ __forceinline__ void operator()(const f32x4 (&acc)[2][2][4][2], const Unit& u, int wr, int wc, int fr, int fq) const {
;     ...
;         for (int ai = 0; ai < 2; ++ai) {
;             f32x4 rc[4][4];
;             if (ropew) {
; #pragma unroll
;                 for (int m = 0; m < 4; ++m) { const f32x4* rp = (const f32x4*)(rope + (size_t)((row0 + ai * HALF + m * 16) & 4095) * 16); rc[m][0] = rp[0]; rc[m][1] = rp[1]; rc[m][2] = rp[2]; rc[m][3] = rp[3]; }
;             }
; #pragma unroll
;             for (int m = 0; m < 4; ++m) {
;                 const int row = row0 + ai * HALF + m * 16;
;                 bf16_t* rowp = O + (size_t)row * 3072 + col0;
;                 const float scr = sc * (slot >= 0 ? tab[slot * 256 + (row - u.pm * BM)] : row_rstd(ssp, row, 1e-6f));
;                 f32x4 c0 = {1.f, 1.f, 1.f, 1.f}, c1 = c0, s0 = {0.f, 0.f, 0.f, 0.f}, s1 = s0;
;                 if (ropew) { c0 = rc[m][0]; c1 = rc[m][1]; s0 = rc[m][2]; s1 = rc[m][3]; if (fq == 0) { s0 = -s0; s1 = -s1; } if (fq >= 2) { c0 = (f32x4){1.f, 1.f, 1.f, 1.f}; c1 = c0; s0 = (f32x4){0.f, 0.f, 0.f, 0.f}; s1 = s0; } }
;     ...
;                     *(u32x4*)(rowp + bj * HALF) = w;
.LBB0_362:
	s_and_b64 vcc, exec, s[12:13]
	v_cvt_pk_bf16_f32 v108, v108, v109
	v_cvt_pk_bf16_f32 v109, v110, v111
	v_cvt_pk_bf16_f32 v110, v104, v105
	v_cvt_pk_bf16_f32 v111, v106, v107
	ds_bpermute_b32 v214, v253, v108
	ds_bpermute_b32 v215, v253, v109
	ds_bpermute_b32 v216, v253, v110
	ds_bpermute_b32 v217, v253, v111
	v_lshl_add_u64 v[218:219], v[112:113], 0, v[228:229]
	s_waitcnt lgkmcnt(4)
	global_store_dwordx4 v[226:227], v[222:225], off sc1
	s_cbranch_vccnz .LBB0_364
	v_add_u32_e32 v48, 0x800, v251
	v_and_b32_e32 v48, 0xfcf0, v48
	v_lshlrev_b32_e32 v60, 2, v48
	global_load_dwordx4 v[128:131], v60, s[72:73] offset:16
	global_load_dwordx4 v[132:135], v60, s[72:73]
	global_load_dwordx4 v[144:147], v60, s[72:73] offset:48
	global_load_dwordx4 v[152:155], v60, s[72:73] offset:32
	global_load_dwordx4 v[96:99], v60, s[72:73] offset:1040
	global_load_dwordx4 v[100:103], v60, s[72:73] offset:1024
	global_load_dwordx4 v[120:123], v60, s[72:73] offset:1072
	global_load_dwordx4 v[124:127], v60, s[72:73] offset:1056
	global_load_dwordx4 v[76:79], v60, s[72:73] offset:2064
	global_load_dwordx4 v[84:87], v60, s[72:73] offset:2048
	global_load_dwordx4 v[88:91], v60, s[72:73] offset:2096
	global_load_dwordx4 v[92:95], v60, s[72:73] offset:2080
	global_load_dwordx4 v[48:51], v60, s[72:73] offset:3088
	global_load_dwordx4 v[52:55], v60, s[72:73] offset:3072
	global_load_dwordx4 v[56:59], v60, s[72:73] offset:3120
	s_nop 0
	global_load_dwordx4 v[60:63], v60, s[72:73] offset:3104

; __device__ __forceinline__ unsigned cvt_pk_bf16(float lo, float hi) { unsigned r; asm volatile("v_cvt_pk_bf16_f32 %0, %1, %2" : "=v"(r) : "v"(lo), "v"(hi)); return r; }
;     __device__ __forceinline__ void operator()(const f32x4 (&acc)[2][2][4][2], const Unit& u, int wr, int wc, int fr, int fq) const {
;     ...
;                 bf16_t* rowp = O + (size_t)row * 3072 + col0;
;                 const float scr = sc * (slot >= 0 ? tab[slot * 256 + (row - u.pm * BM)] : row_rstd(ssp, row, 1e-6f));
;                 f32x4 c0 = {1.f, 1.f, 1.f, 1.f}, c1 = c0, s0 = {0.f, 0.f, 0.f, 0.f}, s1 = s0;
;                 if (ropew) { c0 = rc[m][0]; c1 = rc[m][1]; s0 = rc[m][2]; s1 = rc[m][3]; if (fq == 0) { s0 = -s0; s1 = -s1; } if (fq >= 2) { c0 = (f32x4){1.f, 1.f, 1.f, 1.f}; c1 = c0; s0 = (f32x4){0.f, 0.f, 0.f, 0.f}; s1 = s0; } }
; #pragma unroll
;                 for (int bj = 0; bj < 2; ++bj) {
;                     f32x4 v0 = acc[ai][bj][m][0], v1 = acc[ai][bj][m][1];
;                     if (ropew) {
;                         f32x4 p0, p1;
; #pragma unroll
;                         for (int e = 0; e < 4; ++e) { p0[e] = __shfl_xor(v0[e], 16); p1[e] = __shfl_xor(v1[e], 16); }
;                         v0 = v0 * c0 + p0 * s0; v1 = v1 * c1 + p1 * s1;
;                     }
;                     v0 = v0 * scr; v1 = v1 * scr;
;                     if (nrmw) { float q = (v0[0] * v0[0] + v0[1] * v0[1]) + (v0[2] * v0[2] + v0[3] * v0[3]) + (v1[0] * v1[0] + v1[1] * v1[1]) + (v1[2] * v1[2] + v1[3] * v1[3]);
;                         q += __shfl_xor(q, 16); q += __shfl_xor(q, 32); mxn[bj] = fmaxf(mxn[bj], q); }
;                     u32x4 w; w.x = cvt_pk_bf16(v0[0], v0[1]); w.y = cvt_pk_bf16(v0[2], v0[3]); w.z = cvt_pk_bf16(v1[0], v1[1]); w.w = cvt_pk_bf16(v1[2], v1[3]);
;                     *(u32x4*)(rowp + bj * HALF) = w;
.LBB0_378:
	v_mov_b64_e32 v[72:73], s[28:29]
	v_mad_i64_i32 v[72:73], s[0:1], v104, s86, v[72:73]
	v_lshl_add_u64 v[72:73], v[184:185], 1, v[72:73]
	s_and_b64 vcc, exec, s[12:13]
	v_cvt_pk_bf16_f32 v80, v80, v81
	v_cvt_pk_bf16_f32 v81, v82, v83
	v_cvt_pk_bf16_f32 v82, v116, v117
	v_cvt_pk_bf16_f32 v83, v74, v75
	ds_bpermute_b32 v222, v253, v80
	ds_bpermute_b32 v223, v253, v81
	ds_bpermute_b32 v224, v253, v82
	ds_bpermute_b32 v225, v253, v83
	v_lshl_add_u64 v[226:227], v[72:73], 0, v[228:229]
	s_waitcnt lgkmcnt(4)
	global_store_dwordx4 v[218:219], v[214:217], off offset:256 sc1
	s_cbranch_vccnz .LBB0_380
	ds_bpermute_b32 v74, v235, v68
	ds_bpermute_b32 v75, v235, v69
	ds_bpermute_b32 v80, v235, v64
	ds_bpermute_b32 v82, v235, v70
	ds_bpermute_b32 v83, v235, v71
	ds_bpermute_b32 v81, v235, v65
	ds_bpermute_b32 v104, v235, v66
	ds_bpermute_b32 v105, v235, v67
	s_waitcnt lgkmcnt(6)
	v_pk_mul_f32 v[74:75], v[110:111], v[74:75]
	s_waitcnt lgkmcnt(3)
	v_pk_mul_f32 v[82:83], v[112:113], v[82:83]
	v_pk_fma_f32 v[68:69], v[68:69], v[132:133], v[74:75]
	s_waitcnt lgkmcnt(2)
	v_pk_mul_f32 v[74:75], v[108:109], v[80:81]
	s_waitcnt lgkmcnt(0)
	v_pk_mul_f32 v[80:81], v[106:107], v[104:105]
	v_pk_fma_f32 v[70:71], v[70:71], v[134:135], v[82:83]
	v_pk_fma_f32 v[66:67], v[66:67], v[130:131], v[80:81]
	v_pk_fma_f32 v[64:65], v[64:65], v[128:129], v[74:75]

; __device__ __forceinline__ unsigned cvt_pk_bf16(float lo, float hi) { unsigned r; asm volatile("v_cvt_pk_bf16_f32 %0, %1, %2" : "=v"(r) : "v"(lo), "v"(hi)); return r; }
; __device__ __forceinline__ float row_rstd(const float* part, int row, float eps) {
;     const f32x4* p = (const f32x4*)(part + (size_t)row * 16);
;     const f32x4 a = p[0], b = p[1], c = p[2], d = p[3];
;     const float s = ((a[0] + a[1]) + (a[2] + a[3])) + ((b[0] + b[1]) + (b[2] + b[3])) + ((c[0] + c[1]) + (c[2] + c[3])) + ((d[0] + d[1]) + (d[2] + d[3]));
;     return 1.0f / sqrtf(s * (1.0f / 1024.0f) + eps);
; }
;     __device__ __forceinline__ void operator()(const f32x4 (&acc)[2][2][4][2], const Unit& u, int wr, int wc, int fr, int fq) const {
;     ...
;                 const int row = row0 + ai * HALF + m * 16;
;                 bf16_t* rowp = O + (size_t)row * 3072 + col0;
;                 const float scr = sc * (slot >= 0 ? tab[slot * 256 + (row - u.pm * BM)] : row_rstd(ssp, row, 1e-6f));
;                 f32x4 c0 = {1.f, 1.f, 1.f, 1.f}, c1 = c0, s0 = {0.f, 0.f, 0.f, 0.f}, s1 = s0;
;                 if (ropew) { c0 = rc[m][0]; c1 = rc[m][1]; s0 = rc[m][2]; s1 = rc[m][3]; if (fq == 0) { s0 = -s0; s1 = -s1; } if (fq >= 2) { c0 = (f32x4){1.f, 1.f, 1.f, 1.f}; c1 = c0; s0 = (f32x4){0.f, 0.f, 0.f, 0.f}; s1 = s0; } }
; #pragma unroll
;                 for (int bj = 0; bj < 2; ++bj) {
;                     f32x4 v0 = acc[ai][bj][m][0], v1 = acc[ai][bj][m][1];
;                     if (ropew) {
;                         f32x4 p0, p1;
; #pragma unroll
;                         for (int e = 0; e < 4; ++e) { p0[e] = __shfl_xor(v0[e], 16); p1[e] = __shfl_xor(v1[e], 16); }
;                         v0 = v0 * c0 + p0 * s0; v1 = v1 * c1 + p1 * s1;
;                     }
;                     v0 = v0 * scr; v1 = v1 * scr;
;                     if (nrmw) { float q = (v0[0] * v0[0] + v0[1] * v0[1]) + (v0[2] * v0[2] + v0[3] * v0[3]) + (v1[0] * v1[0] + v1[1] * v1[1]) + (v1[2] * v1[2] + v1[3] * v1[3]);
;                         q += __shfl_xor(q, 16); q += __shfl_xor(q, 32); mxn[bj] = fmaxf(mxn[bj], q); }
;                     u32x4 w; w.x = cvt_pk_bf16(v0[0], v0[1]); w.y = cvt_pk_bf16(v0[2], v0[3]); w.z = cvt_pk_bf16(v1[0], v1[1]); w.w = cvt_pk_bf16(v1[2], v1[3]);
;                     *(u32x4*)(rowp + bj * HALF) = w;
.LBB0_384:
	v_cvt_pk_bf16_f32 v68, v68, v69
	v_cvt_pk_bf16_f32 v69, v70, v71
	v_cvt_pk_bf16_f32 v70, v64, v65
	v_add_u32_e32 v64, 0x90, v208
	v_ashrrev_i32_e32 v65, 31, v64
	s_and_b64 vcc, exec, s[16:17]
	s_mov_b64 s[0:1], -1
	v_cvt_pk_bf16_f32 v71, v66, v67
	ds_bpermute_b32 v214, v253, v68
	ds_bpermute_b32 v215, v253, v69
	ds_bpermute_b32 v216, v253, v70
	ds_bpermute_b32 v217, v253, v71
	v_lshl_add_u64 v[218:219], v[72:73], 0, v[228:229]
	s_waitcnt lgkmcnt(4)
	global_store_dwordx4 v[226:227], v[222:225], off sc1
	s_cbranch_vccnz .LBB0_390
	v_lshlrev_b64 v[66:67], 6, v[64:65]
	v_lshl_add_u64 v[74:75], s[22:23], 0, v[66:67]
	global_load_dwordx4 v[66:69], v[74:75], off offset:48
	global_load_dwordx4 v[70:73], v[74:75], off offset:32
	global_load_dwordx4 v[80:83], v[74:75], off offset:16
	global_load_dwordx4 v[104:107], v[74:75], off
	s_waitcnt vmcnt(2)
	v_add_f32_e32 v70, v70, v71
	v_add_f32_e32 v72, v72, v73
	s_waitcnt vmcnt(0)
	v_mov_b32_e32 v74, v105
	v_mov_b32_e32 v75, v106
	v_mov_b32_e32 v105, v107
	v_pk_add_f32 v[74:75], v[74:75], v[104:105]
	v_mov_b32_e32 v104, v81
	v_mov_b32_e32 v105, v82
	v_mov_b32_e32 v81, v83
	v_pk_add_f32 v[80:81], v[104:105], v[80:81]
	v_pk_add_f32 v[74:75], v[74:75], v[74:75] op_sel:[0,1] op_sel_hi:[1,0]
	v_pk_add_f32 v[80:81], v[80:81], v[80:81] op_sel:[0,1] op_sel_hi:[1,0]
	v_mov_b32_e32 v75, v66
	v_mov_b32_e32 v81, v67
	v_mov_b32_e32 v71, v68
	v_mov_b32_e32 v73, v69
	v_pk_add_f32 v[66:67], v[74:75], v[80:81]
	v_pk_add_f32 v[68:69], v[70:71], v[72:73]
	s_nop 0
	v_pk_add_f32 v[66:67], v[66:67], v[68:69]
	s_nop 0
	v_add_f32_e32 v65, v66, v67
	v_fmamk_f32 v65, v65, 0x3a800000, v246
	v_cmp_gt_f32_e32 vcc, s83, v65
	v_mul_f32_e32 v66, 0x4f800000, v65
	s_nop 0
	v_cndmask_b32_e32 v65, v65, v66, vcc
	v_sqrt_f32_e32 v66, v65
	s_nop 0
	v_add_u32_e32 v67, -1, v66
	v_fma_f32 v68, -v67, v66, v65
	v_cmp_ge_f32_e64 s[0:1], 0, v68
	v_add_u32_e32 v68, 1, v66
	s_nop 0
	v_cndmask_b32_e64 v67, v66, v67, s[0:1]
	v_fma_f32 v66, -v68, v66, v65
	v_cmp_lt_f32_e64 s[0:1], 0, v66
	s_nop 1
	v_cndmask_b32_e64 v66, v67, v68, s[0:1]
	v_mul_f32_e32 v67, 0x37800000, v66
	v_cndmask_b32_e32 v66, v66, v67, vcc
	v_cmp_class_f32_e32 vcc, v65, v247
	s_nop 1
	v_cndmask_b32_e32 v65, v66, v65, vcc
	v_div_scale_f32 v66, s[0:1], v65, v65, 1.0
	v_rcp_f32_e32 v67, v66
	s_nop 0
	v_fma_f32 v68, -v66, v67, 1.0
	v_fmac_f32_e32 v67, v68, v67
	v_div_scale_f32 v68, vcc, 1.0, v65, 1.0
	v_mul_f32_e32 v69, v68, v67
	v_fma_f32 v70, -v66, v69, v68
	v_fmac_f32_e32 v69, v70, v67
	v_fma_f32 v66, -v66, v69, v68
	v_div_fmas_f32 v66, v66, v67, v69
	v_div_fixup_f32 v74, v66, v65, 1.0
	s_cbranch_execz .LBB0_391

; __device__ __forceinline__ unsigned cvt_pk_bf16(float lo, float hi) { unsigned r; asm volatile("v_cvt_pk_bf16_f32 %0, %1, %2" : "=v"(r) : "v"(lo), "v"(hi)); return r; }
;     __device__ __forceinline__ void operator()(const f32x4 (&acc)[2][2][4][2], const Unit& u, int wr, int wc, int fr, int fq) const {
;     ...
;                 bf16_t* rowp = O + (size_t)row * 3072 + col0;
;                 const float scr = sc * (slot >= 0 ? tab[slot * 256 + (row - u.pm * BM)] : row_rstd(ssp, row, 1e-6f));
;                 f32x4 c0 = {1.f, 1.f, 1.f, 1.f}, c1 = c0, s0 = {0.f, 0.f, 0.f, 0.f}, s1 = s0;
;                 if (ropew) { c0 = rc[m][0]; c1 = rc[m][1]; s0 = rc[m][2]; s1 = rc[m][3]; if (fq == 0) { s0 = -s0; s1 = -s1; } if (fq >= 2) { c0 = (f32x4){1.f, 1.f, 1.f, 1.f}; c1 = c0; s0 = (f32x4){0.f, 0.f, 0.f, 0.f}; s1 = s0; } }
; #pragma unroll
;                 for (int bj = 0; bj < 2; ++bj) {
;                     f32x4 v0 = acc[ai][bj][m][0], v1 = acc[ai][bj][m][1];
;                     if (ropew) {
;                         f32x4 p0, p1;
; #pragma unroll
;                         for (int e = 0; e < 4; ++e) { p0[e] = __shfl_xor(v0[e], 16); p1[e] = __shfl_xor(v1[e], 16); }
;                         v0 = v0 * c0 + p0 * s0; v1 = v1 * c1 + p1 * s1;
;                     }
;                     v0 = v0 * scr; v1 = v1 * scr;
;                     if (nrmw) { float q = (v0[0] * v0[0] + v0[1] * v0[1]) + (v0[2] * v0[2] + v0[3] * v0[3]) + (v1[0] * v1[0] + v1[1] * v1[1]) + (v1[2] * v1[2] + v1[3] * v1[3]);
;                         q += __shfl_xor(q, 16); q += __shfl_xor(q, 32); mxn[bj] = fmaxf(mxn[bj], q); }
;                     u32x4 w; w.x = cvt_pk_bf16(v0[0], v0[1]); w.y = cvt_pk_bf16(v0[2], v0[3]); w.z = cvt_pk_bf16(v1[0], v1[1]); w.w = cvt_pk_bf16(v1[2], v1[3]);
;                     *(u32x4*)(rowp + bj * HALF) = w;
.LBB0_398:
	v_mov_b64_e32 v[40:41], s[28:29]
	v_mad_i64_i32 v[40:41], s[0:1], v64, s86, v[40:41]
	v_lshl_add_u64 v[40:41], v[184:185], 1, v[40:41]
	s_and_b64 vcc, exec, s[12:13]
	v_cvt_pk_bf16_f32 v44, v44, v45
	v_cvt_pk_bf16_f32 v45, v46, v47
	v_cvt_pk_bf16_f32 v46, v80, v81
	v_cvt_pk_bf16_f32 v47, v42, v43
	ds_bpermute_b32 v222, v253, v44
	ds_bpermute_b32 v223, v253, v45
	ds_bpermute_b32 v224, v253, v46
	ds_bpermute_b32 v225, v253, v47
	v_lshl_add_u64 v[226:227], v[40:41], 0, v[228:229]
	s_waitcnt lgkmcnt(4)
	global_store_dwordx4 v[218:219], v[214:217], off offset:256 sc1
	s_cbranch_vccnz .LBB0_400
	ds_bpermute_b32 v42, v235, v36
	ds_bpermute_b32 v43, v235, v37
	ds_bpermute_b32 v44, v235, v32
	ds_bpermute_b32 v46, v235, v38
	ds_bpermute_b32 v47, v235, v39
	ds_bpermute_b32 v45, v235, v33
	ds_bpermute_b32 v64, v235, v34
	ds_bpermute_b32 v65, v235, v35
	s_waitcnt lgkmcnt(6)
	v_pk_mul_f32 v[42:43], v[70:71], v[42:43]
	s_waitcnt lgkmcnt(3)
	v_pk_mul_f32 v[46:47], v[72:73], v[46:47]
	v_pk_fma_f32 v[36:37], v[36:37], v[100:101], v[42:43]
	s_waitcnt lgkmcnt(2)
	v_pk_mul_f32 v[42:43], v[68:69], v[44:45]
	s_waitcnt lgkmcnt(0)
	v_pk_mul_f32 v[44:45], v[66:67], v[64:65]
	v_pk_fma_f32 v[38:39], v[38:39], v[102:103], v[46:47]
	v_pk_fma_f32 v[34:35], v[34:35], v[98:99], v[44:45]
	v_pk_fma_f32 v[32:33], v[32:33], v[96:97], v[42:43]

; __device__ __forceinline__ unsigned cvt_pk_bf16(float lo, float hi) { unsigned r; asm volatile("v_cvt_pk_bf16_f32 %0, %1, %2" : "=v"(r) : "v"(lo), "v"(hi)); return r; }
; __device__ __forceinline__ float row_rstd(const float* part, int row, float eps) {
;     const f32x4* p = (const f32x4*)(part + (size_t)row * 16);
;     const f32x4 a = p[0], b = p[1], c = p[2], d = p[3];
;     const float s = ((a[0] + a[1]) + (a[2] + a[3])) + ((b[0] + b[1]) + (b[2] + b[3])) + ((c[0] + c[1]) + (c[2] + c[3])) + ((d[0] + d[1]) + (d[2] + d[3]));
;     return 1.0f / sqrtf(s * (1.0f / 1024.0f) + eps);
; }
;     __device__ __forceinline__ void operator()(const f32x4 (&acc)[2][2][4][2], const Unit& u, int wr, int wc, int fr, int fq) const {
;     ...
;                 const int row = row0 + ai * HALF + m * 16;
;                 bf16_t* rowp = O + (size_t)row * 3072 + col0;
;                 const float scr = sc * (slot >= 0 ? tab[slot * 256 + (row - u.pm * BM)] : row_rstd(ssp, row, 1e-6f));
;                 f32x4 c0 = {1.f, 1.f, 1.f, 1.f}, c1 = c0, s0 = {0.f, 0.f, 0.f, 0.f}, s1 = s0;
;                 if (ropew) { c0 = rc[m][0]; c1 = rc[m][1]; s0 = rc[m][2]; s1 = rc[m][3]; if (fq == 0) { s0 = -s0; s1 = -s1; } if (fq >= 2) { c0 = (f32x4){1.f, 1.f, 1.f, 1.f}; c1 = c0; s0 = (f32x4){0.f, 0.f, 0.f, 0.f}; s1 = s0; } }
; #pragma unroll
;                 for (int bj = 0; bj < 2; ++bj) {
;                     f32x4 v0 = acc[ai][bj][m][0], v1 = acc[ai][bj][m][1];
;                     if (ropew) {
;                         f32x4 p0, p1;
; #pragma unroll
;                         for (int e = 0; e < 4; ++e) { p0[e] = __shfl_xor(v0[e], 16); p1[e] = __shfl_xor(v1[e], 16); }
;                         v0 = v0 * c0 + p0 * s0; v1 = v1 * c1 + p1 * s1;
;                     }
;                     v0 = v0 * scr; v1 = v1 * scr;
;                     if (nrmw) { float q = (v0[0] * v0[0] + v0[1] * v0[1]) + (v0[2] * v0[2] + v0[3] * v0[3]) + (v1[0] * v1[0] + v1[1] * v1[1]) + (v1[2] * v1[2] + v1[3] * v1[3]);
;                         q += __shfl_xor(q, 16); q += __shfl_xor(q, 32); mxn[bj] = fmaxf(mxn[bj], q); }
;                     u32x4 w; w.x = cvt_pk_bf16(v0[0], v0[1]); w.y = cvt_pk_bf16(v0[2], v0[3]); w.z = cvt_pk_bf16(v1[0], v1[1]); w.w = cvt_pk_bf16(v1[2], v1[3]);
;                     *(u32x4*)(rowp + bj * HALF) = w;
.LBB0_404:
	v_cvt_pk_bf16_f32 v36, v36, v37
	v_cvt_pk_bf16_f32 v37, v38, v39
	v_cvt_pk_bf16_f32 v38, v32, v33
	v_add_u32_e32 v32, 0xa0, v208
	v_ashrrev_i32_e32 v33, 31, v32
	s_and_b64 vcc, exec, s[16:17]
	s_mov_b64 s[0:1], -1
	v_cvt_pk_bf16_f32 v39, v34, v35
	ds_bpermute_b32 v214, v253, v36
	ds_bpermute_b32 v215, v253, v37
	ds_bpermute_b32 v216, v253, v38
	ds_bpermute_b32 v217, v253, v39
	v_lshl_add_u64 v[218:219], v[40:41], 0, v[228:229]
	s_waitcnt lgkmcnt(4)
	global_store_dwordx4 v[226:227], v[222:225], off sc1
	s_cbranch_vccnz .LBB0_410
	v_lshlrev_b64 v[34:35], 6, v[32:33]
	v_lshl_add_u64 v[46:47], s[22:23], 0, v[34:35]
	global_load_dwordx4 v[34:37], v[46:47], off offset:48
	global_load_dwordx4 v[38:41], v[46:47], off offset:32
	global_load_dwordx4 v[42:45], v[46:47], off offset:16
	global_load_dwordx4 v[64:67], v[46:47], off
	s_waitcnt vmcnt(2)
	v_add_f32_e32 v38, v38, v39
	v_add_f32_e32 v40, v40, v41
	s_waitcnt vmcnt(0)
	v_mov_b32_e32 v46, v65
	v_mov_b32_e32 v47, v66
	v_mov_b32_e32 v65, v67
	v_pk_add_f32 v[46:47], v[46:47], v[64:65]
	v_mov_b32_e32 v64, v43
	v_mov_b32_e32 v65, v44
	v_mov_b32_e32 v43, v45
	v_pk_add_f32 v[42:43], v[64:65], v[42:43]
	v_pk_add_f32 v[46:47], v[46:47], v[46:47] op_sel:[0,1] op_sel_hi:[1,0]
	v_pk_add_f32 v[42:43], v[42:43], v[42:43] op_sel:[0,1] op_sel_hi:[1,0]
	v_mov_b32_e32 v47, v34
	v_mov_b32_e32 v43, v35
	v_mov_b32_e32 v39, v36
	v_mov_b32_e32 v41, v37
	v_pk_add_f32 v[34:35], v[46:47], v[42:43]
	v_pk_add_f32 v[36:37], v[38:39], v[40:41]
	s_nop 0
	v_pk_add_f32 v[34:35], v[34:35], v[36:37]
	s_nop 0
	v_add_f32_e32 v33, v34, v35
	v_fmamk_f32 v33, v33, 0x3a800000, v246
	v_cmp_gt_f32_e32 vcc, s83, v33
	v_mul_f32_e32 v34, 0x4f800000, v33
	s_nop 0
	v_cndmask_b32_e32 v33, v33, v34, vcc
	v_sqrt_f32_e32 v34, v33
	s_nop 0
	v_add_u32_e32 v35, -1, v34
	v_fma_f32 v36, -v35, v34, v33
	v_cmp_ge_f32_e64 s[0:1], 0, v36
	v_add_u32_e32 v36, 1, v34
	s_nop 0
	v_cndmask_b32_e64 v35, v34, v35, s[0:1]
	v_fma_f32 v34, -v36, v34, v33
	v_cmp_lt_f32_e64 s[0:1], 0, v34
	s_nop 1
	v_cndmask_b32_e64 v34, v35, v36, s[0:1]
	v_mul_f32_e32 v35, 0x37800000, v34
	v_cndmask_b32_e32 v34, v34, v35, vcc
	v_cmp_class_f32_e32 vcc, v33, v247
	s_nop 1
	v_cndmask_b32_e32 v33, v34, v33, vcc
	v_div_scale_f32 v34, s[0:1], v33, v33, 1.0
	v_rcp_f32_e32 v35, v34
	s_nop 0
	v_fma_f32 v36, -v34, v35, 1.0
	v_fmac_f32_e32 v35, v36, v35
	v_div_scale_f32 v36, vcc, 1.0, v33, 1.0
	v_mul_f32_e32 v37, v36, v35
	v_fma_f32 v38, -v34, v37, v36
	v_fmac_f32_e32 v37, v38, v35
	v_fma_f32 v34, -v34, v37, v36
	v_div_fmas_f32 v34, v34, v35, v37
	v_div_fixup_f32 v42, v34, v33, 1.0
	s_cbranch_execz .LBB0_411

; __device__ __forceinline__ unsigned cvt_pk_bf16(float lo, float hi) { unsigned r; asm volatile("v_cvt_pk_bf16_f32 %0, %1, %2" : "=v"(r) : "v"(lo), "v"(hi)); return r; }
;     __device__ __forceinline__ void operator()(const f32x4 (&acc)[2][2][4][2], const Unit& u, int wr, int wc, int fr, int fq) const {
;     ...
;                 bf16_t* rowp = O + (size_t)row * 3072 + col0;
;                 const float scr = sc * (slot >= 0 ? tab[slot * 256 + (row - u.pm * BM)] : row_rstd(ssp, row, 1e-6f));
;                 f32x4 c0 = {1.f, 1.f, 1.f, 1.f}, c1 = c0, s0 = {0.f, 0.f, 0.f, 0.f}, s1 = s0;
;                 if (ropew) { c0 = rc[m][0]; c1 = rc[m][1]; s0 = rc[m][2]; s1 = rc[m][3]; if (fq == 0) { s0 = -s0; s1 = -s1; } if (fq >= 2) { c0 = (f32x4){1.f, 1.f, 1.f, 1.f}; c1 = c0; s0 = (f32x4){0.f, 0.f, 0.f, 0.f}; s1 = s0; } }
; #pragma unroll
;                 for (int bj = 0; bj < 2; ++bj) {
;                     f32x4 v0 = acc[ai][bj][m][0], v1 = acc[ai][bj][m][1];
;                     if (ropew) {
;                         f32x4 p0, p1;
; #pragma unroll
;                         for (int e = 0; e < 4; ++e) { p0[e] = __shfl_xor(v0[e], 16); p1[e] = __shfl_xor(v1[e], 16); }
;                         v0 = v0 * c0 + p0 * s0; v1 = v1 * c1 + p1 * s1;
;                     }
;                     v0 = v0 * scr; v1 = v1 * scr;
;                     if (nrmw) { float q = (v0[0] * v0[0] + v0[1] * v0[1]) + (v0[2] * v0[2] + v0[3] * v0[3]) + (v1[0] * v1[0] + v1[1] * v1[1]) + (v1[2] * v1[2] + v1[3] * v1[3]);
;                         q += __shfl_xor(q, 16); q += __shfl_xor(q, 32); mxn[bj] = fmaxf(mxn[bj], q); }
;                     u32x4 w; w.x = cvt_pk_bf16(v0[0], v0[1]); w.y = cvt_pk_bf16(v0[2], v0[3]); w.z = cvt_pk_bf16(v1[0], v1[1]); w.w = cvt_pk_bf16(v1[2], v1[3]);
;                     *(u32x4*)(rowp + bj * HALF) = w;
.LBB0_418:
	v_mov_b64_e32 v[24:25], s[28:29]
	v_mad_i64_i32 v[24:25], s[0:1], v32, s86, v[24:25]
	v_lshl_add_u64 v[24:25], v[184:185], 1, v[24:25]
	s_and_b64 vcc, exec, s[12:13]
	v_cvt_pk_bf16_f32 v28, v28, v29
	v_cvt_pk_bf16_f32 v29, v30, v31
	v_cvt_pk_bf16_f32 v30, v44, v45
	v_cvt_pk_bf16_f32 v31, v26, v27
	ds_bpermute_b32 v222, v253, v28
	ds_bpermute_b32 v223, v253, v29
	ds_bpermute_b32 v224, v253, v30
	ds_bpermute_b32 v225, v253, v31
	v_lshl_add_u64 v[226:227], v[24:25], 0, v[228:229]
	s_waitcnt lgkmcnt(4)
	global_store_dwordx4 v[218:219], v[214:217], off offset:256 sc1
	s_cbranch_vccnz .LBB0_420
	ds_bpermute_b32 v26, v235, v20
	ds_bpermute_b32 v27, v235, v21
	ds_bpermute_b32 v28, v235, v16
	ds_bpermute_b32 v30, v235, v22
	ds_bpermute_b32 v31, v235, v23
	ds_bpermute_b32 v29, v235, v17
	ds_bpermute_b32 v32, v235, v18
	ds_bpermute_b32 v33, v235, v19
	s_waitcnt lgkmcnt(6)
	v_pk_mul_f32 v[26:27], v[38:39], v[26:27]
	s_waitcnt lgkmcnt(3)
	v_pk_mul_f32 v[30:31], v[40:41], v[30:31]
	v_pk_fma_f32 v[20:21], v[20:21], v[84:85], v[26:27]
	s_waitcnt lgkmcnt(2)
	v_pk_mul_f32 v[26:27], v[36:37], v[28:29]
	s_waitcnt lgkmcnt(0)
	v_pk_mul_f32 v[28:29], v[34:35], v[32:33]
	v_pk_fma_f32 v[22:23], v[22:23], v[86:87], v[30:31]
	v_pk_fma_f32 v[18:19], v[18:19], v[78:79], v[28:29]
	v_pk_fma_f32 v[16:17], v[16:17], v[76:77], v[26:27]

; __device__ __forceinline__ unsigned cvt_pk_bf16(float lo, float hi) { unsigned r; asm volatile("v_cvt_pk_bf16_f32 %0, %1, %2" : "=v"(r) : "v"(lo), "v"(hi)); return r; }
; __device__ __forceinline__ float row_rstd(const float* part, int row, float eps) {
;     const f32x4* p = (const f32x4*)(part + (size_t)row * 16);
;     const f32x4 a = p[0], b = p[1], c = p[2], d = p[3];
;     const float s = ((a[0] + a[1]) + (a[2] + a[3])) + ((b[0] + b[1]) + (b[2] + b[3])) + ((c[0] + c[1]) + (c[2] + c[3])) + ((d[0] + d[1]) + (d[2] + d[3]));
;     return 1.0f / sqrtf(s * (1.0f / 1024.0f) + eps);
; }
;     __device__ __forceinline__ void operator()(const f32x4 (&acc)[2][2][4][2], const Unit& u, int wr, int wc, int fr, int fq) const {
;     ...
;                 const int row = row0 + ai * HALF + m * 16;
;                 bf16_t* rowp = O + (size_t)row * 3072 + col0;
;                 const float scr = sc * (slot >= 0 ? tab[slot * 256 + (row - u.pm * BM)] : row_rstd(ssp, row, 1e-6f));
;                 f32x4 c0 = {1.f, 1.f, 1.f, 1.f}, c1 = c0, s0 = {0.f, 0.f, 0.f, 0.f}, s1 = s0;
;                 if (ropew) { c0 = rc[m][0]; c1 = rc[m][1]; s0 = rc[m][2]; s1 = rc[m][3]; if (fq == 0) { s0 = -s0; s1 = -s1; } if (fq >= 2) { c0 = (f32x4){1.f, 1.f, 1.f, 1.f}; c1 = c0; s0 = (f32x4){0.f, 0.f, 0.f, 0.f}; s1 = s0; } }
; #pragma unroll
;                 for (int bj = 0; bj < 2; ++bj) {
;                     f32x4 v0 = acc[ai][bj][m][0], v1 = acc[ai][bj][m][1];
;                     if (ropew) {
;                         f32x4 p0, p1;
; #pragma unroll
;                         for (int e = 0; e < 4; ++e) { p0[e] = __shfl_xor(v0[e], 16); p1[e] = __shfl_xor(v1[e], 16); }
;                         v0 = v0 * c0 + p0 * s0; v1 = v1 * c1 + p1 * s1;
;                     }
;                     v0 = v0 * scr; v1 = v1 * scr;
;                     if (nrmw) { float q = (v0[0] * v0[0] + v0[1] * v0[1]) + (v0[2] * v0[2] + v0[3] * v0[3]) + (v1[0] * v1[0] + v1[1] * v1[1]) + (v1[2] * v1[2] + v1[3] * v1[3]);
;                         q += __shfl_xor(q, 16); q += __shfl_xor(q, 32); mxn[bj] = fmaxf(mxn[bj], q); }
;                     u32x4 w; w.x = cvt_pk_bf16(v0[0], v0[1]); w.y = cvt_pk_bf16(v0[2], v0[3]); w.z = cvt_pk_bf16(v1[0], v1[1]); w.w = cvt_pk_bf16(v1[2], v1[3]);
;                     *(u32x4*)(rowp + bj * HALF) = w;
.LBB0_424:
	v_cvt_pk_bf16_f32 v20, v20, v21
	v_cvt_pk_bf16_f32 v21, v22, v23
	v_cvt_pk_bf16_f32 v22, v16, v17
	v_add_u32_e32 v16, 0xb0, v208
	v_ashrrev_i32_e32 v17, 31, v16
	s_and_b64 vcc, exec, s[16:17]
	s_mov_b64 s[0:1], -1
	v_cvt_pk_bf16_f32 v23, v18, v19
	ds_bpermute_b32 v214, v253, v20
	ds_bpermute_b32 v215, v253, v21
	ds_bpermute_b32 v216, v253, v22
	ds_bpermute_b32 v217, v253, v23
	v_lshl_add_u64 v[218:219], v[24:25], 0, v[228:229]
	s_waitcnt lgkmcnt(4)
	global_store_dwordx4 v[226:227], v[222:225], off sc1
	s_cbranch_vccnz .LBB0_430
	v_lshlrev_b64 v[18:19], 6, v[16:17]
	v_lshl_add_u64 v[30:31], s[22:23], 0, v[18:19]
	global_load_dwordx4 v[18:21], v[30:31], off offset:48
	global_load_dwordx4 v[22:25], v[30:31], off offset:32
	global_load_dwordx4 v[26:29], v[30:31], off offset:16
	s_nop 0
	global_load_dwordx4 v[30:33], v[30:31], off
	s_waitcnt vmcnt(2)
	v_add_f32_e32 v22, v22, v23
	v_add_f32_e32 v24, v24, v25
	s_waitcnt vmcnt(0)
	v_mov_b32_e32 v34, v31
	v_mov_b32_e32 v35, v32
	v_mov_b32_e32 v31, v33
	v_mov_b32_e32 v32, v27
	v_mov_b32_e32 v33, v28
	v_mov_b32_e32 v27, v29
	v_pk_add_f32 v[30:31], v[34:35], v[30:31]
	v_pk_add_f32 v[26:27], v[32:33], v[26:27]
	v_pk_add_f32 v[30:31], v[30:31], v[30:31] op_sel:[0,1] op_sel_hi:[1,0]
	v_pk_add_f32 v[26:27], v[26:27], v[26:27] op_sel:[0,1] op_sel_hi:[1,0]
	v_mov_b32_e32 v31, v18
	v_mov_b32_e32 v27, v19
	v_mov_b32_e32 v23, v20
	v_mov_b32_e32 v25, v21
	v_pk_add_f32 v[18:19], v[30:31], v[26:27]
	v_pk_add_f32 v[20:21], v[22:23], v[24:25]
	s_nop 0
	v_pk_add_f32 v[18:19], v[18:19], v[20:21]
	s_nop 0
	v_add_f32_e32 v17, v18, v19
	v_fmamk_f32 v17, v17, 0x3a800000, v246
	v_cmp_gt_f32_e32 vcc, s83, v17
	v_mul_f32_e32 v18, 0x4f800000, v17
	s_nop 0
	v_cndmask_b32_e32 v17, v17, v18, vcc
	v_sqrt_f32_e32 v18, v17
	s_nop 0
	v_add_u32_e32 v19, -1, v18
	v_fma_f32 v20, -v19, v18, v17
	v_cmp_ge_f32_e64 s[0:1], 0, v20
	v_add_u32_e32 v20, 1, v18
	s_nop 0
	v_cndmask_b32_e64 v19, v18, v19, s[0:1]
	v_fma_f32 v18, -v20, v18, v17
	v_cmp_lt_f32_e64 s[0:1], 0, v18
	s_nop 1
	v_cndmask_b32_e64 v18, v19, v20, s[0:1]
	v_mul_f32_e32 v19, 0x37800000, v18
	v_cndmask_b32_e32 v18, v18, v19, vcc
	v_cmp_class_f32_e32 vcc, v17, v247
	s_nop 1
	v_cndmask_b32_e32 v17, v18, v17, vcc
	v_div_scale_f32 v18, s[0:1], v17, v17, 1.0
	v_rcp_f32_e32 v19, v18
	s_nop 0
	v_fma_f32 v20, -v18, v19, 1.0
	v_fmac_f32_e32 v19, v20, v19
	v_div_scale_f32 v20, vcc, 1.0, v17, 1.0
	v_mul_f32_e32 v21, v20, v19
	v_fma_f32 v22, -v18, v21, v20
	v_fmac_f32_e32 v21, v22, v19
	v_fma_f32 v18, -v18, v21, v20
	v_div_fmas_f32 v18, v18, v19, v21
	v_div_fixup_f32 v26, v18, v17, 1.0
	s_cbranch_execz .LBB0_431

; __device__ __forceinline__ unsigned cvt_pk_bf16(float lo, float hi) { unsigned r; asm volatile("v_cvt_pk_bf16_f32 %0, %1, %2" : "=v"(r) : "v"(lo), "v"(hi)); return r; }
;     __device__ __forceinline__ void operator()(const f32x4 (&acc)[2][2][4][2], const Unit& u, int wr, int wc, int fr, int fq) const {
;     ...
;                 bf16_t* rowp = O + (size_t)row * 3072 + col0;
;                 const float scr = sc * (slot >= 0 ? tab[slot * 256 + (row - u.pm * BM)] : row_rstd(ssp, row, 1e-6f));
;                 f32x4 c0 = {1.f, 1.f, 1.f, 1.f}, c1 = c0, s0 = {0.f, 0.f, 0.f, 0.f}, s1 = s0;
;                 if (ropew) { c0 = rc[m][0]; c1 = rc[m][1]; s0 = rc[m][2]; s1 = rc[m][3]; if (fq == 0) { s0 = -s0; s1 = -s1; } if (fq >= 2) { c0 = (f32x4){1.f, 1.f, 1.f, 1.f}; c1 = c0; s0 = (f32x4){0.f, 0.f, 0.f, 0.f}; s1 = s0; } }
; #pragma unroll
;                 for (int bj = 0; bj < 2; ++bj) {
;                     f32x4 v0 = acc[ai][bj][m][0], v1 = acc[ai][bj][m][1];
;                     if (ropew) {
;                         f32x4 p0, p1;
; #pragma unroll
;                         for (int e = 0; e < 4; ++e) { p0[e] = __shfl_xor(v0[e], 16); p1[e] = __shfl_xor(v1[e], 16); }
;                         v0 = v0 * c0 + p0 * s0; v1 = v1 * c1 + p1 * s1;
;                     }
;                     v0 = v0 * scr; v1 = v1 * scr;
;                     if (nrmw) { float q = (v0[0] * v0[0] + v0[1] * v0[1]) + (v0[2] * v0[2] + v0[3] * v0[3]) + (v1[0] * v1[0] + v1[1] * v1[1]) + (v1[2] * v1[2] + v1[3] * v1[3]);
;                         q += __shfl_xor(q, 16); q += __shfl_xor(q, 32); mxn[bj] = fmaxf(mxn[bj], q); }
;                     u32x4 w; w.x = cvt_pk_bf16(v0[0], v0[1]); w.y = cvt_pk_bf16(v0[2], v0[3]); w.z = cvt_pk_bf16(v1[0], v1[1]); w.w = cvt_pk_bf16(v1[2], v1[3]);
;                     *(u32x4*)(rowp + bj * HALF) = w;
.LBB0_438:
	v_mov_b64_e32 v[8:9], s[28:29]
	v_mad_i64_i32 v[8:9], s[0:1], v16, s86, v[8:9]
	v_lshl_add_u64 v[8:9], v[184:185], 1, v[8:9]
	s_and_b64 vcc, exec, s[12:13]
	v_cvt_pk_bf16_f32 v12, v12, v13
	v_cvt_pk_bf16_f32 v13, v14, v15
	v_cvt_pk_bf16_f32 v14, v28, v29
	v_cvt_pk_bf16_f32 v15, v10, v11
	ds_bpermute_b32 v222, v253, v12
	ds_bpermute_b32 v223, v253, v13
	ds_bpermute_b32 v224, v253, v14
	ds_bpermute_b32 v225, v253, v15
	v_lshl_add_u64 v[226:227], v[8:9], 0, v[228:229]
	s_waitcnt lgkmcnt(4)
	global_store_dwordx4 v[218:219], v[214:217], off offset:256 sc1
	s_cbranch_vccnz .LBB0_440
	ds_bpermute_b32 v10, v235, v4
	ds_bpermute_b32 v11, v235, v5
	ds_bpermute_b32 v12, v235, v0
	ds_bpermute_b32 v14, v235, v6
	ds_bpermute_b32 v15, v235, v7
	ds_bpermute_b32 v13, v235, v1
	ds_bpermute_b32 v16, v235, v2
	ds_bpermute_b32 v17, v235, v3
	s_waitcnt lgkmcnt(6)
	v_pk_mul_f32 v[10:11], v[22:23], v[10:11]
	s_waitcnt lgkmcnt(3)
	v_pk_mul_f32 v[14:15], v[24:25], v[14:15]
	v_pk_fma_f32 v[4:5], v[4:5], v[52:53], v[10:11]
	s_waitcnt lgkmcnt(2)
	v_pk_mul_f32 v[10:11], v[20:21], v[12:13]
	s_waitcnt lgkmcnt(0)
	v_pk_mul_f32 v[12:13], v[18:19], v[16:17]
	v_pk_fma_f32 v[6:7], v[6:7], v[54:55], v[14:15]
	v_pk_fma_f32 v[2:3], v[2:3], v[50:51], v[12:13]
	v_pk_fma_f32 v[0:1], v[0:1], v[48:49], v[10:11]

; __device__ __forceinline__ unsigned cvt_pk_bf16(float lo, float hi) { unsigned r; asm volatile("v_cvt_pk_bf16_f32 %0, %1, %2" : "=v"(r) : "v"(lo), "v"(hi)); return r; }
;     __device__ __forceinline__ void operator()(const f32x4 (&acc)[2][2][4][2], const Unit& u, int wr, int wc, int fr, int fq) const {
;     ...
;                     u32x4 w; w.x = cvt_pk_bf16(v0[0], v0[1]); w.y = cvt_pk_bf16(v0[2], v0[3]); w.z = cvt_pk_bf16(v1[0], v1[1]); w.w = cvt_pk_bf16(v1[2], v1[3]);
;                     *(u32x4*)(rowp + bj * HALF) = w;
;                 }
;             }
;         }
;         if (nrmw) {
; #pragma unroll
;             for (int bj = 0; bj < 2; ++bj) { float q = mxn[bj];
;                 q = fmaxf(q, __shfl_xor(q, 1)); q = fmaxf(q, __shfl_xor(q, 2)); q = fmaxf(q, __shfl_xor(q, 4)); q = fmaxf(q, __shfl_xor(q, 8));
;                 const int rel = 256 * (u.pn & 1) + 128 * bj + 32 * wc, b = (u.pm * BM) >> 12;
;                 if (fr == 0 && fq == 0) atomicMax((unsigned*)nrm + (typ < 2 ? 256 : 0) + ((b * 2 + ((typ == 1 || typ == 4) ? 1 : 0)) * 8 + (rel >> 6)) * 2 + ((rel >> 5) & 1), __float_as_uint(q * 1.02f)); }
.LBB0_444:
	s_and_b64 vcc, exec, s[60:61]
	v_cvt_pk_bf16_f32 v4, v4, v5
	v_cvt_pk_bf16_f32 v5, v6, v7
	v_cvt_pk_bf16_f32 v6, v0, v1
	v_cvt_pk_bf16_f32 v7, v2, v3
	ds_bpermute_b32 v214, v253, v4
	ds_bpermute_b32 v215, v253, v5
	ds_bpermute_b32 v216, v253, v6
	ds_bpermute_b32 v217, v253, v7
	v_lshl_add_u64 v[218:219], v[8:9], 0, v[228:229]
	s_waitcnt lgkmcnt(4)
	global_store_dwordx4 v[226:227], v[222:225], off sc1
	s_waitcnt lgkmcnt(0)
	global_store_dwordx4 v[218:219], v[214:217], off offset:256 sc1
	s_cbranch_vccz .LBB0_456
	ds_bpermute_b32 v0, v237, v209
	v_max_f32_e32 v1, v209, v209
	s_cmp_eq_u32 s34, 1
	s_cselect_b64 s[0:1], -1, 0
	s_and_b64 s[2:3], s[58:59], exec
	s_waitcnt lgkmcnt(0)
	v_max_f32_e32 v0, v0, v0
	v_max_f32_e32 v0, v1, v0
	ds_bpermute_b32 v1, v238, v0
	s_cselect_b32 s2, 0x100, 0
	s_cmp_eq_u32 s34, 4
	s_cselect_b64 s[12:13], -1, 0
	s_or_b64 s[0:1], s[0:1], s[12:13]
	s_waitcnt lgkmcnt(0)
	v_max_f32_e32 v1, v1, v1
	v_max_f32_e32 v0, v0, v1
	ds_bpermute_b32 v1, v239, v0
	s_and_b64 s[0:1], s[0:1], exec
	s_cselect_b32 s3, 8, 0
	s_waitcnt lgkmcnt(0)
	v_max_f32_e32 v1, v1, v1
	v_max_f32_e32 v0, v0, v1
	ds_bpermute_b32 v1, v240, v0
	s_and_saveexec_b64 s[0:1], s[8:9]
	s_cbranch_execz .LBB0_450
	s_waitcnt lgkmcnt(0)
	v_max_f32_e32 v1, v1, v1
	v_max_f32_e32 v0, v0, v0
	v_max_f32_e32 v0, v0, v1
	s_mov_b64 s[12:13], exec
	v_mul_f32_e32 v0, 0x3f828f5c, v0
	s_mov_b32 s14, 0

; __device__ __forceinline__ int crow(int r,int hi){return (r&3)+8*(r>>2)+4*hi;}
; __device__ __forceinline__ int crow(int r, int hi) { return (r & 3) + 8 * (r >> 2) + 4 * hi; }
;     ...
;   {auto rr=__builtin_amdgcn_permlane32_swap(__float_as_uint(l_reg),__float_as_uint(l_reg),false,false);l_reg=__uint_as_float(rr[0])+__uint_as_float(rr[1]);}
;   if(hi==0)wsf[32+r32]=l_reg;asm volatile("s_waitcnt lgkmcnt(0)":::"memory");
;   float rli[16];
;   #pragma unroll
;   for(int r=0;r<16;++r)rli[r]=__builtin_amdgcn_rcpf(wsf[32+crow(r,hi)]);
;   bf16*Ow=Oc+(rowbase+q0+wid*QBLK)*PO;
;   { bf16*stg=(bf16*)(shm+LDS_OST128)+wid*2048;
;     #pragma unroll
;     for(int hf=0;hf<2;++hf){
;       #pragma unroll
;       for(int r=0;r<16;++r){const int orow=crow(r,hi);
;         #pragma unroll
;         for(int d0=0;d0<2;++d0)stg[orow*64+d0*32+r32]=__float2bfloat16(o[2*hf+d0][r]*rli[r]);}
;       asm volatile("s_waitcnt lgkmcnt(0)":::"memory");
.LBB0_517:
	s_or_b64 exec, exec, s[0:1]
	s_waitcnt lgkmcnt(0)
	v_lshl_add_u32 v0, v228, 2, s4
	ds_read_b128 v[2:5], v0 offset:128
	ds_read_b128 v[6:9], v0 offset:160
	s_mul_hi_i32 s1, s12, 0xc00
	s_mulk_i32 s12, 0xc00
	s_add_u32 s0, s40, s12
	s_waitcnt lgkmcnt(1)
	v_rcp_f32_e32 v12, v2
	v_rcp_f32_e32 v13, v3
	v_rcp_f32_e32 v14, v4
	v_rcp_f32_e32 v15, v5
	s_waitcnt lgkmcnt(0)
	v_rcp_f32_e32 v80, v6
	ds_read_b128 v[2:5], v0 offset:192
	v_rcp_f32_e32 v81, v7
	v_rcp_f32_e32 v82, v8
	v_rcp_f32_e32 v83, v9
	ds_read_b128 v[6:9], v0 offset:224
	s_addc_u32 s1, s41, s1
	s_lshl_b32 s2, s2, 12
	s_add_i32 s2, s2, 0
	v_lshlrev_b32_e32 v0, 1, v227
	s_waitcnt lgkmcnt(0)
	v_rcp_f32_e32 v90, v8
	v_lshrrev_b32_e32 v8, 3, v225
	v_rcp_f32_e32 v85, v3
	s_add_i32 s2, s2, 0x12800
	v_and_b32_e32 v0, 0x70, v0
	v_lshlrev_b32_e32 v3, 7, v8
	v_rcp_f32_e32 v84, v2
	v_rcp_f32_e32 v88, v6
	v_rcp_f32_e32 v89, v7
	v_lshl_add_u32 v2, v226, 1, s2
	v_lshl_add_u64 v[6:7], s[0:1], 0, v[0:1]
	v_add3_u32 v92, s2, v0, v3
	v_lshlrev_b32_e32 v0, 7, v228
	v_mul_f32_e32 v3, v48, v12
	v_add_u32_e32 v93, v2, v0
	v_cvt_pk_bf16_f32 v3, v3, s0
	ds_write_b16 v93, v3
	v_mul_f32_e32 v3, v64, v12
	v_cvt_pk_bf16_f32 v3, v3, s0
	ds_write_b16 v93, v3 offset:64
	v_mul_f32_e32 v3, v49, v13
	v_cvt_pk_bf16_f32 v3, v3, s0
	ds_write_b16 v93, v3 offset:128
	v_mul_f32_e32 v3, v65, v13
	v_cvt_pk_bf16_f32 v3, v3, s0
	ds_write_b16 v93, v3 offset:192
	v_mul_f32_e32 v3, v50, v14
	v_cvt_pk_bf16_f32 v3, v3, s0
	ds_write_b16 v93, v3 offset:256
	v_mul_f32_e32 v3, v66, v14
	v_cvt_pk_bf16_f32 v3, v3, s0
	ds_write_b16 v93, v3 offset:320
	v_mul_f32_e32 v3, v51, v15
	v_cvt_pk_bf16_f32 v3, v3, s0
	ds_write_b16 v93, v3 offset:384
	v_mul_f32_e32 v3, v67, v15
	v_cvt_pk_bf16_f32 v3, v3, s0
	ds_write_b16 v93, v3 offset:448
	v_or_b32_e32 v3, 0x400, v0
	v_add_u32_e32 v64, v2, v3
	v_mul_f32_e32 v3, v52, v80
	v_cvt_pk_bf16_f32 v3, v3, s0
	ds_write_b16 v64, v3
	v_mul_f32_e32 v3, v68, v80
	v_cvt_pk_bf16_f32 v3, v3, s0
	ds_write_b16 v64, v3 offset:64
	v_or_b32_e32 v3, 0x480, v0
	v_add_u32_e32 v65, v2, v3
	v_mul_f32_e32 v3, v53, v81
	v_cvt_pk_bf16_f32 v3, v3, s0
	ds_write_b16 v65, v3
	v_mul_f32_e32 v3, v69, v81
	v_cvt_pk_bf16_f32 v3, v3, s0
	ds_write_b16 v65, v3 offset:64
	v_or_b32_e32 v3, 0x500, v0
	v_add_u32_e32 v66, v2, v3
	v_mul_f32_e32 v3, v54, v82
	v_cvt_pk_bf16_f32 v3, v3, s0
	ds_write_b16 v66, v3
	v_mul_f32_e32 v3, v70, v82
	v_cvt_pk_bf16_f32 v3, v3, s0
	ds_write_b16 v66, v3 offset:64
	v_or_b32_e32 v3, 0x580, v0
	v_add_u32_e32 v54, v2, v3
	v_mul_f32_e32 v3, v55, v83
	v_cvt_pk_bf16_f32 v3, v3, s0
	ds_write_b16 v54, v3
	v_mul_f32_e32 v3, v71, v83
	v_cvt_pk_bf16_f32 v3, v3, s0
	ds_write_b16 v54, v3 offset:64
	v_or_b32_e32 v3, 0x800, v0
	v_add_u32_e32 v55, v2, v3
	v_mul_f32_e32 v3, v56, v84
	v_cvt_pk_bf16_f32 v3, v3, s0
	ds_write_b16 v55, v3
	v_mul_f32_e32 v3, v72, v84
	v_cvt_pk_bf16_f32 v3, v3, s0
	ds_write_b16 v55, v3 offset:64
	v_or_b32_e32 v3, 0x880, v0
	v_add_u32_e32 v56, v2, v3
	v_mul_f32_e32 v3, v57, v85
	v_rcp_f32_e32 v86, v4
	v_cvt_pk_bf16_f32 v3, v3, s0
	ds_write_b16 v56, v3
	v_mul_f32_e32 v3, v73, v85
	v_cvt_pk_bf16_f32 v3, v3, s0
	ds_write_b16 v56, v3 offset:64
	v_or_b32_e32 v3, 0x900, v0
	v_add_u32_e32 v57, v2, v3
	v_mul_f32_e32 v3, v58, v86
	v_rcp_f32_e32 v87, v5
	v_cvt_pk_bf16_f32 v3, v3, s0
	ds_write_b16 v57, v3
	v_mul_f32_e32 v3, v74, v86
	v_cvt_pk_bf16_f32 v3, v3, s0
	ds_write_b16 v57, v3 offset:64
	v_or_b32_e32 v3, 0x980, v0
	v_add_u32_e32 v58, v2, v3
	v_mul_f32_e32 v3, v59, v87
	v_cvt_pk_bf16_f32 v3, v3, s0
	ds_write_b16 v58, v3
	v_mul_f32_e32 v3, v75, v87
	v_cvt_pk_bf16_f32 v3, v3, s0
	ds_write_b16 v58, v3 offset:64
	v_or_b32_e32 v3, 0xc00, v0
	v_add_u32_e32 v59, v2, v3
	v_mul_f32_e32 v3, v60, v88
	v_cvt_pk_bf16_f32 v3, v3, s0
	ds_write_b16 v59, v3
	v_mul_f32_e32 v3, v76, v88
	v_cvt_pk_bf16_f32 v3, v3, s0
	ds_write_b16 v59, v3 offset:64
	v_or_b32_e32 v3, 0xc80, v0
	v_add_u32_e32 v60, v2, v3
	v_mul_f32_e32 v3, v61, v89
	v_cvt_pk_bf16_f32 v3, v3, s0
	ds_write_b16 v60, v3
	v_mul_f32_e32 v3, v77, v89
	v_rcp_f32_e32 v91, v9
	v_cvt_pk_bf16_f32 v3, v3, s0
	ds_write_b16 v60, v3 offset:64
	v_or_b32_e32 v3, 0xd00, v0
	v_add_u32_e32 v61, v2, v3
	v_mul_f32_e32 v3, v62, v90
	v_cvt_pk_bf16_f32 v3, v3, s0
	v_or_b32_e32 v0, 0xd80, v0
	ds_write_b16 v61, v3
	v_mul_f32_e32 v3, v78, v90
	v_add_u32_e32 v62, v2, v0
	v_mul_f32_e32 v0, v63, v91
	v_cvt_pk_bf16_f32 v3, v3, s0
	v_cvt_pk_bf16_f32 v0, v0, s0
	ds_write_b16 v61, v3 offset:64
	ds_write_b16 v62, v0
	v_mul_f32_e32 v0, v79, v91
	v_cvt_pk_bf16_f32 v0, v0, s0
	ds_write_b16 v62, v0 offset:64
	s_waitcnt lgkmcnt(0)
; __device__ __forceinline__ int crow(int r,int hi){return (r&3)+8*(r>>2)+4*hi;}
; __device__ __forceinline__ int crow(int r, int hi) { return (r & 3) + 8 * (r >> 2) + 4 * hi; }
;     ...
;   { bf16*stg=(bf16*)(shm+LDS_OST128)+wid*2048;
;     #pragma unroll
;     for(int hf=0;hf<2;++hf){
;       #pragma unroll
;       for(int r=0;r<16;++r){const int orow=crow(r,hi);
;         #pragma unroll
;         for(int d0=0;d0<2;++d0)stg[orow*64+d0*32+r32]=__float2bfloat16(o[2*hf+d0][r]*rli[r]);}
;       asm volatile("s_waitcnt lgkmcnt(0)":::"memory");
;       #pragma unroll
;       for(int i=0;i<4;++i){const int row=i*8+(lane>>3),ch=lane&7; const u32x4 v=*(const u32x4*)(stg+row*64+ch*8); ATTN_STORE16(Ow+(long)row*PO+hf*64+ch*8,v);}
;       asm volatile("s_waitcnt lgkmcnt(0)":::"memory"); } }
	ds_read_b128 v[2:5], v92
	v_mul_u32_u24_e32 v0, 0x600, v8
	v_lshlrev_b32_e32 v0, 1, v0
	v_lshl_add_u64 v[48:49], v[6:7], 0, v[0:1]
	ds_read_b128 v[6:9], v92 offset:1024
	s_waitcnt lgkmcnt(1)
	global_store_dwordx4 v[48:49], v[2:5], off sc1
	s_mov_b64 s[0:1], 0x6000
	v_lshl_add_u64 v[50:51], v[48:49], 0, s[0:1]
	v_add_co_u32_e32 v2, vcc, s67, v48
	s_mov_b32 s0, 0x12000
	s_nop 0
	v_addc_co_u32_e32 v3, vcc, 0, v49, vcc
	s_waitcnt lgkmcnt(0)
	global_store_dwordx4 v[2:3], v[6:9], off sc1
	ds_read_b128 v[2:5], v92 offset:2048
	ds_read_b128 v[6:9], v92 offset:3072
	v_add_co_u32_e32 v10, vcc, s97, v48
	v_mul_f32_e32 v0, v16, v12
	s_nop 0
	v_addc_co_u32_e32 v11, vcc, 0, v49, vcc
	s_waitcnt lgkmcnt(1)
	global_store_dwordx4 v[10:11], v[2:5], off sc1
	v_cvt_pk_bf16_f32 v0, v0, s0
	v_lshl_add_u64 v[52:53], v[48:49], 0, s[42:43]
	v_add_co_u32_e32 v2, vcc, s0, v48
	s_nop 1
	v_addc_co_u32_e32 v3, vcc, 0, v49, vcc
	s_waitcnt lgkmcnt(0)
	global_store_dwordx4 v[2:3], v[6:9], off sc1
	s_waitcnt lgkmcnt(0)
	ds_write_b16 v93, v0
	v_mul_f32_e32 v0, v32, v12
	v_cvt_pk_bf16_f32 v0, v0, s0
	ds_write_b16 v93, v0 offset:64
	v_mul_f32_e32 v0, v17, v13
	v_cvt_pk_bf16_f32 v0, v0, s0
	ds_write_b16 v93, v0 offset:128
	v_mul_f32_e32 v0, v33, v13
	v_cvt_pk_bf16_f32 v0, v0, s0
	ds_write_b16 v93, v0 offset:192
	v_mul_f32_e32 v0, v18, v14
	v_cvt_pk_bf16_f32 v0, v0, s0
	ds_write_b16 v93, v0 offset:256
	v_mul_f32_e32 v0, v34, v14
	v_cvt_pk_bf16_f32 v0, v0, s0
	ds_write_b16 v93, v0 offset:320
	v_mul_f32_e32 v0, v19, v15
	v_cvt_pk_bf16_f32 v0, v0, s0
	ds_write_b16 v93, v0 offset:384
	v_mul_f32_e32 v0, v35, v15
	v_cvt_pk_bf16_f32 v0, v0, s0
	ds_write_b16 v93, v0 offset:448
	v_mul_f32_e32 v0, v20, v80
	v_cvt_pk_bf16_f32 v0, v0, s0
	ds_write_b16 v64, v0
	v_mul_f32_e32 v0, v36, v80
	v_cvt_pk_bf16_f32 v0, v0, s0
	ds_write_b16 v64, v0 offset:64
	v_mul_f32_e32 v0, v21, v81
	v_cvt_pk_bf16_f32 v0, v0, s0
	ds_write_b16 v65, v0
	v_mul_f32_e32 v0, v37, v81
	v_cvt_pk_bf16_f32 v0, v0, s0
	ds_write_b16 v65, v0 offset:64
	v_mul_f32_e32 v0, v22, v82
	v_cvt_pk_bf16_f32 v0, v0, s0
	ds_write_b16 v66, v0
	v_mul_f32_e32 v0, v38, v82
	v_cvt_pk_bf16_f32 v0, v0, s0
	ds_write_b16 v66, v0 offset:64
	v_mul_f32_e32 v0, v23, v83
	v_cvt_pk_bf16_f32 v0, v0, s0
	ds_write_b16 v54, v0
	v_mul_f32_e32 v0, v39, v83
	v_cvt_pk_bf16_f32 v0, v0, s0
	ds_write_b16 v54, v0 offset:64
	v_mul_f32_e32 v0, v24, v84
	v_cvt_pk_bf16_f32 v0, v0, s0
	ds_write_b16 v55, v0
	v_mul_f32_e32 v0, v40, v84
	v_cvt_pk_bf16_f32 v0, v0, s0
	ds_write_b16 v55, v0 offset:64
	v_mul_f32_e32 v0, v25, v85
	v_cvt_pk_bf16_f32 v0, v0, s0
	ds_write_b16 v56, v0
	v_mul_f32_e32 v0, v41, v85
	v_cvt_pk_bf16_f32 v0, v0, s0
	ds_write_b16 v56, v0 offset:64
	v_mul_f32_e32 v0, v26, v86
	v_cvt_pk_bf16_f32 v0, v0, s0
	ds_write_b16 v57, v0
	v_mul_f32_e32 v0, v42, v86
	v_cvt_pk_bf16_f32 v0, v0, s0
	ds_write_b16 v57, v0 offset:64
	v_mul_f32_e32 v0, v27, v87
	v_cvt_pk_bf16_f32 v0, v0, s0
	ds_write_b16 v58, v0
	v_mul_f32_e32 v0, v43, v87
	v_cvt_pk_bf16_f32 v0, v0, s0
	ds_write_b16 v58, v0 offset:64
	v_mul_f32_e32 v0, v28, v88
	v_cvt_pk_bf16_f32 v0, v0, s0
	ds_write_b16 v59, v0
	v_mul_f32_e32 v0, v44, v88
	v_cvt_pk_bf16_f32 v0, v0, s0
	ds_write_b16 v59, v0 offset:64
	v_mul_f32_e32 v0, v29, v89
	v_cvt_pk_bf16_f32 v0, v0, s0
	ds_write_b16 v60, v0
	v_mul_f32_e32 v0, v45, v89
	v_cvt_pk_bf16_f32 v0, v0, s0
	ds_write_b16 v60, v0 offset:64
	v_mul_f32_e32 v0, v30, v90
	v_cvt_pk_bf16_f32 v0, v0, s0
	ds_write_b16 v61, v0
	v_mul_f32_e32 v0, v46, v90
	v_cvt_pk_bf16_f32 v0, v0, s0
	ds_write_b16 v61, v0 offset:64
	v_mul_f32_e32 v0, v31, v91
	v_cvt_pk_bf16_f32 v0, v0, s0
	ds_write_b16 v62, v0
	v_mul_f32_e32 v0, v47, v91
	v_cvt_pk_bf16_f32 v0, v0, s0
	ds_write_b16 v62, v0 offset:64
	s_waitcnt lgkmcnt(0)
	ds_read_b128 v[2:5], v92
	ds_read_b128 v[6:9], v92 offset:1024
	ds_read_b128 v[10:13], v92 offset:2048
	ds_read_b128 v[14:17], v92 offset:3072
	v_lshl_add_u64 v[18:19], v[48:49], 0, s[44:45]
	s_waitcnt lgkmcnt(3)
	global_store_dwordx4 v[48:49], v[2:5], off offset:128 sc1
	s_waitcnt lgkmcnt(2)
	global_store_dwordx4 v[50:51], v[6:9], off offset:128 sc1
	s_waitcnt lgkmcnt(1)
	global_store_dwordx4 v[52:53], v[10:13], off offset:128 sc1
	s_waitcnt lgkmcnt(0)
	global_store_dwordx4 v[18:19], v[14:17], off offset:128 sc1
	s_waitcnt lgkmcnt(0)
	s_waitcnt lgkmcnt(0)
	s_barrier

; __device__ __forceinline__ int crow(int r,int hi){return (r&3)+8*(r>>2)+4*hi;}
; #define SBAR() __builtin_amdgcn_sched_barrier(0)
;   #define PKW(P,B) cvtpk_s(P[B],P[B+1])
;   #define PKW(P,B) cvtpk_s(P[B],P[B+1])
; __device__ __forceinline__ int crow(int r, int hi) { return (r & 3) + 8 * (r >> 2) + 4 * hi; }
; template<int THRL,bool HASB> __device__ __forceinline__ void attn_unit(int b,int qb,const bf16*Qc,const bf16*__restrict__ Kc,const bf16*__restrict__ Vc,bf16*Oc,const float*__restrict__ kbg,int t0,char*shm,const int wv){
;     ...
;   { float sacc=pB0[0]+pB0[1]; _Pragma("unroll") for(int r=2;r<16;++r)sacc+=pB0[r]; _Pragma("unroll") for(int r=0;r<16;++r)sacc+=pB1[r]; l_reg+=sacc;
;     pw0=(u32x4){PKW(pB0,0),PKW(pB0,2),PKW(pB0,4),PKW(pB0,6)};pw1=(u32x4){PKW(pB0,8),PKW(pB0,10),PKW(pB0,12),PKW(pB0,14)};pw2=(u32x4){PKW(pB1,0),PKW(pB1,2),PKW(pB1,4),PKW(pB1,6)};pw3=(u32x4){PKW(pB1,8),PKW(pB1,10),PKW(pB1,12),PKW(pB1,14)};
;     SBAR(); pv(o,vb0+sl_cur,PAF(0),PAF(1),PAF(2),PAF(3)); }
;     ...
;   {auto rr=__builtin_amdgcn_permlane32_swap(__float_as_uint(l_reg),__float_as_uint(l_reg),false,false);l_reg=__uint_as_float(rr[0])+__uint_as_float(rr[1]);}
;   if(hi==0)wsf[32+r32]=l_reg;asm volatile("s_waitcnt lgkmcnt(0)":::"memory");
;   float rli[16];
;   #pragma unroll
;   for(int r=0;r<16;++r)rli[r]=__builtin_amdgcn_rcpf(wsf[32+crow(r,hi)]);
.LBB0_598:
	v_add_f32_e32 v4, v64, v65
	v_add_f32_e32 v4, v66, v4
	v_add_f32_e32 v4, v67, v4
	v_add_f32_e32 v4, v68, v4
	v_add_f32_e32 v4, v69, v4
	v_add_f32_e32 v4, v70, v4
	v_add_f32_e32 v4, v71, v4
	v_add_f32_e32 v4, v72, v4
	v_add_f32_e32 v4, v73, v4
	v_add_f32_e32 v4, v74, v4
	v_add_f32_e32 v4, v75, v4
	v_add_f32_e32 v4, v76, v4
	v_add_f32_e32 v4, v77, v4
	v_add_f32_e32 v4, v78, v4
	v_add_f32_e32 v4, v79, v4
	v_add_f32_e32 v4, v4, v48
	v_add_f32_e32 v4, v49, v4
	v_add_f32_e32 v4, v50, v4
	v_add_f32_e32 v4, v51, v4
	v_add_f32_e32 v4, v52, v4
	v_add_f32_e32 v4, v53, v4
	v_add_f32_e32 v4, v54, v4
	v_add_f32_e32 v4, v55, v4
	v_add_f32_e32 v4, v56, v4
	v_add_f32_e32 v4, v57, v4
	v_add_f32_e32 v4, v58, v4
	v_add_f32_e32 v4, v59, v4
	v_add_f32_e32 v4, v60, v4
	s_cmp_lg_u32 0, -1
	v_add_f32_e32 v4, v61, v4
	s_cselect_b32 s0, 0, 0
	v_add_f32_e32 v4, v62, v4
	s_addk_i32 s0, 0x6000
	v_add_f32_e32 v4, v63, v4
	v_add3_u32 v3, v217, s0, v214
	v_add_f32_e32 v0, v0, v4
	v_cvt_pk_bf16_f32 v4, v64, v65
	v_cvt_pk_bf16_f32 v5, v66, v67
	v_cvt_pk_bf16_f32 v6, v68, v69
	v_cvt_pk_bf16_f32 v7, v70, v71
	v_cvt_pk_bf16_f32 v8, v72, v73
	v_cvt_pk_bf16_f32 v9, v74, v75
	v_cvt_pk_bf16_f32 v10, v76, v77
	v_cvt_pk_bf16_f32 v11, v78, v79
	v_cvt_pk_bf16_f32 v12, v48, v49
	v_cvt_pk_bf16_f32 v13, v50, v51
	v_cvt_pk_bf16_f32 v14, v52, v53
	v_cvt_pk_bf16_f32 v15, v54, v55
	v_cvt_pk_bf16_f32 v48, v56, v57
	v_cvt_pk_bf16_f32 v49, v58, v59
	v_cvt_pk_bf16_f32 v50, v60, v61
	v_cvt_pk_bf16_f32 v51, v62, v63
	v_add3_u32 v3, v3, v215, v226
	ds_read_b64_tr_b16 v[52:53],v3 offset:0
	ds_read_b64_tr_b16 v[54:55],v3 offset:512
	ds_read_b64_tr_b16 v[56:57],v3 offset:1024
	ds_read_b64_tr_b16 v[58:59],v3 offset:1536
	ds_read_b64_tr_b16 v[60:61],v3 offset:2048
	ds_read_b64_tr_b16 v[62:63],v3 offset:2560
	ds_read_b64_tr_b16 v[64:65],v3 offset:3072
	ds_read_b64_tr_b16 v[66:67],v3 offset:3584
	s_waitcnt lgkmcnt(0)
	s_nop 0
	v_mfma_f32_32x32x16_bf16 v[32:47], v[4:7], v[52:55], v[32:47]
	ds_read_b64_tr_b16 v[52:53],v3 offset:4096
	ds_read_b64_tr_b16 v[54:55],v3 offset:4608
	v_mfma_f32_32x32x16_bf16 v[32:47], v[8:11], v[56:59], v[32:47]
	ds_read_b64_tr_b16 v[56:57],v3 offset:5120
	ds_read_b64_tr_b16 v[58:59],v3 offset:5632
	v_mfma_f32_32x32x16_bf16 v[32:47], v[12:15], v[60:63], v[32:47]
	ds_read_b64_tr_b16 v[60:61],v3 offset:6144
	ds_read_b64_tr_b16 v[62:63],v3 offset:6656
	v_mfma_f32_32x32x16_bf16 v[32:47], v[48:51], v[64:67], v[32:47]
	ds_read_b64_tr_b16 v[64:65],v3 offset:7168
	ds_read_b64_tr_b16 v[66:67],v3 offset:7680
	s_waitcnt lgkmcnt(0)
	v_mfma_f32_32x32x16_bf16 v[16:31], v[4:7], v[52:55], v[16:31]
	v_mov_b32_e32 v3, v0
	s_nop 1
	v_permlane32_swap_b32_e32 v0, v3
	v_cmp_gt_u32_e32 vcc, 32, v208
	v_mfma_f32_32x32x16_bf16 v[16:31], v[8:11], v[56:59], v[16:31]
	v_mfma_f32_32x32x16_bf16 v[16:31], v[12:15], v[60:63], v[16:31]
	v_mfma_f32_32x32x16_bf16 v[16:31], v[48:51], v[64:67], v[16:31]
	s_and_saveexec_b64 s[0:1], vcc
	v_add_f32_e32 v0, v0, v3
	ds_write_b32 v218, v0 offset:49280
	s_or_b64 exec, exec, s[0:1]
	s_waitcnt lgkmcnt(0)
	ds_read_b128 v[4:7], v2 offset:49280
	ds_read_b128 v[8:11], v2 offset:49312
	s_lshl_b32 s0, s12, 12
	s_add_i32 s2, s0, 0
	v_lshlrev_b32_e32 v50, 9, v211
	s_waitcnt lgkmcnt(1)
	v_rcp_f32_e32 v0, v4
	v_rcp_f32_e32 v3, v5
	v_rcp_f32_e32 v12, v6
	v_rcp_f32_e32 v13, v7
	s_waitcnt lgkmcnt(0)
	v_rcp_f32_e32 v14, v8
	ds_read_b128 v[4:7], v2 offset:49344
	v_rcp_f32_e32 v15, v9
	v_rcp_f32_e32 v48, v10
	v_rcp_f32_e32 v49, v11
	ds_read_b128 v[8:11], v2 offset:49376
	s_waitcnt lgkmcnt(1)
	v_rcp_f32_e32 v2, v4
	v_rcp_f32_e32 v4, v5
	v_rcp_f32_e32 v5, v6
	v_rcp_f32_e32 v6, v7
	s_waitcnt lgkmcnt(0)
; __device__ __forceinline__ int crow(int r,int hi){return (r&3)+8*(r>>2)+4*hi;}
; __device__ __forceinline__ int crow(int r, int hi) { return (r & 3) + 8 * (r >> 2) + 4 * hi; }
; template<int THRL,bool HASB> __device__ __forceinline__ void attn_unit(int b,int qb,const bf16*Qc,const bf16*__restrict__ Kc,const bf16*__restrict__ Vc,bf16*Oc,const float*__restrict__ kbg,int t0,char*shm,const int wv){
;     ...
;   for(int r=0;r<16;++r)rli[r]=__builtin_amdgcn_rcpf(wsf[32+crow(r,hi)]);
;   bf16*Ow=Oc+(rowbase+q0+wid*QBLK)*PO;
;   { bf16*stg=(bf16*)(shm+LDS_OST)+wid*2048;
;     #pragma unroll
;     for(int r=0;r<16;++r){const int orow=crow(r,hi);
;       #pragma unroll
;       for(int d0=0;d0<2;++d0)stg[orow*64+d0*32+r32]=__float2bfloat16(o[d0][r]*rli[r]);}
;     asm volatile("s_waitcnt lgkmcnt(0)":::"memory");
;     #pragma unroll
;     for(int i=0;i<4;++i){const int row=i*8+(lane>>3),ch=lane&7; const u32x4 v=*(const u32x4*)(stg+row*64+ch*8); ATTN_STORE16(Ow+(long)row*PO+ch*8,v);} }
;   asm volatile("s_waitcnt lgkmcnt(0)\n\ts_barrier":::"memory");
	v_rcp_f32_e32 v7, v8
	v_rcp_f32_e32 v8, v9
	v_rcp_f32_e32 v9, v10
	v_rcp_f32_e32 v10, v11
	v_lshlrev_b32_e32 v11, 1, v210
	v_mul_f32_e32 v32, v32, v0
	v_mul_f32_e32 v0, v16, v0
	v_add3_u32 v11, s2, v11, v50
	v_cvt_pk_bf16_f32 v0, v0, s0
	ds_write_b16 v11, v0 offset:51264
	v_mul_f32_e32 v0, v33, v3
	v_cvt_pk_bf16_f32 v0, v0, s0
	ds_write_b16 v11, v0 offset:51328
	v_mul_f32_e32 v0, v17, v3
	v_cvt_pk_bf16_f32 v0, v0, s0
	ds_write_b16 v11, v0 offset:51392
	v_mul_f32_e32 v0, v34, v12
	v_cvt_pk_bf16_f32 v0, v0, s0
	ds_write_b16 v11, v0 offset:51456
	v_mul_f32_e32 v0, v18, v12
	v_cvt_pk_bf16_f32 v0, v0, s0
	ds_write_b16 v11, v0 offset:51520
	v_mul_f32_e32 v0, v35, v13
	v_cvt_pk_bf16_f32 v0, v0, s0
	ds_write_b16 v11, v0 offset:51584
	v_mul_f32_e32 v0, v19, v13
	v_cvt_pk_bf16_f32 v0, v0, s0
	ds_write_b16 v11, v0 offset:51648
	v_mul_f32_e32 v0, v36, v14
	v_cvt_pk_bf16_f32 v0, v0, s0
	ds_write_b16 v11, v0 offset:52224
	v_mul_f32_e32 v0, v20, v14
	v_cvt_pk_bf16_f32 v0, v0, s0
	ds_write_b16 v11, v0 offset:52288
	v_mul_f32_e32 v0, v37, v15
	v_cvt_pk_bf16_f32 v0, v0, s0
	ds_write_b16 v11, v0 offset:52352
	v_mul_f32_e32 v0, v21, v15
	v_cvt_pk_bf16_f32 v0, v0, s0
	ds_write_b16 v11, v0 offset:52416
	v_mul_f32_e32 v0, v38, v48
	v_cvt_pk_bf16_f32 v0, v0, s0
	ds_write_b16 v11, v0 offset:52480
	v_mul_f32_e32 v0, v22, v48
	v_cvt_pk_bf16_f32 v0, v0, s0
	ds_write_b16 v11, v0 offset:52544
	v_mul_f32_e32 v0, v39, v49
	v_cvt_pk_bf16_f32 v0, v0, s0
	ds_write_b16 v11, v0 offset:52608
	v_mul_f32_e32 v0, v23, v49
	v_cvt_pk_bf16_f32 v0, v0, s0
	ds_write_b16 v11, v0 offset:52672
	v_mul_f32_e32 v0, v40, v2
	v_cvt_pk_bf16_f32 v0, v0, s0
	ds_write_b16 v11, v0 offset:53248
	v_mul_f32_e32 v0, v24, v2
	v_cvt_pk_bf16_f32 v0, v0, s0
	ds_write_b16 v11, v0 offset:53312
	v_mul_f32_e32 v0, v41, v4
	v_cvt_pk_bf16_f32 v0, v0, s0
	ds_write_b16 v11, v0 offset:53376
	v_mul_f32_e32 v0, v25, v4
	v_cvt_pk_bf16_f32 v0, v0, s0
	ds_write_b16 v11, v0 offset:53440
	v_mul_f32_e32 v0, v42, v5
	v_cvt_pk_bf16_f32 v0, v0, s0
	ds_write_b16 v11, v0 offset:53504
	v_mul_f32_e32 v0, v26, v5
	v_cvt_pk_bf16_f32 v0, v0, s0
	ds_write_b16 v11, v0 offset:53568
	v_mul_f32_e32 v0, v43, v6
	v_cvt_pk_bf16_f32 v0, v0, s0
	ds_write_b16 v11, v0 offset:53632
	v_mul_f32_e32 v0, v27, v6
	v_cvt_pk_bf16_f32 v0, v0, s0
	ds_write_b16 v11, v0 offset:53696
	v_mul_f32_e32 v0, v44, v7
	v_cvt_pk_bf16_f32 v0, v0, s0
	ds_write_b16 v11, v0 offset:54272
	v_mul_f32_e32 v0, v28, v7
	v_cvt_pk_bf16_f32 v0, v0, s0
	ds_write_b16 v11, v0 offset:54336
	v_mul_f32_e32 v0, v45, v8
	v_cvt_pk_bf16_f32 v0, v0, s0
	ds_write_b16 v11, v0 offset:54400
	v_mul_f32_e32 v0, v29, v8
	v_cvt_pk_bf16_f32 v0, v0, s0
	ds_write_b16 v11, v0 offset:54464
	v_mul_f32_e32 v0, v46, v9
	v_cvt_pk_bf16_f32 v0, v0, s0
	ds_write_b16 v11, v0 offset:54528
	v_mul_f32_e32 v0, v30, v9
	v_cvt_pk_bf16_f32 v0, v0, s0
	ds_write_b16 v11, v0 offset:54592
	v_mul_f32_e32 v0, v47, v10
	v_cvt_pk_bf16_f32 v0, v0, s0
	ds_write_b16 v11, v0 offset:54656
	v_mul_f32_e32 v0, v31, v10
	v_cvt_pk_bf16_f32 v0, v0, s0
	v_mov_b64_e32 v[2:3], s[54:55]
	v_cvt_pk_bf16_f32 v32, v32, s0
	ds_write_b16 v11, v0 offset:54720
	v_mad_u64_u32 v[2:3], s[0:1], v196, s66, v[2:3]
	v_lshlrev_b32_e32 v0, 1, v209
	v_mad_i32_i24 v3, v197, s66, v3
	v_lshrrev_b32_e32 v8, 3, v208
	v_and_b32_e32 v0, 0x70, v0
	ds_write_b16 v11, v32 offset:51200
	v_lshl_add_u64 v[6:7], v[2:3], 0, v[0:1]
	v_lshlrev_b32_e32 v2, 7, v8
	s_waitcnt lgkmcnt(0)
	v_add3_u32 v14, s2, v0, v2
	ds_read_b128 v[2:5], v14 offset:51200
	v_mul_u32_u24_e32 v0, 0x600, v8
	v_lshlrev_b32_e32 v0, 1, v0
	v_lshl_add_u64 v[10:11], v[6:7], 0, v[0:1]
	ds_read_b128 v[6:9], v14 offset:52224
	s_waitcnt lgkmcnt(1)
	global_store_dwordx4 v[10:11], v[2:5], off sc1
	s_mov_b64 s[0:1], 0
	s_nop 0
	v_add_co_u32_e32 v2, vcc, s67, v10
	s_nop 1
	v_addc_co_u32_e32 v3, vcc, 0, v11, vcc
	s_waitcnt lgkmcnt(0)
	global_store_dwordx4 v[2:3], v[6:9], off sc1
	ds_read_b128 v[2:5], v14 offset:53248
	ds_read_b128 v[6:9], v14 offset:54272
	v_add_co_u32_e32 v12, vcc, 0xc000, v10
	s_nop 1
	v_addc_co_u32_e32 v13, vcc, 0, v11, vcc
	s_waitcnt lgkmcnt(1)
	global_store_dwordx4 v[12:13], v[2:5], off sc1
	s_nop 1
	v_add_co_u32_e32 v2, vcc, 0x12000, v10
	s_nop 1
	v_addc_co_u32_e32 v3, vcc, 0, v11, vcc
	s_waitcnt lgkmcnt(0)
	global_store_dwordx4 v[2:3], v[6:9], off sc1
	s_waitcnt lgkmcnt(0)
	s_barrier

; __device__ __forceinline__ int crow(int r,int hi){return (r&3)+8*(r>>2)+4*hi;}
; #define SBAR() __builtin_amdgcn_sched_barrier(0)
;   #define PKW(P,B) cvtpk_s(P[B],P[B+1])
;   #define PKW(P,B) cvtpk_s(P[B],P[B+1])
; __device__ __forceinline__ int crow(int r, int hi) { return (r & 3) + 8 * (r >> 2) + 4 * hi; }
;     ...
;   { float sacc=pB0[0]+pB0[1]; _Pragma("unroll") for(int r=2;r<16;++r)sacc+=pB0[r]; _Pragma("unroll") for(int r=0;r<16;++r)sacc+=pB1[r]; l_reg+=sacc;
;     pw0=(u32x4){PKW(pB0,0),PKW(pB0,2),PKW(pB0,4),PKW(pB0,6)};pw1=(u32x4){PKW(pB0,8),PKW(pB0,10),PKW(pB0,12),PKW(pB0,14)};pw2=(u32x4){PKW(pB1,0),PKW(pB1,2),PKW(pB1,4),PKW(pB1,6)};pw3=(u32x4){PKW(pB1,8),PKW(pB1,10),PKW(pB1,12),PKW(pB1,14)};
;     SBAR(); pv(o,vb0+2*sl_cur,PAF(0),PAF(1),PAF(2),PAF(3)); pv(o+2,vb0+2*sl_cur+8192,PAF(0),PAF(1),PAF(2),PAF(3)); }
;     ...
;   {auto rr=__builtin_amdgcn_permlane32_swap(__float_as_uint(l_reg),__float_as_uint(l_reg),false,false);l_reg=__uint_as_float(rr[0])+__uint_as_float(rr[1]);}
;   if(hi==0)wsf[32+r32]=l_reg;asm volatile("s_waitcnt lgkmcnt(0)":::"memory");
;   float rli[16];
;   #pragma unroll
;   for(int r=0;r<16;++r)rli[r]=__builtin_amdgcn_rcpf(wsf[32+crow(r,hi)]);
.LBB0_686:
	v_add_f32_e32 v100, v82, v83
	v_add_f32_e32 v100, v84, v100
	v_add_f32_e32 v100, v85, v100
	v_add_f32_e32 v100, v86, v100
	v_add_f32_e32 v100, v87, v100
	v_add_f32_e32 v100, v88, v100
	v_add_f32_e32 v100, v89, v100
	v_add_f32_e32 v100, v90, v100
	v_add_f32_e32 v100, v91, v100
	v_add_f32_e32 v100, v92, v100
	v_add_f32_e32 v100, v93, v100
	v_add_f32_e32 v100, v94, v100
	v_add_f32_e32 v100, v95, v100
	v_add_f32_e32 v100, v96, v100
	v_add_f32_e32 v100, v97, v100
	v_add_f32_e32 v100, v100, v66
	v_add_f32_e32 v100, v67, v100
	v_add_f32_e32 v100, v68, v100
	v_add_f32_e32 v100, v69, v100
	v_add_f32_e32 v100, v70, v100
	v_add_f32_e32 v100, v71, v100
	v_add_f32_e32 v100, v72, v100
	v_add_f32_e32 v100, v73, v100
	v_add_f32_e32 v100, v74, v100
	v_add_f32_e32 v100, v75, v100
	v_add_f32_e32 v100, v76, v100
	v_add_f32_e32 v100, v77, v100
	v_add_f32_e32 v100, v78, v100
	v_add_f32_e32 v100, v79, v100
	s_cmp_lg_u32 0, -1
	v_add_f32_e32 v100, v80, v100
	s_cselect_b32 s0, 0, 0
	v_add_f32_e32 v100, v81, v100
	s_addk_i32 s0, 0x6000
	v_add_f32_e32 v98, v98, v100
	v_cvt_pk_bf16_f32 v66, v66, v67
	v_add3_u32 v99, v226, s0, v222
	v_cvt_pk_bf16_f32 v82, v82, v83
	v_cvt_pk_bf16_f32 v83, v84, v85
	v_cvt_pk_bf16_f32 v84, v86, v87
	v_cvt_pk_bf16_f32 v85, v88, v89
	v_cvt_pk_bf16_f32 v86, v90, v91
	v_cvt_pk_bf16_f32 v87, v92, v93
	v_cvt_pk_bf16_f32 v88, v94, v95
	v_cvt_pk_bf16_f32 v89, v96, v97
	v_cvt_pk_bf16_f32 v67, v68, v69
	v_cvt_pk_bf16_f32 v68, v70, v71
	v_cvt_pk_bf16_f32 v69, v72, v73
	v_cvt_pk_bf16_f32 v70, v74, v75
	v_cvt_pk_bf16_f32 v71, v76, v77
	v_cvt_pk_bf16_f32 v72, v78, v79
	v_cvt_pk_bf16_f32 v73, v80, v81
	s_lshl_b32 s0, s33, 1
	v_add3_u32 v99, v99, v225, s0
	ds_read_b64_tr_b16 v[74:75],v99 offset:0
	ds_read_b64_tr_b16 v[76:77],v99 offset:512
	ds_read_b64_tr_b16 v[78:79],v99 offset:1024
	ds_read_b64_tr_b16 v[80:81],v99 offset:1536
	ds_read_b64_tr_b16 v[90:91],v99 offset:2048
	ds_read_b64_tr_b16 v[92:93],v99 offset:2560
	ds_read_b64_tr_b16 v[94:95],v99 offset:3072
	ds_read_b64_tr_b16 v[96:97],v99 offset:3584
	s_waitcnt lgkmcnt(0)
	s_nop 0
	v_mfma_f32_32x32x16_bf16 v[50:65], v[82:85], v[74:77], v[50:65]
	ds_read_b64_tr_b16 v[74:75],v99 offset:4096
	ds_read_b64_tr_b16 v[76:77],v99 offset:4608
	v_mfma_f32_32x32x16_bf16 v[50:65], v[86:89], v[78:81], v[50:65]
	ds_read_b64_tr_b16 v[78:79],v99 offset:5120
	ds_read_b64_tr_b16 v[80:81],v99 offset:5632
	v_mfma_f32_32x32x16_bf16 v[50:65], v[66:69], v[90:93], v[50:65]
	ds_read_b64_tr_b16 v[90:91],v99 offset:6144
	ds_read_b64_tr_b16 v[92:93],v99 offset:6656
	v_mfma_f32_32x32x16_bf16 v[50:65], v[70:73], v[94:97], v[50:65]
	ds_read_b64_tr_b16 v[94:95],v99 offset:7168
	ds_read_b64_tr_b16 v[96:97],v99 offset:7680
	s_waitcnt lgkmcnt(0)
	v_mfma_f32_32x32x16_bf16 v[34:49], v[82:85], v[74:77], v[34:49]
	v_add_u32_e32 v99, 0x2000, v99
	ds_read_b64_tr_b16 v[74:75],v99 offset:0
	ds_read_b64_tr_b16 v[76:77],v99 offset:512
	v_mfma_f32_32x32x16_bf16 v[34:49], v[86:89], v[78:81], v[34:49]
	ds_read_b64_tr_b16 v[78:79],v99 offset:1024
	ds_read_b64_tr_b16 v[80:81],v99 offset:1536
	v_mfma_f32_32x32x16_bf16 v[34:49], v[66:69], v[90:93], v[34:49]
	ds_read_b64_tr_b16 v[90:91],v99 offset:2048
	ds_read_b64_tr_b16 v[92:93],v99 offset:2560
	v_mfma_f32_32x32x16_bf16 v[34:49], v[70:73], v[94:97], v[34:49]
	ds_read_b64_tr_b16 v[94:95],v99 offset:3072
	ds_read_b64_tr_b16 v[96:97],v99 offset:3584
	s_waitcnt lgkmcnt(0)
	v_mfma_f32_32x32x16_bf16 v[18:33], v[82:85], v[74:77], v[18:33]
	ds_read_b64_tr_b16 v[74:75],v99 offset:4096
	ds_read_b64_tr_b16 v[76:77],v99 offset:4608
	v_mfma_f32_32x32x16_bf16 v[18:33], v[86:89], v[78:81], v[18:33]
	ds_read_b64_tr_b16 v[78:79],v99 offset:5120
	ds_read_b64_tr_b16 v[80:81],v99 offset:5632
	v_mfma_f32_32x32x16_bf16 v[18:33], v[66:69], v[90:93], v[18:33]
	ds_read_b64_tr_b16 v[90:91],v99 offset:6144
	ds_read_b64_tr_b16 v[92:93],v99 offset:6656
	v_mfma_f32_32x32x16_bf16 v[18:33], v[70:73], v[94:97], v[18:33]
	ds_read_b64_tr_b16 v[94:95],v99 offset:7168
	ds_read_b64_tr_b16 v[96:97],v99 offset:7680
	s_waitcnt lgkmcnt(0)
	v_mfma_f32_32x32x16_bf16 v[2:17], v[82:85], v[74:77], v[2:17]
	v_cmp_gt_u32_e32 vcc, 32, v219
	v_mfma_f32_32x32x16_bf16 v[2:17], v[86:89], v[78:81], v[2:17]
	v_mfma_f32_32x32x16_bf16 v[2:17], v[66:69], v[90:93], v[2:17]
	v_mov_b32_e32 v66, v98
	s_nop 1
	v_permlane32_swap_b32_e32 v98, v66
	v_mfma_f32_32x32x16_bf16 v[2:17], v[70:73], v[94:97], v[2:17]
	s_and_saveexec_b64 s[0:1], vcc
	v_add_f32_e32 v66, v98, v66
	ds_write_b32 v223, v66 offset:128
	s_or_b64 exec, exec, s[0:1]
	s_waitcnt lgkmcnt(0)
	ds_read_b128 v[66:69], v0 offset:128
	ds_read_b128 v[70:73], v0 offset:160
	s_mul_hi_i32 s1, s13, 0xc00
	s_mulk_i32 s13, 0xc00
	s_add_u32 s0, s40, s13
	s_waitcnt lgkmcnt(1)
	v_rcp_f32_e32 v74, v66
	v_rcp_f32_e32 v75, v67
	v_rcp_f32_e32 v76, v68
	v_rcp_f32_e32 v77, v69
	ds_read_b128 v[66:69], v0 offset:192
	s_addc_u32 s1, s41, s1
	s_lshl_b32 s2, s12, 12
	s_waitcnt lgkmcnt(1)
	v_rcp_f32_e32 v78, v70
	v_rcp_f32_e32 v79, v71
	v_rcp_f32_e32 v80, v72
	v_rcp_f32_e32 v81, v73
	ds_read_b128 v[70:73], v0 offset:224
	s_add_i32 s2, s2, 0
	v_lshrrev_b32_e32 v85, 3, v219
	v_lshlrev_b32_e32 v0, 1, v221
	s_add_i32 s2, s2, 0x12800
	v_and_b32_e32 v0, 0x70, v0
	v_lshlrev_b32_e32 v86, 7, v85
	s_waitcnt lgkmcnt(1)
; __device__ __forceinline__ int crow(int r,int hi){return (r&3)+8*(r>>2)+4*hi;}
; __device__ __forceinline__ int crow(int r, int hi) { return (r & 3) + 8 * (r >> 2) + 4 * hi; }
;     ...
;   {auto rr=__builtin_amdgcn_permlane32_swap(__float_as_uint(l_reg),__float_as_uint(l_reg),false,false);l_reg=__uint_as_float(rr[0])+__uint_as_float(rr[1]);}
;   if(hi==0)wsf[32+r32]=l_reg;asm volatile("s_waitcnt lgkmcnt(0)":::"memory");
;   float rli[16];
;   #pragma unroll
;   for(int r=0;r<16;++r)rli[r]=__builtin_amdgcn_rcpf(wsf[32+crow(r,hi)]);
;   bf16*Ow=Oc+(rowbase+q0+wid*QBLK)*PO;
;   { bf16*stg=(bf16*)(shm+LDS_OST128)+wid*2048;
;     #pragma unroll
;     for(int hf=0;hf<2;++hf){
;       #pragma unroll
;       for(int r=0;r<16;++r){const int orow=crow(r,hi);
;         #pragma unroll
;         for(int d0=0;d0<2;++d0)stg[orow*64+d0*32+r32]=__float2bfloat16(o[2*hf+d0][r]*rli[r]);}
;       asm volatile("s_waitcnt lgkmcnt(0)":::"memory");
;       #pragma unroll
;       for(int i=0;i<4;++i){const int row=i*8+(lane>>3),ch=lane&7; const u32x4 v=*(const u32x4*)(stg+row*64+ch*8); ATTN_STORE16(Ow+(long)row*PO+hf*64+ch*8,v);}
;       asm volatile("s_waitcnt lgkmcnt(0)":::"memory"); } }
	v_rcp_f32_e32 v82, v66
	v_rcp_f32_e32 v83, v67
	v_lshlrev_b32_e32 v84, 1, v220
	v_lshl_add_u64 v[66:67], s[0:1], 0, v[0:1]
	v_add3_u32 v86, s2, v0, v86
	v_lshlrev_b32_e32 v0, 9, v218
	v_add3_u32 v84, s2, v84, v0
	v_mul_f32_e32 v0, v50, v74
	v_cvt_pk_bf16_f32 v0, v0, s0
	ds_write_b16 v84, v0
	v_mul_f32_e32 v0, v34, v74
	v_cvt_pk_bf16_f32 v0, v0, s0
	ds_write_b16 v84, v0 offset:64
	v_mul_f32_e32 v0, v51, v75
	v_cvt_pk_bf16_f32 v0, v0, s0
	ds_write_b16 v84, v0 offset:128
	v_mul_f32_e32 v0, v35, v75
	v_cvt_pk_bf16_f32 v0, v0, s0
	ds_write_b16 v84, v0 offset:192
	v_mul_f32_e32 v0, v52, v76
	v_cvt_pk_bf16_f32 v0, v0, s0
	ds_write_b16 v84, v0 offset:256
	v_mul_f32_e32 v0, v36, v76
	v_cvt_pk_bf16_f32 v0, v0, s0
	ds_write_b16 v84, v0 offset:320
	v_mul_f32_e32 v0, v53, v77
	v_cvt_pk_bf16_f32 v0, v0, s0
	ds_write_b16 v84, v0 offset:384
	v_mul_f32_e32 v0, v37, v77
	v_cvt_pk_bf16_f32 v0, v0, s0
	ds_write_b16 v84, v0 offset:448
	v_mul_f32_e32 v0, v54, v78
	v_cvt_pk_bf16_f32 v0, v0, s0
	ds_write_b16 v84, v0 offset:1024
	v_mul_f32_e32 v0, v38, v78
	v_cvt_pk_bf16_f32 v0, v0, s0
	ds_write_b16 v84, v0 offset:1088
	v_mul_f32_e32 v0, v55, v79
	v_cvt_pk_bf16_f32 v0, v0, s0
	ds_write_b16 v84, v0 offset:1152
	v_mul_f32_e32 v0, v39, v79
	v_cvt_pk_bf16_f32 v0, v0, s0
	ds_write_b16 v84, v0 offset:1216
	v_mul_f32_e32 v0, v56, v80
	v_cvt_pk_bf16_f32 v0, v0, s0
	ds_write_b16 v84, v0 offset:1280
	v_mul_f32_e32 v0, v40, v80
	v_cvt_pk_bf16_f32 v0, v0, s0
	ds_write_b16 v84, v0 offset:1344
	v_mul_f32_e32 v0, v57, v81
	v_cvt_pk_bf16_f32 v0, v0, s0
	ds_write_b16 v84, v0 offset:1408
	v_mul_f32_e32 v0, v41, v81
	v_cvt_pk_bf16_f32 v0, v0, s0
	ds_write_b16 v84, v0 offset:1472
	v_mul_f32_e32 v0, v58, v82
	v_cvt_pk_bf16_f32 v0, v0, s0
	ds_write_b16 v84, v0 offset:2048
	v_mul_f32_e32 v0, v42, v82
	v_cvt_pk_bf16_f32 v0, v0, s0
	v_rcp_f32_e32 v68, v68
	ds_write_b16 v84, v0 offset:2112
	v_mul_f32_e32 v0, v59, v83
	v_cvt_pk_bf16_f32 v0, v0, s0
	ds_write_b16 v84, v0 offset:2176
	v_mul_f32_e32 v0, v43, v83
	v_cvt_pk_bf16_f32 v0, v0, s0
	v_rcp_f32_e32 v69, v69
	ds_write_b16 v84, v0 offset:2240
	v_mul_f32_e32 v0, v60, v68
	v_cvt_pk_bf16_f32 v0, v0, s0
	ds_write_b16 v84, v0 offset:2304
	v_mul_f32_e32 v0, v44, v68
	v_cvt_pk_bf16_f32 v0, v0, s0
	s_waitcnt lgkmcnt(14)
	v_rcp_f32_e32 v70, v70
	ds_write_b16 v84, v0 offset:2368
	v_mul_f32_e32 v0, v61, v69
	v_cvt_pk_bf16_f32 v0, v0, s0
	ds_write_b16 v84, v0 offset:2432
	v_mul_f32_e32 v0, v45, v69
	v_cvt_pk_bf16_f32 v0, v0, s0
	v_rcp_f32_e32 v71, v71
	ds_write_b16 v84, v0 offset:2496
	v_mul_f32_e32 v0, v62, v70
	v_cvt_pk_bf16_f32 v0, v0, s0
	ds_write_b16 v84, v0 offset:3072
	v_mul_f32_e32 v0, v46, v70
	v_cvt_pk_bf16_f32 v0, v0, s0
	v_rcp_f32_e32 v72, v72
	ds_write_b16 v84, v0 offset:3136
	v_mul_f32_e32 v0, v63, v71
	v_cvt_pk_bf16_f32 v0, v0, s0
	ds_write_b16 v84, v0 offset:3200
	v_mul_f32_e32 v0, v47, v71
	v_cvt_pk_bf16_f32 v0, v0, s0
	v_rcp_f32_e32 v73, v73
	ds_write_b16 v84, v0 offset:3264
	v_mul_f32_e32 v0, v64, v72
	v_cvt_pk_bf16_f32 v0, v0, s0
	ds_write_b16 v84, v0 offset:3328
	v_mul_f32_e32 v0, v48, v72
	v_cvt_pk_bf16_f32 v0, v0, s0
	ds_write_b16 v84, v0 offset:3392
	v_mul_f32_e32 v0, v65, v73
	v_cvt_pk_bf16_f32 v0, v0, s0
	ds_write_b16 v84, v0 offset:3456
	v_mul_f32_e32 v0, v49, v73
	v_cvt_pk_bf16_f32 v0, v0, s0
	ds_write_b16 v84, v0 offset:3520
	s_waitcnt lgkmcnt(0)
	ds_read_b128 v[34:37], v86
	ds_read_b128 v[38:41], v86 offset:1024
	v_mul_u32_u24_e32 v0, 0x600, v85
	v_lshlrev_b32_e32 v0, 1, v0
	v_lshl_add_u64 v[42:43], v[66:67], 0, v[0:1]
	s_waitcnt lgkmcnt(1)
	global_store_dwordx4 v[42:43], v[34:37], off sc1
	s_mov_b64 s[0:1], 0x6000
	v_lshl_add_u64 v[44:45], v[42:43], 0, s[0:1]
	v_add_co_u32_e32 v34, vcc, s67, v42
	s_mov_b32 s0, 0x12000
	s_nop 0
	v_addc_co_u32_e32 v35, vcc, 0, v43, vcc
	s_waitcnt lgkmcnt(0)
	global_store_dwordx4 v[34:35], v[38:41], off sc1
	ds_read_b128 v[34:37], v86 offset:2048
	ds_read_b128 v[38:41], v86 offset:3072
	v_add_co_u32_e32 v48, vcc, s97, v42
	v_mul_f32_e32 v0, v18, v74
	s_nop 0
	v_addc_co_u32_e32 v49, vcc, 0, v43, vcc
	s_waitcnt lgkmcnt(1)
; __device__ __forceinline__ int crow(int r,int hi){return (r&3)+8*(r>>2)+4*hi;}
; __device__ __forceinline__ int crow(int r, int hi) { return (r & 3) + 8 * (r >> 2) + 4 * hi; }
;     ...
;     for(int hf=0;hf<2;++hf){
;       #pragma unroll
;       for(int r=0;r<16;++r){const int orow=crow(r,hi);
;         #pragma unroll
;         for(int d0=0;d0<2;++d0)stg[orow*64+d0*32+r32]=__float2bfloat16(o[2*hf+d0][r]*rli[r]);}
;       asm volatile("s_waitcnt lgkmcnt(0)":::"memory");
;       #pragma unroll
;       for(int i=0;i<4;++i){const int row=i*8+(lane>>3),ch=lane&7; const u32x4 v=*(const u32x4*)(stg+row*64+ch*8); ATTN_STORE16(Ow+(long)row*PO+hf*64+ch*8,v);}
;       asm volatile("s_waitcnt lgkmcnt(0)":::"memory"); } }
;   asm volatile("s_waitcnt lgkmcnt(0)\n\ts_barrier":::"memory");
	global_store_dwordx4 v[48:49], v[34:37], off sc1
	v_cvt_pk_bf16_f32 v0, v0, s0
	v_lshl_add_u64 v[46:47], v[42:43], 0, s[42:43]
	v_add_co_u32_e32 v34, vcc, s0, v42
	s_nop 1
	v_addc_co_u32_e32 v35, vcc, 0, v43, vcc
	s_waitcnt lgkmcnt(0)
	global_store_dwordx4 v[34:35], v[38:41], off sc1
	s_waitcnt lgkmcnt(0)
	ds_write_b16 v84, v0
	v_mul_f32_e32 v0, v2, v74
	v_cvt_pk_bf16_f32 v0, v0, s0
	ds_write_b16 v84, v0 offset:64
	v_mul_f32_e32 v0, v19, v75
	v_cvt_pk_bf16_f32 v0, v0, s0
	ds_write_b16 v84, v0 offset:128
	v_mul_f32_e32 v0, v3, v75
	v_cvt_pk_bf16_f32 v0, v0, s0
	ds_write_b16 v84, v0 offset:192
	v_mul_f32_e32 v0, v20, v76
	v_cvt_pk_bf16_f32 v0, v0, s0
	ds_write_b16 v84, v0 offset:256
	v_mul_f32_e32 v0, v4, v76
	v_cvt_pk_bf16_f32 v0, v0, s0
	ds_write_b16 v84, v0 offset:320
	v_mul_f32_e32 v0, v21, v77
	v_cvt_pk_bf16_f32 v0, v0, s0
	ds_write_b16 v84, v0 offset:384
	v_mul_f32_e32 v0, v5, v77
	v_cvt_pk_bf16_f32 v0, v0, s0
	ds_write_b16 v84, v0 offset:448
	v_mul_f32_e32 v0, v22, v78
	v_cvt_pk_bf16_f32 v0, v0, s0
	ds_write_b16 v84, v0 offset:1024
	v_mul_f32_e32 v0, v6, v78
	v_cvt_pk_bf16_f32 v0, v0, s0
	ds_write_b16 v84, v0 offset:1088
	v_mul_f32_e32 v0, v23, v79
	v_cvt_pk_bf16_f32 v0, v0, s0
	ds_write_b16 v84, v0 offset:1152
	v_mul_f32_e32 v0, v7, v79
	v_cvt_pk_bf16_f32 v0, v0, s0
	ds_write_b16 v84, v0 offset:1216
	v_mul_f32_e32 v0, v24, v80
	v_cvt_pk_bf16_f32 v0, v0, s0
	ds_write_b16 v84, v0 offset:1280
	v_mul_f32_e32 v0, v8, v80
	v_cvt_pk_bf16_f32 v0, v0, s0
	ds_write_b16 v84, v0 offset:1344
	v_mul_f32_e32 v0, v25, v81
	v_cvt_pk_bf16_f32 v0, v0, s0
	ds_write_b16 v84, v0 offset:1408
	v_mul_f32_e32 v0, v9, v81
	v_cvt_pk_bf16_f32 v0, v0, s0
	ds_write_b16 v84, v0 offset:1472
	v_mul_f32_e32 v0, v26, v82
	v_cvt_pk_bf16_f32 v0, v0, s0
	ds_write_b16 v84, v0 offset:2048
	v_mul_f32_e32 v0, v10, v82
	v_cvt_pk_bf16_f32 v0, v0, s0
	ds_write_b16 v84, v0 offset:2112
	v_mul_f32_e32 v0, v27, v83
	v_cvt_pk_bf16_f32 v0, v0, s0
	ds_write_b16 v84, v0 offset:2176
	v_mul_f32_e32 v0, v11, v83
	v_cvt_pk_bf16_f32 v0, v0, s0
	ds_write_b16 v84, v0 offset:2240
	v_mul_f32_e32 v0, v28, v68
	v_cvt_pk_bf16_f32 v0, v0, s0
	ds_write_b16 v84, v0 offset:2304
	v_mul_f32_e32 v0, v12, v68
	v_cvt_pk_bf16_f32 v0, v0, s0
	ds_write_b16 v84, v0 offset:2368
	v_mul_f32_e32 v0, v29, v69
	v_cvt_pk_bf16_f32 v0, v0, s0
	ds_write_b16 v84, v0 offset:2432
	v_mul_f32_e32 v0, v13, v69
	v_cvt_pk_bf16_f32 v0, v0, s0
	ds_write_b16 v84, v0 offset:2496
	v_mul_f32_e32 v0, v30, v70
	v_cvt_pk_bf16_f32 v0, v0, s0
	ds_write_b16 v84, v0 offset:3072
	v_mul_f32_e32 v0, v14, v70
	v_cvt_pk_bf16_f32 v0, v0, s0
	ds_write_b16 v84, v0 offset:3136
	v_mul_f32_e32 v0, v31, v71
	v_cvt_pk_bf16_f32 v0, v0, s0
	ds_write_b16 v84, v0 offset:3200
	v_mul_f32_e32 v0, v15, v71
	v_cvt_pk_bf16_f32 v0, v0, s0
	ds_write_b16 v84, v0 offset:3264
	v_mul_f32_e32 v0, v32, v72
	v_cvt_pk_bf16_f32 v0, v0, s0
	ds_write_b16 v84, v0 offset:3328
	v_mul_f32_e32 v0, v16, v72
	v_cvt_pk_bf16_f32 v0, v0, s0
	ds_write_b16 v84, v0 offset:3392
	v_mul_f32_e32 v0, v33, v73
	v_cvt_pk_bf16_f32 v0, v0, s0
	ds_write_b16 v84, v0 offset:3456
	v_mul_f32_e32 v0, v17, v73
	v_cvt_pk_bf16_f32 v0, v0, s0
	ds_write_b16 v84, v0 offset:3520
	s_waitcnt lgkmcnt(0)
	ds_read_b128 v[2:5], v86
	ds_read_b128 v[6:9], v86 offset:1024
	ds_read_b128 v[10:13], v86 offset:2048
	ds_read_b128 v[14:17], v86 offset:3072
	v_lshl_add_u64 v[18:19], v[42:43], 0, s[44:45]
	s_waitcnt lgkmcnt(3)
	global_store_dwordx4 v[42:43], v[2:5], off offset:128 sc1
	s_waitcnt lgkmcnt(2)
	global_store_dwordx4 v[44:45], v[6:9], off offset:128 sc1
	s_waitcnt lgkmcnt(1)
	global_store_dwordx4 v[46:47], v[10:13], off offset:128 sc1
	s_waitcnt lgkmcnt(0)
	global_store_dwordx4 v[18:19], v[14:17], off offset:128 sc1
	s_waitcnt lgkmcnt(0)
	s_waitcnt lgkmcnt(0)
	s_barrier
	s_mov_b64 s[0:1], 0

; #define PG8_BAR __builtin_amdgcn_s_barrier()
; template <class Epi, class Sched, bool ALIGN_EPI = false, bool SP2 = false>
; __device__ __forceinline__ void gemm_phase(PG8_LAS unsigned char* lds, const Gemm g, const Sched& S, const Epi& E, const int wv  ) {
;     ...
;     const int tid = tid_, wid = __builtin_amdgcn_readfirstlane(tid >> 6), lane = tid & 63, wr = wid >> 2, wc = wid & 3, fr = lane & 15, fq = lane >> 4;
;     const int K = g.K, nt = K / BK;
;     unsigned voffA[2], voffB[2];
; #pragma unroll
;     for (int i = 0; i < 2; ++i) { int R, C; stage_rc(tid * 16 + i * 8192, R, C); const int Rb = Epi::PERM ? ((R & ~31) + perm32(R & 31)) : R;
;         voffA[i] = (unsigned)(R * K + C) * 2u; voffB[i] = (unsigned)(Rb * K + C) * 2u; }
;     const size_t kstep = (size_t)(BK * 2);
;     const size_t hstep = (size_t)HALF * K * 2;
;     const size_t tstep = 2 * hstep;
;     const unsigned ldsw = (unsigned)wid * 1024u;
;     const int aoff = lds_byte(wr * 64 + fr, fq * 8), boff = lds_byte(wc * 32 + fr, fq * 8);
;     ...
;     Unit cur, nxt; int ui = 0;
;     if (!S.next(0, cur)) return;
;     f32x4 acc[2][2][4][2];
; #pragma unroll
;     for (int a = 0; a < 2; ++a)
; #pragma unroll
;         for (int b = 0; b < 2; ++b)
; #pragma unroll
;             for (int m = 0; m < 4; ++m)
; #pragma unroll
;                 for (int n = 0; n < 2; ++n) acc[a][b][m][n] = (f32x4){0.f, 0.f, 0.f, 0.f};
;     bf16x8 At[4][2], B0[2][2], B1[2][2];
;     const char* cA = (const char*)g.A + (size_t)cur.pm * tstep; const char* cB = (const char*)g.Bt + (size_t)cur.pn * tstep;
;     S.a_ready(cur);
;     if constexpr (SP2) {
;         PG8_STAGE(PG8_SB(0, 0), cB, voffB); PG8_STAGE(PG8_SB(0, 1), cB + hstep, voffB); PG8_STAGE(PG8_SA(0, 0), cA, voffA); PG8_STAGE(PG8_SA(0, 1), cA + hstep, voffA);
;         if (wr == 1) PG8_BAR;
;         PG8_WAIT_V(2); PG8_BAR;
;         PG8_STAGE(PG8_SB(1, 0), cB + kstep, voffB); PG8_STAGE(PG8_SA(1, 0), cA + kstep, voffA); PG8_STAGE(PG8_SB(1, 1), cB + hstep + kstep, voffB);
;         PG8_WAIT_V(6); PG8_BAR;
; __global__ void __launch_bounds__(NWAVES * 64, 2) mk_fwd(Params P) {
;     ...
;         LANE_TID;
;         if (bx < 64) {
;         { pg8::Gemm g{MEMN, Wckv_t, MM, D, D}; pg8::StaticOrder S; S.init(MM, D, G, bx);
;           pg8::EpiBf16<0> E{CKb, D, nullptr, 0, 0, 1.f};
;           pg8::gemm_phase<pg8::EpiBf16<0>, pg8::StaticOrder, true, true>(lds, g, S, E, wave); }
.LBB0_799:
	s_cmp_lt_i32 s74, 4
	s_cselect_b64 s[2:3], -1, 0
	s_and_b64 s[6:7], s[2:3], s[0:1]
	s_andn2_b64 vcc, exec, s[6:7]
	s_cbranch_vccnz .LBB0_848
	s_cmp_lt_i32 s88, 64
	s_cselect_b64 s[0:1], -1, 0
	s_cmp_gt_i32 s88, 63
	v_mov_b32_e32 v128, v212
	s_cbranch_scc1 .LBB0_845
	s_add_u32 s2, s72, 0x1b800000
	s_addc_u32 s3, s73, 0
	s_and_b32 s21, s93, 0xffffffc0
	v_mov_b32_e32 v8, v212
	s_ashr_i32 s20, s82, 31
	s_cmp_gt_i32 s88, 31
	v_add_u32_e32 v0, s21, v8
	s_nop 0
	v_readfirstlane_b32 s15, v0
	s_cbranch_scc1 .LBB0_821
	s_waitcnt lgkmcnt(0)
	v_lshlrev_b32_e32 v1, 4, v0
	v_add_u32_e32 v2, 0x2000, v1
	v_ashrrev_i32_e32 v3, 31, v2
	v_lshrrev_b32_e32 v3, 22, v3
	v_add_u32_e32 v3, v2, v3
	v_ashrrev_i32_e32 v9, 10, v3
	v_mul_i32_i24_e32 v3, 0x400, v9
	v_sub_u32_e32 v2, v2, v3
	v_lshrrev_b32_e32 v3, 4, v2
	v_bitop3_b32 v2, v3, v2, 32 bitop3:0x6c
	v_ashrrev_i32_e32 v3, 31, v2
	v_lshrrev_b32_e32 v3, 26, v3
	s_ashr_i32 s10, s15, 6
	v_add_u32_e32 v3, v2, v3
	v_lshlrev_b32_e32 v4, 3, v9
	s_ashr_i32 s16, s15, 8
	s_lshl_b32 s33, s10, 10
	v_ashrrev_i32_e32 v10, 6, v3
	v_and_b32_e32 v4, -16, v4
	s_add_u32 s36, s72, 0x1a200000
	v_add_u32_e32 v4, v10, v4
	s_addc_u32 s37, s73, 0
	s_ashr_i32 s38, s88, 31
	v_and_b32_e32 v5, 3, v10
	s_mov_b32 s9, 0x1fffe0
	v_lshrrev_b32_e32 v6, 2, v4
	v_lshlrev_b32_e32 v7, 1, v4
	v_and_b32_e32 v3, 0xc0, v3
	s_lshr_b32 s4, s38, 29
	v_and_or_b32 v5, v4, s9, v5
	v_and_b32_e32 v6, 4, v6
	v_and_b32_e32 v7, 24, v7
	v_sub_u32_e32 v2, v2, v3
	v_mov_b32_e32 v3, 1
	s_add_i32 s4, s88, s4
	v_or3_b32 v5, v5, v6, v7
	v_lshlrev_b32_e32 v6, 5, v9
	v_ashrrev_i16_sdwa v2, v3, sext(v2) dst_sel:DWORD dst_unused:UNUSED_PAD src0_sel:DWORD src1_sel:BYTE_0
	s_ashr_i32 s5, s4, 3
	s_and_b32 s4, s4, -8
	v_and_b32_e32 v6, 32, v6
	v_bfe_i32 v11, v2, 0, 16
	s_sub_i32 s4, s88, s4
	v_add_lshl_u32 v2, v6, v11, 1
	s_lshl_b32 s8, s4, 2
	v_lshl_add_u32 v130, v5, 11, v2
	v_lshl_add_u32 v132, v4, 11, v2
	v_bfe_i32 v2, v0, 27, 1
	s_cmp_lt_i32 s4, 0
	s_mul_i32 s4, s4, 5
	v_lshrrev_b32_e32 v2, 22, v2
	v_add_u32_e32 v2, v1, v2
	s_cselect_b32 s4, s4, s8
	v_and_b32_e32 v2, 0xfffffc00, v2
	s_add_i32 s4, s4, s5
	v_sub_u32_e32 v1, v1, v2
	s_ashr_i32 s5, s4, 31
	v_lshrrev_b32_e32 v2, 4, v1
	v_ashrrev_i32_e32 v4, 31, v0
	s_lshr_b32 s5, s5, 27
	v_bitop3_b32 v1, v2, v1, 32 bitop3:0x6c
	v_lshrrev_b32_e32 v4, 26, v4
	s_add_i32 s5, s4, s5
	v_ashrrev_i32_e32 v2, 31, v1
	v_add_u32_e32 v0, v0, v4
	s_ashr_i32 s8, s5, 5
	s_andn2_b32 s5, s5, 31
	v_lshrrev_b32_e32 v2, 26, v2
	v_ashrrev_i32_e32 v13, 6, v0
	s_sub_i32 s4, s4, s5
	v_add_u32_e32 v2, v1, v2
	v_lshlrev_b32_e32 v0, 3, v13
	s_bfe_i32 s5, s4, 0x80000
	v_ashrrev_i32_e32 v12, 6, v2
	v_and_b32_e32 v0, -16, v0
	s_bfe_u32 s5, s5, 0x3000c
	v_add_u32_e32 v0, v12, v0
	v_and_b32_e32 v4, 3, v12
	s_add_i32 s5, s4, s5
	v_and_or_b32 v4, v0, s9, v4
	s_bfe_i32 s9, s5, 0x80000
	s_and_b32 s5, s5, 0xf8
	s_sub_i32 s4, s4, s5
	s_lshl_b32 s8, s8, 3
	s_sext_i32_i16 s9, s9
	s_sext_i32_i8 s4, s4
	v_lshrrev_b32_e32 v5, 2, v0
	v_lshlrev_b32_e32 v6, 1, v0
	v_and_b32_e32 v2, 0xc0, v2
	s_lshr_b32 s14, s9, 3
	s_lshr_b32 s14, s88, 3
	s_add_i32 s42, s8, s4
	s_and_b32 s42, s88, 7
	v_and_b32_e32 v5, 4, v5
	v_and_b32_e32 v6, 24, v6
	v_sub_u32_e32 v1, v1, v2
	s_ashr_i32 s43, s42, 31
	s_bfe_i64 s[8:9], s[14:15], 0x100000
	v_or3_b32 v4, v4, v5, v6
	v_lshlrev_b32_e32 v5, 5, v13
	v_ashrrev_i16_sdwa v1, v3, sext(v1) dst_sel:DWORD dst_unused:UNUSED_PAD src0_sel:DWORD src1_sel:BYTE_0
	s_lshl_b64 s[4:5], s[42:43], 19
	s_lshl_b64 s[8:9], s[8:9], 19
	v_and_b32_e32 v5, 32, v5
	v_bfe_i32 v14, v1, 0, 16
	s_add_u32 s46, s36, s8
	v_add_lshl_u32 v1, v5, v14, 1
	s_addc_u32 s47, s37, s9
	s_add_i32 s39, s33, 0
	v_lshl_add_u32 v134, v4, 11, v1
	s_add_i32 m0, s39, 0x10000
	v_lshl_add_u32 v136, v0, 11, v1
	global_load_lds_dwordx4 v134, s[46:47]
	s_add_i32 m0, s39, 0x12000
	s_add_u32 s8, s46, 0x40000
	global_load_lds_dwordx4 v130, s[46:47]
	s_addc_u32 s9, s47, 0
	s_add_i32 m0, s39, 0x14000
	v_mov_b32_e32 v135, 0
	global_load_lds_dwordx4 v134, s[8:9]
	s_add_i32 m0, s39, 0x16000
	s_add_u32 s44, s2, s4
	s_addc_u32 s45, s3, s5
	s_add_i32 s40, s39, 0x2000
	global_load_lds_dwordx4 v130, s[8:9]
	s_mov_b32 m0, s39
	s_add_u32 s4, s44, 0x40000
	global_load_lds_dwordx4 v136, s[44:45]
	s_mov_b32 m0, s40
	s_addc_u32 s5, s45, 0
	s_add_i32 s41, s39, 0x4000
	global_load_lds_dwordx4 v132, s[44:45]
	s_mov_b32 m0, s41
	s_add_i32 s43, s39, 0x6000
	global_load_lds_dwordx4 v136, s[4:5]
	s_mov_b32 m0, s43
	v_mov_b32_e32 v131, v135
	global_load_lds_dwordx4 v132, s[4:5]
	v_mov_b32_e32 v137, v135
	v_mov_b32_e32 v133, v135
	s_cmp_eq_u32 s16, 1
	s_mov_b32 s50, 0
	v_lshl_add_u64 v[6:7], s[46:47], 0, v[134:135]
	v_lshl_add_u64 v[2:3], s[46:47], 0, v[130:131]
	s_mov_b64 s[4:5], 0x40000
	v_lshl_add_u64 v[0:1], s[44:45], 0, v[136:137]
	s_cselect_b64 s[8:9], -1, 0
	s_cmp_lg_u32 s16, 1
	v_lshl_add_u64 v[4:5], s[44:45], 0, v[132:133]
	s_cbranch_scc1 .LBB0_804
	s_barrier

; #define LAS __attribute__((address_space(3)))
; __device__ __forceinline__ unsigned xb_ld(unsigned* p)              { return __hip_atomic_load(p, __ATOMIC_RELAXED, __HIP_MEMORY_SCOPE_AGENT); }
; __device__ __forceinline__ unsigned xb_add(unsigned* p, unsigned v) { return __hip_atomic_fetch_add(p, v, __ATOMIC_RELAXED, __HIP_MEMORY_SCOPE_AGENT); }
; #define XB_SPIN(cond, bar) do { unsigned _sp = 0; while (cond) { __builtin_amdgcn_s_sleep(1); \
;     if ((++_sp & 255u) == 0u) { if (xb_ld(&(bar)[XB_TMO])) break; if (_sp > XB_SPIN_CAP) { atomicAdd(&(bar)[XB_TMO], 1u); break; } } } } while (0)
; __device__ __forceinline__ void xcd_barrier(const XcdBarrier& b, bool leader) {
;     asm volatile("s_waitcnt vmcnt(0)" ::: "memory");
;     __syncthreads();
;     if (leader) {
;         unsigned* bar = b.bar;
;         __builtin_amdgcn_s_waitcnt(0);
;         unsigned nloc = b.st[0], nx = b.st[1];
;         if (nloc == 0u) { xcd_barrier_complete(bar, b.x, nloc, nx); b.st[0] = nloc; b.st[1] = nx; }
;         const unsigned old = xb_add(&bar[XB_XSUB(b.x)], 1u);
;         const unsigned gen = old / nloc;
;         if (old + 1u == (gen + 1u) * nloc) {
;             __builtin_amdgcn_fence(__ATOMIC_RELEASE, "agent");
;             asm volatile("s_waitcnt vmcnt(0)" ::: "memory");
;             const unsigned og = xb_add(&bar[XB_TOP], 1u);
;             const unsigned tg = og / nx;
;             if (og + 1u == (tg + 1u) * nx) xb_add(&bar[XB_TOPGEN], 1u);
;             else XB_SPIN(xb_ld(&bar[XB_TOPGEN]) == tg, bar);
;             __builtin_amdgcn_fence(__ATOMIC_ACQUIRE, "agent");
;             xb_add(&bar[XB_XGEN(b.x)], 1u);
;             asm volatile("s_waitcnt vmcnt(0)" ::: "memory");
;         } else {
;             XB_SPIN(xb_ld(&bar[XB_XGEN(b.x)]) == gen, bar);
;             __builtin_amdgcn_fence(__ATOMIC_ACQUIRE, "agent");
;             asm volatile("s_waitcnt vmcnt(0)" ::: "memory");
;         }
;     }
;     __syncthreads();
; }
; __global__ void __launch_bounds__(NWAVES * 64, 2) mk_fwd(Params P) {
;     ...
;         pg8::EpiRowScale<0> E{CQ, D, SS1, EPS, pg8::CROSS_C2, (const LAS int*)(lds + RING_BYTES + 1536), (const LAS float*)(lds + RING_BYTES + 2048)};
;         pg8::gemm_phase<pg8::EpiRowScale<0>, pg8::StaticOrder, true, true>(lds, g, S, E, wave); }
;     SEAM(5);
.LBB0_1089:
	s_cmp_gt_i32 s75, 6
	s_cselect_b64 s[0:1], -1, 0
	s_and_b64 s[2:3], s[36:37], s[0:1]
	s_andn2_b64 vcc, exec, s[2:3]
	s_cbranch_vccnz .LBB0_1141
	v_readlane_b32 s2, v254, 4
	v_readlane_b32 s3, v254, 5
	s_and_b64 vcc, exec, s[2:3]
	s_mov_b64 s[6:7], 0
	s_cbranch_vccnz .LBB0_1092
	v_mov_b32_e32 v0, v212
	s_nop 0
	v_cmp_eq_u32_e32 vcc, 0, v0
	s_and_b64 s[6:7], vcc, exec
.LBB0_1092:
	s_waitcnt vmcnt(0)
	s_waitcnt vmcnt(0) lgkmcnt(0)
	s_barrier
	s_and_saveexec_b64 s[4:5], s[6:7]
	s_cbranch_execz .LBB0_1140
	v_readlane_b32 s8, v254, 2
	v_readlane_b32 s9, v254, 3
	s_and_b32 s2, s88, 7
	s_lshl_b32 s2, s2, 8
	s_add_u32 s2, s8, s2
	s_addc_u32 s3, s9, 0
	v_mov_b32_e32 v0, 0
	v_mov_b32_e32 v1, 1
	v_mov_b32_e32 v5, 0x1400
	global_load_dwordx4 v[6:9], v0, s[8:9] offset:768 sc1
	global_load_dwordx4 v[10:13], v0, s[8:9] offset:784 sc1
	global_atomic_add v3, v5, v1, s[2:3] offset:128 sc0
	s_waitcnt vmcnt(0)
	v_add_u32_e32 v14, -1, v6
	v_and_b32_e32 v2, v14, v6
	v_add_u32_e32 v14, -1, v7
	v_and_or_b32 v2, v14, v7, v2
	v_add_u32_e32 v14, -1, v8
	v_and_or_b32 v2, v14, v8, v2
	v_add_u32_e32 v14, -1, v9
	v_and_or_b32 v2, v14, v9, v2
	v_add_u32_e32 v14, -1, v10
	v_and_or_b32 v2, v14, v10, v2
	v_add_u32_e32 v14, -1, v11
	v_and_or_b32 v2, v14, v11, v2
	v_add_u32_e32 v14, -1, v12
	v_and_or_b32 v2, v14, v12, v2
	v_add_u32_e32 v14, -1, v13
	v_and_or_b32 v2, v14, v13, v2
	v_cmp_ne_u32_e32 vcc, 0, v2
	s_cbranch_vccnz .Lmy_glob_k5
	v_and_b32_e32 v4, 0xffffffe0, v3
	v_add_u32_e32 v4, 32, v4
	v_add_u32_e32 v3, 1, v3
	v_cmp_eq_u32_e32 vcc, v3, v4
	s_cbranch_vccnz .Lmy_done_k5
	s_mov_b32 s10, 0

; #define LAS __attribute__((address_space(3)))
; __device__ __forceinline__ unsigned xb_ld(unsigned* p)              { return __hip_atomic_load(p, __ATOMIC_RELAXED, __HIP_MEMORY_SCOPE_AGENT); }
; __device__ __forceinline__ unsigned xb_add(unsigned* p, unsigned v) { return __hip_atomic_fetch_add(p, v, __ATOMIC_RELAXED, __HIP_MEMORY_SCOPE_AGENT); }
; #define XB_SPIN(cond, bar) do { unsigned _sp = 0; while (cond) { __builtin_amdgcn_s_sleep(1); \
;     if ((++_sp & 255u) == 0u) { if (xb_ld(&(bar)[XB_TMO])) break; if (_sp > XB_SPIN_CAP) { atomicAdd(&(bar)[XB_TMO], 1u); break; } } } } while (0)
; __device__ __forceinline__ void xcd_barrier(const XcdBarrier& b, bool leader) {
;     asm volatile("s_waitcnt vmcnt(0)" ::: "memory");
;     __syncthreads();
;     if (leader) {
;         unsigned* bar = b.bar;
;         __builtin_amdgcn_s_waitcnt(0);
;         unsigned nloc = b.st[0], nx = b.st[1];
;         if (nloc == 0u) { xcd_barrier_complete(bar, b.x, nloc, nx); b.st[0] = nloc; b.st[1] = nx; }
;         const unsigned old = xb_add(&bar[XB_XSUB(b.x)], 1u);
;         const unsigned gen = old / nloc;
;         if (old + 1u == (gen + 1u) * nloc) {
;             __builtin_amdgcn_fence(__ATOMIC_RELEASE, "agent");
;             asm volatile("s_waitcnt vmcnt(0)" ::: "memory");
;             const unsigned og = xb_add(&bar[XB_TOP], 1u);
;             const unsigned tg = og / nx;
;             if (og + 1u == (tg + 1u) * nx) xb_add(&bar[XB_TOPGEN], 1u);
;             else XB_SPIN(xb_ld(&bar[XB_TOPGEN]) == tg, bar);
;             __builtin_amdgcn_fence(__ATOMIC_ACQUIRE, "agent");
;             xb_add(&bar[XB_XGEN(b.x)], 1u);
;             asm volatile("s_waitcnt vmcnt(0)" ::: "memory");
;         } else {
;             XB_SPIN(xb_ld(&bar[XB_XGEN(b.x)]) == gen, bar);
;             __builtin_amdgcn_fence(__ATOMIC_ACQUIRE, "agent");
;             asm volatile("s_waitcnt vmcnt(0)" ::: "memory");
;         }
;     }
;     __syncthreads();
; }
; __global__ void __launch_bounds__(NWAVES * 64, 2) mk_fwd(Params P) {
;     ...
;         pg8::EpiRowScale<0> E{CQ, D, SS1, EPS, pg8::CROSS_C2, (const LAS int*)(lds + RING_BYTES + 1536), (const LAS float*)(lds + RING_BYTES + 2048)};
;         pg8::gemm_phase<pg8::EpiRowScale<0>, pg8::StaticOrder, true, true>(lds, g, S, E, wave); }
;     SEAM(5);
.Lmy_done_k5:
	s_and_b32 s11, s88, 7
	s_mul_i32 s11, s11, 11
	s_lshr_b32 s11, s11, 5
	s_lshl_b32 s11, s11, 8
	s_add_u32 s12, s8, s11
	s_addc_u32 s13, s9, 0
	s_mov_b32 s10, 0
.Lmy_xw_k5:
	global_load_dword v2, v5, s[12:13] offset:128 sc1
	s_waitcnt vmcnt(0)
	v_cmp_gt_u32_e32 vcc, 64, v2
	s_cbranch_vccz .Lmy_xok_k5
	s_sleep 1
	s_add_i32 s10, s10, 1
	s_cmp_lt_u32 s10, 0x100000
	s_cbranch_scc1 .Lmy_xw_k5

; __device__ __forceinline__ int crow(int r,int hi){return (r&3)+8*(r>>2)+4*hi;}
; #define XLAS __attribute__((address_space(3)))
; __device__ __forceinline__ int crow(int r, int hi) { return (r & 3) + 8 * (r >> 2) + 4 * hi; }
; #define X_LOADV(c)  do { _Pragma("unroll") for (int i_ = 0; i_ < 4; ++i_) st[i_] = *(const u32x4*)(Vg + (size_t)(c) * 64 * 2048 + i_ * 64); } while (0)
; __device__ __forceinline__ void unit(int b, int h, int qblk, const bf16_t* __restrict__ CQ, const bf16_t* __restrict__ CK, const bf16_t* __restrict__ CVT, bf16_t* __restrict__ CO, XLAS unsigned char* lds, const int wv) {
;     ...
;     XLAS float* wsf = (XLAS float*)(lds + X_WSF) + wid * 64;
;     if (hi == 0) wsf[r32] = l;
;     asm volatile("s_waitcnt lgkmcnt(0)" ::: "memory");
;     float rli[16];
; #pragma unroll
;     for (int r = 0; r < 16; ++r) rli[r] = __builtin_amdgcn_rcpf(wsf[crow(r, hi)]);
;     XLAS bf16_t* stg = (XLAS bf16_t*)(lds + X_OST) + wid * 2048;
;     bf16_t* Ow = CO + qrow0 * 1024 + h * 256;
; #pragma unroll
;     for (int c = 0; c < 4; ++c) {
;         const int buf = (c & 1) ? XB1 : XB0, nbuf = (c & 1) ? XB0 : XB1;
;         if (c < 3) X_LOADV(c + 1);
;         f32x16 o[2]; o[0] = f32x16{}; o[1] = f32x16{};
; #pragma unroll
;         for (int j = 0; j < 16; ++j)
; #pragma unroll
;             for (int dt = 0; dt < 2; ++dt) {
;                 const bf16x8 vf = *(const XLAS bf16x8*)(lds + buf + voff + dt * 512 + j * 2048);
;                 o[dt] = __builtin_amdgcn_mfma_f32_32x32x16_bf16(__builtin_bit_cast(bf16x8, pw[j]), vf, o[dt], 0, 0, 0);
;             }
.LBB0_1144:
	s_or_b64 exec, exec, s[14:15]
	s_mov_b32 s30, s23
	s_mov_b32 s31, 0
	v_lshl_add_u64 v[242:243], v[144:145], 0, s[30:31]
	global_load_dwordx4 v[226:229], v[242:243], off
	global_load_dwordx4 v[230:233], v[242:243], off offset:128
	global_load_dwordx4 v[234:237], v[242:243], off offset:256
	global_load_dwordx4 v[238:241], v[242:243], off offset:384
	v_lshlrev_b32_e32 v0, 4, v191
	s_waitcnt lgkmcnt(0)
	v_lshlrev_b32_e32 v1, 10, v192
	s_waitcnt lgkmcnt(0)
	v_add3_u32 v104, 0, v1, v0
	ds_read_b128 v[0:3], v104
	ds_read_b128 v[4:7], v104 offset:512
	ds_read_b128 v[96:99], v104 offset:2048
	ds_read_b128 v[100:103], v104 offset:2560
	s_waitcnt lgkmcnt(3)
	v_mfma_f32_32x32x16_bf16 v[16:31], v[92:95], v[0:3], 0
	v_lshl_add_u32 v105, v192, 4, s17
	s_add_i32 s4, s4, 0x10800
	s_lshl_b64 s[12:13], s[12:13], 11
	s_add_u32 s12, s18, s12
	s_addc_u32 s13, s19, s13
	s_lshl_b32 s14, s16, 1
	s_add_u32 s12, s12, s14
	s_waitcnt lgkmcnt(2)
	v_mfma_f32_32x32x16_bf16 v[0:15], v[92:95], v[4:7], 0
	s_addc_u32 s13, s13, 0
	s_add_i32 s2, s2, 1
	s_addk_i32 s21, 0x100
	s_cmp_lt_i32 s2, s3
	s_waitcnt lgkmcnt(1)
	v_mfma_f32_32x32x16_bf16 v[16:31], v[88:91], v[96:99], v[16:31]
	s_waitcnt lgkmcnt(0)
	v_mfma_f32_32x32x16_bf16 v[0:15], v[88:91], v[100:103], v[0:15]
	ds_read_b128 v[96:99], v104 offset:4096
	ds_read_b128 v[100:103], v104 offset:4608
	s_waitcnt lgkmcnt(1)
	v_mfma_f32_32x32x16_bf16 v[16:31], v[84:87], v[96:99], v[16:31]
	s_waitcnt lgkmcnt(0)
	v_mfma_f32_32x32x16_bf16 v[0:15], v[84:87], v[100:103], v[0:15]
	ds_read_b128 v[96:99], v104 offset:6144
	ds_read_b128 v[100:103], v104 offset:6656
	s_waitcnt lgkmcnt(1)
	v_mfma_f32_32x32x16_bf16 v[16:31], v[80:83], v[96:99], v[16:31]
	s_waitcnt lgkmcnt(0)
	v_mfma_f32_32x32x16_bf16 v[0:15], v[80:83], v[100:103], v[0:15]
	ds_read_b128 v[96:99], v104 offset:8192
	ds_read_b128 v[100:103], v104 offset:8704
	s_waitcnt lgkmcnt(1)
	v_mfma_f32_32x32x16_bf16 v[16:31], v[76:79], v[96:99], v[16:31]
	s_waitcnt lgkmcnt(0)
	v_mfma_f32_32x32x16_bf16 v[0:15], v[76:79], v[100:103], v[0:15]
	ds_read_b128 v[96:99], v104 offset:10240
	ds_read_b128 v[100:103], v104 offset:10752
	s_waitcnt lgkmcnt(1)
	v_mfma_f32_32x32x16_bf16 v[16:31], v[72:75], v[96:99], v[16:31]
	s_waitcnt lgkmcnt(0)
	v_mfma_f32_32x32x16_bf16 v[0:15], v[72:75], v[100:103], v[0:15]
	ds_read_b128 v[96:99], v104 offset:12288
	ds_read_b128 v[100:103], v104 offset:12800
	s_waitcnt lgkmcnt(1)
	v_mfma_f32_32x32x16_bf16 v[16:31], v[68:71], v[96:99], v[16:31]
	s_waitcnt lgkmcnt(0)
	v_mfma_f32_32x32x16_bf16 v[0:15], v[68:71], v[100:103], v[0:15]
	ds_read_b128 v[96:99], v104 offset:14336
	ds_read_b128 v[100:103], v104 offset:14848
	s_waitcnt lgkmcnt(1)
	v_mfma_f32_32x32x16_bf16 v[16:31], v[64:67], v[96:99], v[16:31]
	s_waitcnt lgkmcnt(0)
	v_mfma_f32_32x32x16_bf16 v[0:15], v[64:67], v[100:103], v[0:15]
	ds_read_b128 v[96:99], v104 offset:16384
	ds_read_b128 v[100:103], v104 offset:16896
	s_waitcnt lgkmcnt(1)
	v_mfma_f32_32x32x16_bf16 v[16:31], v[60:63], v[96:99], v[16:31]
	s_waitcnt lgkmcnt(0)
	v_mfma_f32_32x32x16_bf16 v[0:15], v[60:63], v[100:103], v[0:15]
	ds_read_b128 v[96:99], v104 offset:18432
	ds_read_b128 v[100:103], v104 offset:18944
	s_waitcnt lgkmcnt(1)
	v_mfma_f32_32x32x16_bf16 v[16:31], v[56:59], v[96:99], v[16:31]
	s_waitcnt lgkmcnt(0)
	v_mfma_f32_32x32x16_bf16 v[0:15], v[56:59], v[100:103], v[0:15]
	ds_read_b128 v[96:99], v104 offset:20480
	ds_read_b128 v[100:103], v104 offset:20992
	s_waitcnt lgkmcnt(1)
	v_mfma_f32_32x32x16_bf16 v[16:31], v[52:55], v[96:99], v[16:31]
	s_waitcnt lgkmcnt(0)
	v_mfma_f32_32x32x16_bf16 v[0:15], v[52:55], v[100:103], v[0:15]
	ds_read_b128 v[96:99], v104 offset:22528
	ds_read_b128 v[100:103], v104 offset:23040
	s_waitcnt lgkmcnt(1)
	v_mfma_f32_32x32x16_bf16 v[16:31], v[48:51], v[96:99], v[16:31]
	ds_read_b128 v[96:99], v104 offset:24576
	s_waitcnt lgkmcnt(1)
	v_mfma_f32_32x32x16_bf16 v[0:15], v[48:51], v[100:103], v[0:15]
	ds_read_b128 v[100:103], v104 offset:25088
	s_waitcnt lgkmcnt(1)
	v_mfma_f32_32x32x16_bf16 v[16:31], v[44:47], v[96:99], v[16:31]
	ds_read_b128 v[96:99], v105
	ds_read_b128 v[106:109], v105 offset:32
	ds_read_b128 v[122:125], v104 offset:27136
	s_waitcnt lgkmcnt(2)
	v_rcp_f32_e32 v121, v96
	v_rcp_f32_e32 v120, v97
	v_rcp_f32_e32 v119, v98
	v_mfma_f32_32x32x16_bf16 v[0:15], v[44:47], v[100:103], v[0:15]
	v_rcp_f32_e32 v118, v99
	ds_read_b128 v[96:99], v104 offset:26624
	ds_read_b128 v[100:103], v105 offset:64
	s_waitcnt lgkmcnt(3)
	v_rcp_f32_e32 v117, v106
	v_rcp_f32_e32 v116, v107
	v_rcp_f32_e32 v115, v108
	v_rcp_f32_e32 v113, v109
	s_waitcnt lgkmcnt(1)
	v_mfma_f32_32x32x16_bf16 v[16:31], v[40:43], v[96:99], v[16:31]
	ds_read_b128 v[96:99], v105 offset:96
	s_waitcnt lgkmcnt(1)
	v_rcp_f32_e32 v114, v100
	v_rcp_f32_e32 v112, v101
	v_rcp_f32_e32 v111, v102
	v_rcp_f32_e32 v110, v103
	s_waitcnt lgkmcnt(0)
	v_rcp_f32_e32 v108, v96
	v_rcp_f32_e32 v107, v97
	v_mfma_f32_32x32x16_bf16 v[0:15], v[40:43], v[122:125], v[0:15]
	v_rcp_f32_e32 v106, v98
	v_rcp_f32_e32 v105, v99
	ds_read_b128 v[96:99], v104 offset:28672
	ds_read_b128 v[100:103], v104 offset:29184
	v_lshrrev_b32_e32 v125, 3, v190
	s_waitcnt lgkmcnt(1)
	v_mfma_f32_32x32x16_bf16 v[16:31], v[36:39], v[96:99], v[16:31]
	v_lshlrev_b32_e32 v96, 9, v192
	v_lshlrev_b32_e32 v97, 1, v191
	v_add3_u32 v109, s4, v96, v97
	ds_read_b128 v[96:99], v104 offset:30720
	s_waitcnt lgkmcnt(1)
	v_mfma_f32_32x32x16_bf16 v[0:15], v[36:39], v[100:103], v[0:15]
	v_lshlrev_b32_e32 v100, 4, v189
	v_and_b32_e32 v176, 0x70, v100
	ds_read_b128 v[100:103], v104 offset:31232
	v_add_u32_e32 v147, s4, v176
	v_lshl_add_u32 v122, v125, 7, v147
	v_lshl_add_u64 v[142:143], s[12:13], 0, v[176:177]
	v_lshlrev_b32_e32 v176, 11, v125
	s_waitcnt lgkmcnt(1)
; __device__ __forceinline__ int crow(int r,int hi){return (r&3)+8*(r>>2)+4*hi;}
; #define XLAS __attribute__((address_space(3)))
; __device__ __forceinline__ int crow(int r, int hi) { return (r & 3) + 8 * (r >> 2) + 4 * hi; }
; __device__ __forceinline__ unsigned pk(float lo, float hi) { return pg8::cvt_pk_bf16(lo, hi); }
; #define X_STOREV(buf) do { _Pragma("unroll") for (int i_ = 0; i_ < 4; ++i_) *(XLAS u32x4*)(lds + (buf) + (wid + 8 * i_) * 1024 + lane * 16) = st[i_]; } while (0)
; __device__ __forceinline__ void unit(int b, int h, int qblk, const bf16_t* __restrict__ CQ, const bf16_t* __restrict__ CK, const bf16_t* __restrict__ CVT, bf16_t* __restrict__ CO, XLAS unsigned char* lds, const int wv) {
;     ...
; #pragma unroll
;         for (int r = 0; r < 16; ++r) { const int orow = crow(r, hi);
; #pragma unroll
;             for (int dt = 0; dt < 2; ++dt) { const unsigned w = pk(o[dt][r] * rli[r], 0.f); stg[orow * 64 + dt * 32 + r32] = (bf16_t)(w & 0xffffu); } }
;         asm volatile("s_waitcnt lgkmcnt(0)" ::: "memory");
; #pragma unroll
;         for (int i = 0; i < 4; ++i) { const int row = i * 8 + (lane >> 3), ch = lane & 7; const u32x4 v = *(const XLAS u32x4*)(stg + row * 64 + ch * 8); *(u32x4*)(Ow + (size_t)row * 1024 + c * 64 + ch * 8) = v; }
;         asm volatile("s_waitcnt lgkmcnt(0)" ::: "memory");
;         if (c < 3) X_STOREV(nbuf);
;         __syncthreads();
	v_mfma_f32_32x32x16_bf16 v[16:31], v[32:35], v[96:99], v[16:31]
	v_add_co_u32_e32 v96, vcc, s23, v144
	s_nop 1
	v_addc_co_u32_e32 v97, vcc, 0, v145, vcc
	v_lshl_add_u64 v[96:97], v[142:143], 0, v[176:177]
	s_waitcnt lgkmcnt(0)
	v_mfma_f32_32x32x16_bf16 v[0:15], v[32:35], v[100:103], v[0:15]
	s_nop 0
	v_mul_f32_e32 v16, v121, v16
	v_cvt_pk_bf16_f32 v16, v16, v177
	ds_write_b16 v109, v16
	s_nop 8
	v_mul_f32_e32 v0, v121, v0
	v_cvt_pk_bf16_f32 v0, v0, v177
	ds_write_b16 v109, v0 offset:64
	v_mul_f32_e32 v0, v120, v17
	v_cvt_pk_bf16_f32 v0, v0, v177
	ds_write_b16 v109, v0 offset:128
	v_mul_f32_e32 v0, v120, v1
	v_cvt_pk_bf16_f32 v0, v0, v177
	ds_write_b16 v109, v0 offset:192
	v_mul_f32_e32 v0, v119, v18
	v_cvt_pk_bf16_f32 v0, v0, v177
	ds_write_b16 v109, v0 offset:256
	v_mul_f32_e32 v0, v119, v2
	v_cvt_pk_bf16_f32 v0, v0, v177
	ds_write_b16 v109, v0 offset:320
	v_mul_f32_e32 v0, v118, v19
	v_cvt_pk_bf16_f32 v0, v0, v177
	ds_write_b16 v109, v0 offset:384
	v_mul_f32_e32 v0, v118, v3
	v_cvt_pk_bf16_f32 v0, v0, v177
	ds_write_b16 v109, v0 offset:448
	v_mul_f32_e32 v0, v117, v20
	v_cvt_pk_bf16_f32 v0, v0, v177
	ds_write_b16 v109, v0 offset:1024
	v_mul_f32_e32 v0, v117, v4
	v_cvt_pk_bf16_f32 v0, v0, v177
	ds_write_b16 v109, v0 offset:1088
	v_mul_f32_e32 v0, v116, v21
	v_cvt_pk_bf16_f32 v0, v0, v177
	ds_write_b16 v109, v0 offset:1152
	v_mul_f32_e32 v0, v116, v5
	v_cvt_pk_bf16_f32 v0, v0, v177
	ds_write_b16 v109, v0 offset:1216
	v_mul_f32_e32 v0, v115, v22
	v_cvt_pk_bf16_f32 v0, v0, v177
	ds_write_b16 v109, v0 offset:1280
	v_mul_f32_e32 v0, v115, v6
	v_cvt_pk_bf16_f32 v0, v0, v177
	ds_write_b16 v109, v0 offset:1344
	v_mul_f32_e32 v0, v113, v23
	v_cvt_pk_bf16_f32 v0, v0, v177
	ds_write_b16 v109, v0 offset:1408
	v_mul_f32_e32 v0, v113, v7
	v_cvt_pk_bf16_f32 v0, v0, v177
	ds_write_b16 v109, v0 offset:1472
	v_mul_f32_e32 v0, v114, v24
	v_cvt_pk_bf16_f32 v0, v0, v177
	ds_write_b16 v109, v0 offset:2048
	v_mul_f32_e32 v0, v114, v8
	v_cvt_pk_bf16_f32 v0, v0, v177
	ds_write_b16 v109, v0 offset:2112
	v_mul_f32_e32 v0, v112, v25
	v_cvt_pk_bf16_f32 v0, v0, v177
	ds_write_b16 v109, v0 offset:2176
	v_mul_f32_e32 v0, v112, v9
	v_cvt_pk_bf16_f32 v0, v0, v177
	ds_write_b16 v109, v0 offset:2240
	v_mul_f32_e32 v0, v111, v26
	v_cvt_pk_bf16_f32 v0, v0, v177
	ds_write_b16 v109, v0 offset:2304
	v_mul_f32_e32 v0, v111, v10
	v_cvt_pk_bf16_f32 v0, v0, v177
	ds_write_b16 v109, v0 offset:2368
	v_mul_f32_e32 v0, v110, v27
	v_cvt_pk_bf16_f32 v0, v0, v177
	ds_write_b16 v109, v0 offset:2432
	v_mul_f32_e32 v0, v110, v11
	v_cvt_pk_bf16_f32 v0, v0, v177
	ds_write_b16 v109, v0 offset:2496
	v_mul_f32_e32 v0, v108, v28
	v_cvt_pk_bf16_f32 v0, v0, v177
	ds_write_b16 v109, v0 offset:3072
	v_mul_f32_e32 v0, v108, v12
	v_cvt_pk_bf16_f32 v0, v0, v177
	ds_write_b16 v109, v0 offset:3136
	v_mul_f32_e32 v0, v107, v29
	v_cvt_pk_bf16_f32 v0, v0, v177
	ds_write_b16 v109, v0 offset:3200
	v_mul_f32_e32 v0, v107, v13
	v_cvt_pk_bf16_f32 v0, v0, v177
	ds_write_b16 v109, v0 offset:3264
	v_mul_f32_e32 v0, v106, v30
	v_cvt_pk_bf16_f32 v0, v0, v177
	ds_write_b16 v109, v0 offset:3328
	v_mul_f32_e32 v0, v106, v14
	v_cvt_pk_bf16_f32 v0, v0, v177
	ds_write_b16 v109, v0 offset:3392
	v_mul_f32_e32 v0, v105, v31
	v_cvt_pk_bf16_f32 v0, v0, v177
	ds_write_b16 v109, v0 offset:3456
	v_mul_f32_e32 v0, v105, v15
	v_cvt_pk_bf16_f32 v0, v0, v177
	ds_write_b16 v109, v0 offset:3520
	v_or_b32_e32 v8, 8, v125
	s_waitcnt lgkmcnt(0)
	v_lshl_add_u32 v123, v8, 7, v147
	ds_read_b128 v[0:3], v122
	ds_read_b128 v[4:7], v123
	v_lshlrev_b32_e32 v176, 11, v8
	v_lshl_add_u64 v[98:99], v[142:143], 0, v[176:177]
	v_or_b32_e32 v8, 24, v125
	s_waitcnt lgkmcnt(1)
	global_store_dwordx4 v[96:97], v[0:3], off sc1
	s_waitcnt lgkmcnt(0)
	global_store_dwordx4 v[98:99], v[4:7], off sc1
	s_nop 1
	v_or_b32_e32 v4, 16, v125
	v_lshl_add_u32 v124, v4, 7, v147
	v_lshl_add_u32 v125, v8, 7, v147
	ds_read_b128 v[0:3], v124
	v_lshlrev_b32_e32 v176, 11, v4
	ds_read_b128 v[4:7], v125
	v_lshl_add_u64 v[100:101], v[142:143], 0, v[176:177]
	v_lshlrev_b32_e32 v176, 11, v8
	v_lshl_add_u64 v[102:103], v[142:143], 0, v[176:177]
	s_waitcnt lgkmcnt(1)
	global_store_dwordx4 v[100:101], v[0:3], off sc1
	s_waitcnt lgkmcnt(0)
	global_store_dwordx4 v[102:103], v[4:7], off sc1
	s_waitcnt lgkmcnt(0)
	s_waitcnt vmcnt(7)
	ds_write_b128 v146, v[226:229] offset:32768
	s_waitcnt vmcnt(6)
	ds_write_b128 v146, v[230:233] offset:40960
	s_waitcnt vmcnt(5)
	ds_write_b128 v146, v[234:237] offset:49152
	s_waitcnt vmcnt(4)
	ds_write_b128 v146, v[238:241] offset:57344
	s_waitcnt lgkmcnt(0)
	s_barrier
; #define XLAS __attribute__((address_space(3)))
; #define X_LOADV(c)  do { _Pragma("unroll") for (int i_ = 0; i_ < 4; ++i_) st[i_] = *(const u32x4*)(Vg + (size_t)(c) * 64 * 2048 + i_ * 64); } while (0)
; __device__ __forceinline__ void unit(int b, int h, int qblk, const bf16_t* __restrict__ CQ, const bf16_t* __restrict__ CK, const bf16_t* __restrict__ CVT, bf16_t* __restrict__ CO, XLAS unsigned char* lds, const int wv) {
;     ...
;     for (int c = 0; c < 4; ++c) {
;         const int buf = (c & 1) ? XB1 : XB0, nbuf = (c & 1) ? XB0 : XB1;
;         if (c < 3) X_LOADV(c + 1);
;         f32x16 o[2]; o[0] = f32x16{}; o[1] = f32x16{};
; #pragma unroll
;         for (int j = 0; j < 16; ++j)
; #pragma unroll
;             for (int dt = 0; dt < 2; ++dt) {
;                 const bf16x8 vf = *(const XLAS bf16x8*)(lds + buf + voff + dt * 512 + j * 2048);
;                 o[dt] = __builtin_amdgcn_mfma_f32_32x32x16_bf16(__builtin_bit_cast(bf16x8, pw[j]), vf, o[dt], 0, 0, 0);
;             }
	ds_read_b128 v[0:3], v104 offset:32768
	ds_read_b128 v[4:7], v104 offset:33280
	s_waitcnt lgkmcnt(1)
	v_mfma_f32_32x32x16_bf16 v[16:31], v[92:95], v[0:3], 0
	ds_read_b128 v[126:129], v104 offset:34816
	ds_read_b128 v[130:133], v104 offset:35328
	v_add_co_u32_e32 v142, vcc, s25, v144
	s_nop 1
	v_addc_co_u32_e32 v143, vcc, 0, v145, vcc
	global_load_dwordx4 v[226:229], v[142:143], off
	global_load_dwordx4 v[230:233], v[142:143], off offset:128
	global_load_dwordx4 v[234:237], v[142:143], off offset:256
	global_load_dwordx4 v[238:241], v[142:143], off offset:384
	s_waitcnt lgkmcnt(2)
	v_mfma_f32_32x32x16_bf16 v[0:15], v[92:95], v[4:7], 0
	s_waitcnt lgkmcnt(1)
	v_mfma_f32_32x32x16_bf16 v[16:31], v[88:91], v[126:129], v[16:31]
	s_waitcnt lgkmcnt(0)
	v_mfma_f32_32x32x16_bf16 v[0:15], v[88:91], v[130:133], v[0:15]
	ds_read_b128 v[126:129], v104 offset:36864
	ds_read_b128 v[130:133], v104 offset:37376
	s_waitcnt lgkmcnt(1)
	v_mfma_f32_32x32x16_bf16 v[16:31], v[84:87], v[126:129], v[16:31]
	s_waitcnt lgkmcnt(0)
	v_mfma_f32_32x32x16_bf16 v[0:15], v[84:87], v[130:133], v[0:15]
	ds_read_b128 v[126:129], v104 offset:38912
	ds_read_b128 v[130:133], v104 offset:39424
	s_waitcnt lgkmcnt(1)
	v_mfma_f32_32x32x16_bf16 v[16:31], v[80:83], v[126:129], v[16:31]
	s_waitcnt lgkmcnt(0)
	v_mfma_f32_32x32x16_bf16 v[0:15], v[80:83], v[130:133], v[0:15]
	ds_read_b128 v[126:129], v104 offset:40960
	ds_read_b128 v[130:133], v104 offset:41472
	s_waitcnt lgkmcnt(1)
	v_mfma_f32_32x32x16_bf16 v[16:31], v[76:79], v[126:129], v[16:31]
	s_waitcnt lgkmcnt(0)
	v_mfma_f32_32x32x16_bf16 v[0:15], v[76:79], v[130:133], v[0:15]
	ds_read_b128 v[126:129], v104 offset:43008
	ds_read_b128 v[130:133], v104 offset:43520
	s_waitcnt lgkmcnt(1)
	v_mfma_f32_32x32x16_bf16 v[16:31], v[72:75], v[126:129], v[16:31]
	s_waitcnt lgkmcnt(0)
	v_mfma_f32_32x32x16_bf16 v[0:15], v[72:75], v[130:133], v[0:15]
	ds_read_b128 v[126:129], v104 offset:45056
	ds_read_b128 v[130:133], v104 offset:45568
	s_waitcnt lgkmcnt(1)
	v_mfma_f32_32x32x16_bf16 v[16:31], v[68:71], v[126:129], v[16:31]
	s_waitcnt lgkmcnt(0)
	v_mfma_f32_32x32x16_bf16 v[0:15], v[68:71], v[130:133], v[0:15]
	ds_read_b128 v[126:129], v104 offset:47104
	ds_read_b128 v[130:133], v104 offset:47616
	s_waitcnt lgkmcnt(1)
	v_mfma_f32_32x32x16_bf16 v[16:31], v[64:67], v[126:129], v[16:31]
	s_waitcnt lgkmcnt(0)
	v_mfma_f32_32x32x16_bf16 v[0:15], v[64:67], v[130:133], v[0:15]
	ds_read_b128 v[126:129], v104 offset:49152
	ds_read_b128 v[130:133], v104 offset:49664
	s_waitcnt lgkmcnt(1)
	v_mfma_f32_32x32x16_bf16 v[16:31], v[60:63], v[126:129], v[16:31]
	s_waitcnt lgkmcnt(0)
	v_mfma_f32_32x32x16_bf16 v[0:15], v[60:63], v[130:133], v[0:15]
	ds_read_b128 v[126:129], v104 offset:51200
	ds_read_b128 v[130:133], v104 offset:51712
	s_waitcnt lgkmcnt(1)
	v_mfma_f32_32x32x16_bf16 v[16:31], v[56:59], v[126:129], v[16:31]
	s_waitcnt lgkmcnt(0)
	v_mfma_f32_32x32x16_bf16 v[0:15], v[56:59], v[130:133], v[0:15]
	ds_read_b128 v[126:129], v104 offset:53248
	ds_read_b128 v[130:133], v104 offset:53760
	s_waitcnt lgkmcnt(1)
	v_mfma_f32_32x32x16_bf16 v[16:31], v[52:55], v[126:129], v[16:31]
	s_waitcnt lgkmcnt(0)
	v_mfma_f32_32x32x16_bf16 v[0:15], v[52:55], v[130:133], v[0:15]
	ds_read_b128 v[126:129], v104 offset:55296
	ds_read_b128 v[130:133], v104 offset:55808
	s_waitcnt lgkmcnt(1)
	v_mfma_f32_32x32x16_bf16 v[16:31], v[48:51], v[126:129], v[16:31]
	s_waitcnt lgkmcnt(0)
	v_mfma_f32_32x32x16_bf16 v[0:15], v[48:51], v[130:133], v[0:15]
	ds_read_b128 v[126:129], v104 offset:57344
	ds_read_b128 v[130:133], v104 offset:57856
	s_waitcnt lgkmcnt(1)
	v_mfma_f32_32x32x16_bf16 v[16:31], v[44:47], v[126:129], v[16:31]
	s_waitcnt lgkmcnt(0)
	v_mfma_f32_32x32x16_bf16 v[0:15], v[44:47], v[130:133], v[0:15]
	ds_read_b128 v[126:129], v104 offset:59392
	ds_read_b128 v[130:133], v104 offset:59904
	s_waitcnt lgkmcnt(1)
	v_mfma_f32_32x32x16_bf16 v[16:31], v[40:43], v[126:129], v[16:31]
	s_waitcnt lgkmcnt(0)
	v_mfma_f32_32x32x16_bf16 v[0:15], v[40:43], v[130:133], v[0:15]
	ds_read_b128 v[126:129], v104 offset:61440
	ds_read_b128 v[130:133], v104 offset:61952
	s_waitcnt lgkmcnt(1)
	v_mfma_f32_32x32x16_bf16 v[16:31], v[36:39], v[126:129], v[16:31]
	s_waitcnt lgkmcnt(0)
	v_mfma_f32_32x32x16_bf16 v[0:15], v[36:39], v[130:133], v[0:15]
	ds_read_b128 v[126:129], v104 offset:63488
	ds_read_b128 v[130:133], v104 offset:64000
	s_waitcnt lgkmcnt(1)
	v_mfma_f32_32x32x16_bf16 v[16:31], v[32:35], v[126:129], v[16:31]
	v_add_co_u32_e32 v142, vcc, s26, v144
	s_nop 6
	v_mul_f32_e32 v16, v121, v16
	s_waitcnt lgkmcnt(0)
; __device__ __forceinline__ int crow(int r,int hi){return (r&3)+8*(r>>2)+4*hi;}
; #define XLAS __attribute__((address_space(3)))
; __device__ __forceinline__ int crow(int r, int hi) { return (r & 3) + 8 * (r >> 2) + 4 * hi; }
; __device__ __forceinline__ unsigned pk(float lo, float hi) { return pg8::cvt_pk_bf16(lo, hi); }
; #define X_LOADV(c)  do { _Pragma("unroll") for (int i_ = 0; i_ < 4; ++i_) st[i_] = *(const u32x4*)(Vg + (size_t)(c) * 64 * 2048 + i_ * 64); } while (0)
; #define X_STOREV(buf) do { _Pragma("unroll") for (int i_ = 0; i_ < 4; ++i_) *(XLAS u32x4*)(lds + (buf) + (wid + 8 * i_) * 1024 + lane * 16) = st[i_]; } while (0)
; __device__ __forceinline__ void unit(int b, int h, int qblk, const bf16_t* __restrict__ CQ, const bf16_t* __restrict__ CK, const bf16_t* __restrict__ CVT, bf16_t* __restrict__ CO, XLAS unsigned char* lds, const int wv) {
;     ...
;         if (c < 3) X_LOADV(c + 1);
;         f32x16 o[2]; o[0] = f32x16{}; o[1] = f32x16{};
; #pragma unroll
;         for (int j = 0; j < 16; ++j)
; #pragma unroll
;             for (int dt = 0; dt < 2; ++dt) {
;                 const bf16x8 vf = *(const XLAS bf16x8*)(lds + buf + voff + dt * 512 + j * 2048);
;                 o[dt] = __builtin_amdgcn_mfma_f32_32x32x16_bf16(__builtin_bit_cast(bf16x8, pw[j]), vf, o[dt], 0, 0, 0);
;             }
; #pragma unroll
;         for (int r = 0; r < 16; ++r) { const int orow = crow(r, hi);
; #pragma unroll
;             for (int dt = 0; dt < 2; ++dt) { const unsigned w = pk(o[dt][r] * rli[r], 0.f); stg[orow * 64 + dt * 32 + r32] = (bf16_t)(w & 0xffffu); } }
;         asm volatile("s_waitcnt lgkmcnt(0)" ::: "memory");
; #pragma unroll
;         for (int i = 0; i < 4; ++i) { const int row = i * 8 + (lane >> 3), ch = lane & 7; const u32x4 v = *(const XLAS u32x4*)(stg + row * 64 + ch * 8); *(u32x4*)(Ow + (size_t)row * 1024 + c * 64 + ch * 8) = v; }
;         asm volatile("s_waitcnt lgkmcnt(0)" ::: "memory");
;         if (c < 3) X_STOREV(nbuf);
;         __syncthreads();
	v_mfma_f32_32x32x16_bf16 v[0:15], v[32:35], v[130:133], v[0:15]
	v_cvt_pk_bf16_f32 v16, v16, v177
	ds_write_b16 v109, v16
	v_addc_co_u32_e32 v143, vcc, 0, v145, vcc
	s_nop 9
	v_mul_f32_e32 v0, v121, v0
	v_cvt_pk_bf16_f32 v0, v0, v177
	ds_write_b16 v109, v0 offset:64
	v_mul_f32_e32 v0, v120, v17
	v_cvt_pk_bf16_f32 v0, v0, v177
	ds_write_b16 v109, v0 offset:128
	v_mul_f32_e32 v0, v120, v1
	v_cvt_pk_bf16_f32 v0, v0, v177
	ds_write_b16 v109, v0 offset:192
	v_mul_f32_e32 v0, v119, v18
	v_cvt_pk_bf16_f32 v0, v0, v177
	ds_write_b16 v109, v0 offset:256
	v_mul_f32_e32 v0, v119, v2
	v_cvt_pk_bf16_f32 v0, v0, v177
	ds_write_b16 v109, v0 offset:320
	v_mul_f32_e32 v0, v118, v19
	v_cvt_pk_bf16_f32 v0, v0, v177
	ds_write_b16 v109, v0 offset:384
	v_mul_f32_e32 v0, v118, v3
	v_cvt_pk_bf16_f32 v0, v0, v177
	ds_write_b16 v109, v0 offset:448
	v_mul_f32_e32 v0, v117, v20
	v_cvt_pk_bf16_f32 v0, v0, v177
	ds_write_b16 v109, v0 offset:1024
	v_mul_f32_e32 v0, v117, v4
	v_cvt_pk_bf16_f32 v0, v0, v177
	ds_write_b16 v109, v0 offset:1088
	v_mul_f32_e32 v0, v116, v21
	v_cvt_pk_bf16_f32 v0, v0, v177
	ds_write_b16 v109, v0 offset:1152
	v_mul_f32_e32 v0, v116, v5
	v_cvt_pk_bf16_f32 v0, v0, v177
	ds_write_b16 v109, v0 offset:1216
	v_mul_f32_e32 v0, v115, v22
	v_cvt_pk_bf16_f32 v0, v0, v177
	ds_write_b16 v109, v0 offset:1280
	v_mul_f32_e32 v0, v115, v6
	v_cvt_pk_bf16_f32 v0, v0, v177
	ds_write_b16 v109, v0 offset:1344
	v_mul_f32_e32 v0, v113, v23
	v_cvt_pk_bf16_f32 v0, v0, v177
	ds_write_b16 v109, v0 offset:1408
	v_mul_f32_e32 v0, v113, v7
	v_cvt_pk_bf16_f32 v0, v0, v177
	ds_write_b16 v109, v0 offset:1472
	v_mul_f32_e32 v0, v114, v24
	v_cvt_pk_bf16_f32 v0, v0, v177
	ds_write_b16 v109, v0 offset:2048
	v_mul_f32_e32 v0, v114, v8
	v_cvt_pk_bf16_f32 v0, v0, v177
	ds_write_b16 v109, v0 offset:2112
	v_mul_f32_e32 v0, v112, v25
	v_cvt_pk_bf16_f32 v0, v0, v177
	ds_write_b16 v109, v0 offset:2176
	v_mul_f32_e32 v0, v112, v9
	v_cvt_pk_bf16_f32 v0, v0, v177
	ds_write_b16 v109, v0 offset:2240
	v_mul_f32_e32 v0, v111, v26
	v_cvt_pk_bf16_f32 v0, v0, v177
	ds_write_b16 v109, v0 offset:2304
	v_mul_f32_e32 v0, v111, v10
	v_cvt_pk_bf16_f32 v0, v0, v177
	ds_write_b16 v109, v0 offset:2368
	v_mul_f32_e32 v0, v110, v27
	v_cvt_pk_bf16_f32 v0, v0, v177
	ds_write_b16 v109, v0 offset:2432
	v_mul_f32_e32 v0, v110, v11
	v_cvt_pk_bf16_f32 v0, v0, v177
	ds_write_b16 v109, v0 offset:2496
	v_mul_f32_e32 v0, v108, v28
	v_cvt_pk_bf16_f32 v0, v0, v177
	ds_write_b16 v109, v0 offset:3072
	v_mul_f32_e32 v0, v108, v12
	v_cvt_pk_bf16_f32 v0, v0, v177
	ds_write_b16 v109, v0 offset:3136
	v_mul_f32_e32 v0, v107, v29
	v_cvt_pk_bf16_f32 v0, v0, v177
	ds_write_b16 v109, v0 offset:3200
	v_mul_f32_e32 v0, v107, v13
	v_cvt_pk_bf16_f32 v0, v0, v177
	ds_write_b16 v109, v0 offset:3264
	v_mul_f32_e32 v0, v106, v30
	v_cvt_pk_bf16_f32 v0, v0, v177
	ds_write_b16 v109, v0 offset:3328
	v_mul_f32_e32 v0, v106, v14
	v_cvt_pk_bf16_f32 v0, v0, v177
	ds_write_b16 v109, v0 offset:3392
	v_mul_f32_e32 v0, v105, v31
	v_cvt_pk_bf16_f32 v0, v0, v177
	ds_write_b16 v109, v0 offset:3456
	v_mul_f32_e32 v0, v105, v15
	v_cvt_pk_bf16_f32 v0, v0, v177
	ds_write_b16 v109, v0 offset:3520
	s_waitcnt lgkmcnt(0)
	ds_read_b128 v[0:3], v122
	ds_read_b128 v[4:7], v123
	ds_read_b128 v[8:11], v124
	ds_read_b128 v[12:15], v125
	s_waitcnt lgkmcnt(3)
	global_store_dwordx4 v[96:97], v[0:3], off offset:128 sc1
	s_waitcnt lgkmcnt(2)
	global_store_dwordx4 v[98:99], v[4:7], off offset:128 sc1
	s_waitcnt lgkmcnt(1)
	global_store_dwordx4 v[100:101], v[8:11], off offset:128 sc1
	s_waitcnt lgkmcnt(0)
	global_store_dwordx4 v[102:103], v[12:15], off offset:128 sc1
	s_waitcnt lgkmcnt(0)
	s_waitcnt vmcnt(7)
	ds_write_b128 v146, v[226:229]
	s_waitcnt vmcnt(6)
	ds_write_b128 v146, v[230:233] offset:8192
	s_waitcnt vmcnt(5)
	ds_write_b128 v146, v[234:237] offset:16384
	s_waitcnt vmcnt(4)
	ds_write_b128 v146, v[238:241] offset:24576
	s_waitcnt lgkmcnt(0)
	s_barrier
	global_load_dwordx4 v[226:229], v[142:143], off
	global_load_dwordx4 v[230:233], v[142:143], off offset:128
	global_load_dwordx4 v[234:237], v[142:143], off offset:256
	global_load_dwordx4 v[238:241], v[142:143], off offset:384
	ds_read_b128 v[0:3], v104
	ds_read_b128 v[4:7], v104 offset:512
	s_waitcnt lgkmcnt(1)
	v_mfma_f32_32x32x16_bf16 v[16:31], v[92:95], v[0:3], 0
	ds_read_b128 v[126:129], v104 offset:2048
	ds_read_b128 v[130:133], v104 offset:2560
	s_waitcnt lgkmcnt(2)
	v_mfma_f32_32x32x16_bf16 v[0:15], v[92:95], v[4:7], 0
	s_waitcnt lgkmcnt(1)
	v_mfma_f32_32x32x16_bf16 v[16:31], v[88:91], v[126:129], v[16:31]
	s_waitcnt lgkmcnt(0)
	v_mfma_f32_32x32x16_bf16 v[0:15], v[88:91], v[130:133], v[0:15]
	ds_read_b128 v[126:129], v104 offset:4096
	ds_read_b128 v[130:133], v104 offset:4608
	s_waitcnt lgkmcnt(1)
	v_mfma_f32_32x32x16_bf16 v[16:31], v[84:87], v[126:129], v[16:31]
	s_waitcnt lgkmcnt(0)
	v_mfma_f32_32x32x16_bf16 v[0:15], v[84:87], v[130:133], v[0:15]
	ds_read_b128 v[126:129], v104 offset:6144
	ds_read_b128 v[130:133], v104 offset:6656
	s_waitcnt lgkmcnt(1)
	v_mfma_f32_32x32x16_bf16 v[16:31], v[80:83], v[126:129], v[16:31]
	s_waitcnt lgkmcnt(0)
	v_mfma_f32_32x32x16_bf16 v[0:15], v[80:83], v[130:133], v[0:15]
	ds_read_b128 v[126:129], v104 offset:8192
	ds_read_b128 v[130:133], v104 offset:8704
	s_waitcnt lgkmcnt(1)
	v_mfma_f32_32x32x16_bf16 v[16:31], v[76:79], v[126:129], v[16:31]
	s_waitcnt lgkmcnt(0)
	v_mfma_f32_32x32x16_bf16 v[0:15], v[76:79], v[130:133], v[0:15]
	ds_read_b128 v[126:129], v104 offset:10240
	ds_read_b128 v[130:133], v104 offset:10752
	s_waitcnt lgkmcnt(1)
	v_mfma_f32_32x32x16_bf16 v[16:31], v[72:75], v[126:129], v[16:31]
	s_waitcnt lgkmcnt(0)
; __device__ __forceinline__ int crow(int r,int hi){return (r&3)+8*(r>>2)+4*hi;}
; #define XLAS __attribute__((address_space(3)))
; __device__ __forceinline__ int crow(int r, int hi) { return (r & 3) + 8 * (r >> 2) + 4 * hi; }
; __device__ __forceinline__ unsigned pk(float lo, float hi) { return pg8::cvt_pk_bf16(lo, hi); }
; #define X_STOREV(buf) do { _Pragma("unroll") for (int i_ = 0; i_ < 4; ++i_) *(XLAS u32x4*)(lds + (buf) + (wid + 8 * i_) * 1024 + lane * 16) = st[i_]; } while (0)
; __device__ __forceinline__ void unit(int b, int h, int qblk, const bf16_t* __restrict__ CQ, const bf16_t* __restrict__ CK, const bf16_t* __restrict__ CVT, bf16_t* __restrict__ CO, XLAS unsigned char* lds, const int wv) {
;     ...
; #pragma unroll
;         for (int j = 0; j < 16; ++j)
; #pragma unroll
;             for (int dt = 0; dt < 2; ++dt) {
;                 const bf16x8 vf = *(const XLAS bf16x8*)(lds + buf + voff + dt * 512 + j * 2048);
;                 o[dt] = __builtin_amdgcn_mfma_f32_32x32x16_bf16(__builtin_bit_cast(bf16x8, pw[j]), vf, o[dt], 0, 0, 0);
;             }
; #pragma unroll
;         for (int r = 0; r < 16; ++r) { const int orow = crow(r, hi);
; #pragma unroll
;             for (int dt = 0; dt < 2; ++dt) { const unsigned w = pk(o[dt][r] * rli[r], 0.f); stg[orow * 64 + dt * 32 + r32] = (bf16_t)(w & 0xffffu); } }
;         asm volatile("s_waitcnt lgkmcnt(0)" ::: "memory");
; #pragma unroll
;         for (int i = 0; i < 4; ++i) { const int row = i * 8 + (lane >> 3), ch = lane & 7; const u32x4 v = *(const XLAS u32x4*)(stg + row * 64 + ch * 8); *(u32x4*)(Ow + (size_t)row * 1024 + c * 64 + ch * 8) = v; }
;         asm volatile("s_waitcnt lgkmcnt(0)" ::: "memory");
;         if (c < 3) X_STOREV(nbuf);
;         __syncthreads();
	v_mfma_f32_32x32x16_bf16 v[0:15], v[72:75], v[130:133], v[0:15]
	ds_read_b128 v[126:129], v104 offset:12288
	ds_read_b128 v[130:133], v104 offset:12800
	s_waitcnt lgkmcnt(1)
	v_mfma_f32_32x32x16_bf16 v[16:31], v[68:71], v[126:129], v[16:31]
	s_waitcnt lgkmcnt(0)
	v_mfma_f32_32x32x16_bf16 v[0:15], v[68:71], v[130:133], v[0:15]
	ds_read_b128 v[126:129], v104 offset:14336
	ds_read_b128 v[130:133], v104 offset:14848
	s_waitcnt lgkmcnt(1)
	v_mfma_f32_32x32x16_bf16 v[16:31], v[64:67], v[126:129], v[16:31]
	s_waitcnt lgkmcnt(0)
	v_mfma_f32_32x32x16_bf16 v[0:15], v[64:67], v[130:133], v[0:15]
	ds_read_b128 v[126:129], v104 offset:16384
	ds_read_b128 v[130:133], v104 offset:16896
	s_waitcnt lgkmcnt(1)
	v_mfma_f32_32x32x16_bf16 v[16:31], v[60:63], v[126:129], v[16:31]
	s_waitcnt lgkmcnt(0)
	v_mfma_f32_32x32x16_bf16 v[0:15], v[60:63], v[130:133], v[0:15]
	ds_read_b128 v[126:129], v104 offset:18432
	ds_read_b128 v[130:133], v104 offset:18944
	s_waitcnt lgkmcnt(1)
	v_mfma_f32_32x32x16_bf16 v[16:31], v[56:59], v[126:129], v[16:31]
	s_waitcnt lgkmcnt(0)
	v_mfma_f32_32x32x16_bf16 v[0:15], v[56:59], v[130:133], v[0:15]
	ds_read_b128 v[126:129], v104 offset:20480
	ds_read_b128 v[130:133], v104 offset:20992
	s_waitcnt lgkmcnt(1)
	v_mfma_f32_32x32x16_bf16 v[16:31], v[52:55], v[126:129], v[16:31]
	s_waitcnt lgkmcnt(0)
	v_mfma_f32_32x32x16_bf16 v[0:15], v[52:55], v[130:133], v[0:15]
	ds_read_b128 v[126:129], v104 offset:22528
	ds_read_b128 v[130:133], v104 offset:23040
	s_waitcnt lgkmcnt(1)
	v_mfma_f32_32x32x16_bf16 v[16:31], v[48:51], v[126:129], v[16:31]
	s_waitcnt lgkmcnt(0)
	v_mfma_f32_32x32x16_bf16 v[0:15], v[48:51], v[130:133], v[0:15]
	ds_read_b128 v[126:129], v104 offset:24576
	ds_read_b128 v[130:133], v104 offset:25088
	s_waitcnt lgkmcnt(1)
	v_mfma_f32_32x32x16_bf16 v[16:31], v[44:47], v[126:129], v[16:31]
	s_waitcnt lgkmcnt(0)
	v_mfma_f32_32x32x16_bf16 v[0:15], v[44:47], v[130:133], v[0:15]
	ds_read_b128 v[126:129], v104 offset:26624
	ds_read_b128 v[130:133], v104 offset:27136
	s_waitcnt lgkmcnt(1)
	v_mfma_f32_32x32x16_bf16 v[16:31], v[40:43], v[126:129], v[16:31]
	s_waitcnt lgkmcnt(0)
	v_mfma_f32_32x32x16_bf16 v[0:15], v[40:43], v[130:133], v[0:15]
	ds_read_b128 v[126:129], v104 offset:28672
	ds_read_b128 v[130:133], v104 offset:29184
	s_waitcnt lgkmcnt(1)
	v_mfma_f32_32x32x16_bf16 v[16:31], v[36:39], v[126:129], v[16:31]
	ds_read_b128 v[126:129], v104 offset:30720
	s_waitcnt lgkmcnt(1)
	v_mfma_f32_32x32x16_bf16 v[0:15], v[36:39], v[130:133], v[0:15]
	ds_read_b128 v[130:133], v104 offset:31232
	s_waitcnt lgkmcnt(1)
	v_mfma_f32_32x32x16_bf16 v[16:31], v[32:35], v[126:129], v[16:31]
	s_nop 0
	s_nop 6
	v_mul_f32_e32 v16, v121, v16
	s_waitcnt lgkmcnt(0)
	v_mfma_f32_32x32x16_bf16 v[0:15], v[32:35], v[130:133], v[0:15]
	v_cvt_pk_bf16_f32 v16, v16, v177
	ds_write_b16 v109, v16
	s_nop 10
	v_mul_f32_e32 v0, v121, v0
	v_cvt_pk_bf16_f32 v0, v0, v177
	ds_write_b16 v109, v0 offset:64
	v_mul_f32_e32 v0, v120, v17
	v_cvt_pk_bf16_f32 v0, v0, v177
	ds_write_b16 v109, v0 offset:128
	v_mul_f32_e32 v0, v120, v1
	v_cvt_pk_bf16_f32 v0, v0, v177
	ds_write_b16 v109, v0 offset:192
	v_mul_f32_e32 v0, v119, v18
	v_cvt_pk_bf16_f32 v0, v0, v177
	ds_write_b16 v109, v0 offset:256
	v_mul_f32_e32 v0, v119, v2
	v_cvt_pk_bf16_f32 v0, v0, v177
	ds_write_b16 v109, v0 offset:320
	v_mul_f32_e32 v0, v118, v19
	v_cvt_pk_bf16_f32 v0, v0, v177
	ds_write_b16 v109, v0 offset:384
	v_mul_f32_e32 v0, v118, v3
	v_cvt_pk_bf16_f32 v0, v0, v177
	ds_write_b16 v109, v0 offset:448
	v_mul_f32_e32 v0, v117, v20
	v_cvt_pk_bf16_f32 v0, v0, v177
	ds_write_b16 v109, v0 offset:1024
	v_mul_f32_e32 v0, v117, v4
	v_cvt_pk_bf16_f32 v0, v0, v177
	ds_write_b16 v109, v0 offset:1088
	v_mul_f32_e32 v0, v116, v21
	v_cvt_pk_bf16_f32 v0, v0, v177
	ds_write_b16 v109, v0 offset:1152
	v_mul_f32_e32 v0, v116, v5
	v_cvt_pk_bf16_f32 v0, v0, v177
	ds_write_b16 v109, v0 offset:1216
	v_mul_f32_e32 v0, v115, v22
	v_cvt_pk_bf16_f32 v0, v0, v177
	ds_write_b16 v109, v0 offset:1280
	v_mul_f32_e32 v0, v115, v6
	v_cvt_pk_bf16_f32 v0, v0, v177
	ds_write_b16 v109, v0 offset:1344
	v_mul_f32_e32 v0, v113, v23
	v_cvt_pk_bf16_f32 v0, v0, v177
	ds_write_b16 v109, v0 offset:1408
	v_mul_f32_e32 v0, v113, v7
	v_cvt_pk_bf16_f32 v0, v0, v177
	ds_write_b16 v109, v0 offset:1472
	v_mul_f32_e32 v0, v114, v24
	v_cvt_pk_bf16_f32 v0, v0, v177
	ds_write_b16 v109, v0 offset:2048
	v_mul_f32_e32 v0, v114, v8
	v_cvt_pk_bf16_f32 v0, v0, v177
	ds_write_b16 v109, v0 offset:2112
	v_mul_f32_e32 v0, v112, v25
	v_cvt_pk_bf16_f32 v0, v0, v177
	ds_write_b16 v109, v0 offset:2176
	v_mul_f32_e32 v0, v112, v9
	v_cvt_pk_bf16_f32 v0, v0, v177
	ds_write_b16 v109, v0 offset:2240
	v_mul_f32_e32 v0, v111, v26
	v_cvt_pk_bf16_f32 v0, v0, v177
	ds_write_b16 v109, v0 offset:2304
	v_mul_f32_e32 v0, v111, v10
	v_cvt_pk_bf16_f32 v0, v0, v177
	ds_write_b16 v109, v0 offset:2368
	v_mul_f32_e32 v0, v110, v27
	v_cvt_pk_bf16_f32 v0, v0, v177
	ds_write_b16 v109, v0 offset:2432
	v_mul_f32_e32 v0, v110, v11
	v_cvt_pk_bf16_f32 v0, v0, v177
	ds_write_b16 v109, v0 offset:2496
	v_mul_f32_e32 v0, v108, v28
	v_cvt_pk_bf16_f32 v0, v0, v177
	ds_write_b16 v109, v0 offset:3072
	v_mul_f32_e32 v0, v108, v12
	v_cvt_pk_bf16_f32 v0, v0, v177
	ds_write_b16 v109, v0 offset:3136
	v_mul_f32_e32 v0, v107, v29
	v_cvt_pk_bf16_f32 v0, v0, v177
	ds_write_b16 v109, v0 offset:3200
	v_mul_f32_e32 v0, v107, v13
	v_cvt_pk_bf16_f32 v0, v0, v177
	ds_write_b16 v109, v0 offset:3264
	v_mul_f32_e32 v0, v106, v30
	v_cvt_pk_bf16_f32 v0, v0, v177
	ds_write_b16 v109, v0 offset:3328
	v_mul_f32_e32 v0, v106, v14
	v_cvt_pk_bf16_f32 v0, v0, v177
	ds_write_b16 v109, v0 offset:3392
	v_mul_f32_e32 v0, v105, v31
	v_cvt_pk_bf16_f32 v0, v0, v177
	ds_write_b16 v109, v0 offset:3456
	v_mul_f32_e32 v0, v105, v15
	v_cvt_pk_bf16_f32 v0, v0, v177
	ds_write_b16 v109, v0 offset:3520
	s_waitcnt lgkmcnt(0)
	ds_read_b128 v[0:3], v122
	ds_read_b128 v[4:7], v123
	ds_read_b128 v[8:11], v124
	ds_read_b128 v[12:15], v125
	s_waitcnt lgkmcnt(3)
	global_store_dwordx4 v[96:97], v[0:3], off offset:256 sc1
	s_waitcnt lgkmcnt(2)
	global_store_dwordx4 v[98:99], v[4:7], off offset:256 sc1
	s_waitcnt lgkmcnt(1)
	global_store_dwordx4 v[100:101], v[8:11], off offset:256 sc1
	s_waitcnt lgkmcnt(0)
	global_store_dwordx4 v[102:103], v[12:15], off offset:256 sc1
	s_waitcnt lgkmcnt(0)
	s_waitcnt vmcnt(7)
	ds_write_b128 v146, v[226:229] offset:32768
	s_waitcnt vmcnt(6)
	ds_write_b128 v146, v[230:233] offset:40960
	s_waitcnt vmcnt(5)
	ds_write_b128 v146, v[234:237] offset:49152
	s_waitcnt vmcnt(4)
	ds_write_b128 v146, v[238:241] offset:57344
	s_waitcnt lgkmcnt(0)
	s_barrier
; #define XLAS __attribute__((address_space(3)))
; __device__ __forceinline__ void unit(int b, int h, int qblk, const bf16_t* __restrict__ CQ, const bf16_t* __restrict__ CK, const bf16_t* __restrict__ CVT, bf16_t* __restrict__ CO, XLAS unsigned char* lds, const int wv) {
;     ...
; #pragma unroll
;         for (int j = 0; j < 16; ++j)
; #pragma unroll
;             for (int dt = 0; dt < 2; ++dt) {
;                 const bf16x8 vf = *(const XLAS bf16x8*)(lds + buf + voff + dt * 512 + j * 2048);
;                 o[dt] = __builtin_amdgcn_mfma_f32_32x32x16_bf16(__builtin_bit_cast(bf16x8, pw[j]), vf, o[dt], 0, 0, 0);
;             }
	ds_read_b128 v[0:3], v104 offset:32768
	ds_read_b128 v[4:7], v104 offset:33280
	s_waitcnt lgkmcnt(1)
	v_mfma_f32_32x32x16_bf16 v[16:31], v[92:95], v[0:3], 0
	s_waitcnt lgkmcnt(0)
	v_mfma_f32_32x32x16_bf16 v[0:15], v[92:95], v[4:7], 0
	ds_read_b128 v[92:95], v104 offset:34816
	ds_read_b128 v[126:129], v104 offset:35328
	s_waitcnt lgkmcnt(1)
	v_mfma_f32_32x32x16_bf16 v[16:31], v[88:91], v[92:95], v[16:31]
	s_waitcnt lgkmcnt(0)
	v_mfma_f32_32x32x16_bf16 v[0:15], v[88:91], v[126:129], v[0:15]
	ds_read_b128 v[88:91], v104 offset:36864
	ds_read_b128 v[92:95], v104 offset:37376
	s_waitcnt lgkmcnt(1)
	v_mfma_f32_32x32x16_bf16 v[16:31], v[84:87], v[88:91], v[16:31]
	s_waitcnt lgkmcnt(0)
	v_mfma_f32_32x32x16_bf16 v[0:15], v[84:87], v[92:95], v[0:15]
	ds_read_b128 v[84:87], v104 offset:38912
	ds_read_b128 v[88:91], v104 offset:39424
	s_waitcnt lgkmcnt(1)
	v_mfma_f32_32x32x16_bf16 v[16:31], v[80:83], v[84:87], v[16:31]
	s_waitcnt lgkmcnt(0)
	v_mfma_f32_32x32x16_bf16 v[0:15], v[80:83], v[88:91], v[0:15]
	ds_read_b128 v[80:83], v104 offset:40960
	ds_read_b128 v[84:87], v104 offset:41472
	s_waitcnt lgkmcnt(1)
	v_mfma_f32_32x32x16_bf16 v[16:31], v[76:79], v[80:83], v[16:31]
	s_waitcnt lgkmcnt(0)
	v_mfma_f32_32x32x16_bf16 v[0:15], v[76:79], v[84:87], v[0:15]
	ds_read_b128 v[76:79], v104 offset:43008
	ds_read_b128 v[80:83], v104 offset:43520
	s_waitcnt lgkmcnt(1)
	v_mfma_f32_32x32x16_bf16 v[16:31], v[72:75], v[76:79], v[16:31]
	s_waitcnt lgkmcnt(0)
	v_mfma_f32_32x32x16_bf16 v[0:15], v[72:75], v[80:83], v[0:15]
	ds_read_b128 v[72:75], v104 offset:45056
	ds_read_b128 v[76:79], v104 offset:45568
	s_waitcnt lgkmcnt(1)
	v_mfma_f32_32x32x16_bf16 v[16:31], v[68:71], v[72:75], v[16:31]
	s_waitcnt lgkmcnt(0)
	v_mfma_f32_32x32x16_bf16 v[0:15], v[68:71], v[76:79], v[0:15]
	ds_read_b128 v[68:71], v104 offset:47104
	ds_read_b128 v[72:75], v104 offset:47616
	s_waitcnt lgkmcnt(1)
	v_mfma_f32_32x32x16_bf16 v[16:31], v[64:67], v[68:71], v[16:31]
	s_waitcnt lgkmcnt(0)
	v_mfma_f32_32x32x16_bf16 v[0:15], v[64:67], v[72:75], v[0:15]
	ds_read_b128 v[64:67], v104 offset:49152
	ds_read_b128 v[68:71], v104 offset:49664
	s_waitcnt lgkmcnt(1)
	v_mfma_f32_32x32x16_bf16 v[16:31], v[60:63], v[64:67], v[16:31]
	s_waitcnt lgkmcnt(0)
	v_mfma_f32_32x32x16_bf16 v[0:15], v[60:63], v[68:71], v[0:15]
	ds_read_b128 v[60:63], v104 offset:51200
	ds_read_b128 v[64:67], v104 offset:51712
	s_waitcnt lgkmcnt(1)
	v_mfma_f32_32x32x16_bf16 v[16:31], v[56:59], v[60:63], v[16:31]
	s_waitcnt lgkmcnt(0)
	v_mfma_f32_32x32x16_bf16 v[0:15], v[56:59], v[64:67], v[0:15]
	ds_read_b128 v[56:59], v104 offset:53248
	ds_read_b128 v[60:63], v104 offset:53760
	s_waitcnt lgkmcnt(1)
	v_mfma_f32_32x32x16_bf16 v[16:31], v[52:55], v[56:59], v[16:31]
	s_waitcnt lgkmcnt(0)
	v_mfma_f32_32x32x16_bf16 v[0:15], v[52:55], v[60:63], v[0:15]
	ds_read_b128 v[52:55], v104 offset:55296
	ds_read_b128 v[56:59], v104 offset:55808
	s_waitcnt lgkmcnt(1)
	v_mfma_f32_32x32x16_bf16 v[16:31], v[48:51], v[52:55], v[16:31]
	s_waitcnt lgkmcnt(0)
	v_mfma_f32_32x32x16_bf16 v[0:15], v[48:51], v[56:59], v[0:15]
	ds_read_b128 v[48:51], v104 offset:57344
	ds_read_b128 v[52:55], v104 offset:57856
	s_waitcnt lgkmcnt(1)
	v_mfma_f32_32x32x16_bf16 v[16:31], v[44:47], v[48:51], v[16:31]
	s_waitcnt lgkmcnt(0)
	v_mfma_f32_32x32x16_bf16 v[0:15], v[44:47], v[52:55], v[0:15]
	ds_read_b128 v[44:47], v104 offset:59392
	ds_read_b128 v[48:51], v104 offset:59904
	s_waitcnt lgkmcnt(1)
	v_mfma_f32_32x32x16_bf16 v[16:31], v[40:43], v[44:47], v[16:31]
	s_waitcnt lgkmcnt(0)
	v_mfma_f32_32x32x16_bf16 v[0:15], v[40:43], v[48:51], v[0:15]
	ds_read_b128 v[40:43], v104 offset:61440
	ds_read_b128 v[44:47], v104 offset:61952
	s_waitcnt lgkmcnt(1)
	v_mfma_f32_32x32x16_bf16 v[16:31], v[36:39], v[40:43], v[16:31]
	s_waitcnt lgkmcnt(0)
; __device__ __forceinline__ int crow(int r,int hi){return (r&3)+8*(r>>2)+4*hi;}
; #define XLAS __attribute__((address_space(3)))
; __device__ __forceinline__ int crow(int r, int hi) { return (r & 3) + 8 * (r >> 2) + 4 * hi; }
; __device__ __forceinline__ unsigned pk(float lo, float hi) { return pg8::cvt_pk_bf16(lo, hi); }
; #define X_STOREV(buf) do { _Pragma("unroll") for (int i_ = 0; i_ < 4; ++i_) *(XLAS u32x4*)(lds + (buf) + (wid + 8 * i_) * 1024 + lane * 16) = st[i_]; } while (0)
; __device__ __forceinline__ void unit(int b, int h, int qblk, const bf16_t* __restrict__ CQ, const bf16_t* __restrict__ CK, const bf16_t* __restrict__ CVT, bf16_t* __restrict__ CO, XLAS unsigned char* lds, const int wv) {
;     ...
; #pragma unroll
;         for (int j = 0; j < 16; ++j)
; #pragma unroll
;             for (int dt = 0; dt < 2; ++dt) {
;                 const bf16x8 vf = *(const XLAS bf16x8*)(lds + buf + voff + dt * 512 + j * 2048);
;                 o[dt] = __builtin_amdgcn_mfma_f32_32x32x16_bf16(__builtin_bit_cast(bf16x8, pw[j]), vf, o[dt], 0, 0, 0);
;             }
; #pragma unroll
;         for (int r = 0; r < 16; ++r) { const int orow = crow(r, hi);
; #pragma unroll
;             for (int dt = 0; dt < 2; ++dt) { const unsigned w = pk(o[dt][r] * rli[r], 0.f); stg[orow * 64 + dt * 32 + r32] = (bf16_t)(w & 0xffffu); } }
;         asm volatile("s_waitcnt lgkmcnt(0)" ::: "memory");
; #pragma unroll
;         for (int i = 0; i < 4; ++i) { const int row = i * 8 + (lane >> 3), ch = lane & 7; const u32x4 v = *(const XLAS u32x4*)(stg + row * 64 + ch * 8); *(u32x4*)(Ow + (size_t)row * 1024 + c * 64 + ch * 8) = v; }
;         asm volatile("s_waitcnt lgkmcnt(0)" ::: "memory");
;         if (c < 3) X_STOREV(nbuf);
;         __syncthreads();
;     }
	v_mfma_f32_32x32x16_bf16 v[0:15], v[36:39], v[44:47], v[0:15]
	ds_read_b128 v[36:39], v104 offset:63488
	ds_read_b128 v[40:43], v104 offset:64000
	s_waitcnt lgkmcnt(1)
	v_mfma_f32_32x32x16_bf16 v[16:31], v[32:35], v[36:39], v[16:31]
	s_waitcnt lgkmcnt(0)
	v_mfma_f32_32x32x16_bf16 v[0:15], v[32:35], v[40:43], v[0:15]
	s_nop 9
	v_mul_f32_e32 v16, v121, v16
	v_cvt_pk_bf16_f32 v16, v16, v177
	ds_write_b16 v109, v16
	v_mul_f32_e32 v0, v121, v0
	v_cvt_pk_bf16_f32 v0, v0, v177
	ds_write_b16 v109, v0 offset:64
	v_mul_f32_e32 v0, v120, v17
	v_cvt_pk_bf16_f32 v0, v0, v177
	ds_write_b16 v109, v0 offset:128
	v_mul_f32_e32 v0, v120, v1
	v_cvt_pk_bf16_f32 v0, v0, v177
	ds_write_b16 v109, v0 offset:192
	v_mul_f32_e32 v0, v119, v18
	v_cvt_pk_bf16_f32 v0, v0, v177
	ds_write_b16 v109, v0 offset:256
	v_mul_f32_e32 v0, v119, v2
	v_cvt_pk_bf16_f32 v0, v0, v177
	ds_write_b16 v109, v0 offset:320
	v_mul_f32_e32 v0, v118, v19
	v_cvt_pk_bf16_f32 v0, v0, v177
	ds_write_b16 v109, v0 offset:384
	v_mul_f32_e32 v0, v118, v3
	v_cvt_pk_bf16_f32 v0, v0, v177
	ds_write_b16 v109, v0 offset:448
	v_mul_f32_e32 v0, v117, v20
	v_cvt_pk_bf16_f32 v0, v0, v177
	ds_write_b16 v109, v0 offset:1024
	v_mul_f32_e32 v0, v117, v4
	v_cvt_pk_bf16_f32 v0, v0, v177
	ds_write_b16 v109, v0 offset:1088
	v_mul_f32_e32 v0, v116, v21
	v_cvt_pk_bf16_f32 v0, v0, v177
	ds_write_b16 v109, v0 offset:1152
	v_mul_f32_e32 v0, v116, v5
	v_cvt_pk_bf16_f32 v0, v0, v177
	ds_write_b16 v109, v0 offset:1216
	v_mul_f32_e32 v0, v115, v22
	v_cvt_pk_bf16_f32 v0, v0, v177
	ds_write_b16 v109, v0 offset:1280
	v_mul_f32_e32 v0, v115, v6
	v_cvt_pk_bf16_f32 v0, v0, v177
	ds_write_b16 v109, v0 offset:1344
	v_mul_f32_e32 v0, v113, v23
	v_cvt_pk_bf16_f32 v0, v0, v177
	ds_write_b16 v109, v0 offset:1408
	v_mul_f32_e32 v0, v113, v7
	v_cvt_pk_bf16_f32 v0, v0, v177
	ds_write_b16 v109, v0 offset:1472
	v_mul_f32_e32 v0, v114, v24
	v_cvt_pk_bf16_f32 v0, v0, v177
	ds_write_b16 v109, v0 offset:2048
	v_mul_f32_e32 v0, v114, v8
	v_cvt_pk_bf16_f32 v0, v0, v177
	ds_write_b16 v109, v0 offset:2112
	v_mul_f32_e32 v0, v112, v25
	v_cvt_pk_bf16_f32 v0, v0, v177
	ds_write_b16 v109, v0 offset:2176
	v_mul_f32_e32 v0, v112, v9
	v_cvt_pk_bf16_f32 v0, v0, v177
	ds_write_b16 v109, v0 offset:2240
	v_mul_f32_e32 v0, v111, v26
	v_cvt_pk_bf16_f32 v0, v0, v177
	ds_write_b16 v109, v0 offset:2304
	v_mul_f32_e32 v0, v111, v10
	v_cvt_pk_bf16_f32 v0, v0, v177
	ds_write_b16 v109, v0 offset:2368
	v_mul_f32_e32 v0, v110, v27
	v_cvt_pk_bf16_f32 v0, v0, v177
	ds_write_b16 v109, v0 offset:2432
	v_mul_f32_e32 v0, v110, v11
	v_cvt_pk_bf16_f32 v0, v0, v177
	ds_write_b16 v109, v0 offset:2496
	v_mul_f32_e32 v0, v108, v28
	v_cvt_pk_bf16_f32 v0, v0, v177
	ds_write_b16 v109, v0 offset:3072
	v_mul_f32_e32 v0, v108, v12
	v_cvt_pk_bf16_f32 v0, v0, v177
	ds_write_b16 v109, v0 offset:3136
	v_mul_f32_e32 v0, v107, v29
	v_cvt_pk_bf16_f32 v0, v0, v177
	ds_write_b16 v109, v0 offset:3200
	v_mul_f32_e32 v0, v107, v13
	v_cvt_pk_bf16_f32 v0, v0, v177
	ds_write_b16 v109, v0 offset:3264
	v_mul_f32_e32 v0, v106, v30
	v_cvt_pk_bf16_f32 v0, v0, v177
	ds_write_b16 v109, v0 offset:3328
	v_mul_f32_e32 v0, v106, v14
	v_cvt_pk_bf16_f32 v0, v0, v177
	ds_write_b16 v109, v0 offset:3392
	v_mul_f32_e32 v0, v105, v31
	v_cvt_pk_bf16_f32 v0, v0, v177
	ds_write_b16 v109, v0 offset:3456
	v_mul_f32_e32 v0, v105, v15
	v_cvt_pk_bf16_f32 v0, v0, v177
	ds_write_b16 v109, v0 offset:3520
	s_waitcnt lgkmcnt(0)
	ds_read_b128 v[0:3], v122
	ds_read_b128 v[4:7], v123
	ds_read_b128 v[8:11], v124
	ds_read_b128 v[12:15], v125
	s_waitcnt lgkmcnt(3)
	global_store_dwordx4 v[96:97], v[0:3], off offset:384 sc1
	s_waitcnt lgkmcnt(2)
	global_store_dwordx4 v[98:99], v[4:7], off offset:384 sc1
	s_waitcnt lgkmcnt(1)
	global_store_dwordx4 v[100:101], v[8:11], off offset:384 sc1
	s_waitcnt lgkmcnt(0)
	global_store_dwordx4 v[102:103], v[12:15], off offset:384 sc1
	s_waitcnt lgkmcnt(0)
	s_barrier
	s_cbranch_scc0 .LBB0_1147

; __device__ __forceinline__ unsigned xb_ld(unsigned* p)              { return __hip_atomic_load(p, __ATOMIC_RELAXED, __HIP_MEMORY_SCOPE_AGENT); }
; __device__ __forceinline__ unsigned xb_add(unsigned* p, unsigned v) { return __hip_atomic_fetch_add(p, v, __ATOMIC_RELAXED, __HIP_MEMORY_SCOPE_AGENT); }
; #define XB_SPIN(cond, bar) do { unsigned _sp = 0; while (cond) { __builtin_amdgcn_s_sleep(1); \
;     if ((++_sp & 255u) == 0u) { if (xb_ld(&(bar)[XB_TMO])) break; if (_sp > XB_SPIN_CAP) { atomicAdd(&(bar)[XB_TMO], 1u); break; } } } } while (0)
; #define SEAM(k) do { if (IN(k) && IN((k) + 1)) { xcd_barrier(bar, wave == 0 && mk_lane() == 0); } } while (0)
; __device__ __forceinline__ void xcd_barrier(const XcdBarrier& b, bool leader) {
;     asm volatile("s_waitcnt vmcnt(0)" ::: "memory");
;     __syncthreads();
;     if (leader) {
;         unsigned* bar = b.bar;
;         __builtin_amdgcn_s_waitcnt(0);
;         unsigned nloc = b.st[0], nx = b.st[1];
;         if (nloc == 0u) { xcd_barrier_complete(bar, b.x, nloc, nx); b.st[0] = nloc; b.st[1] = nx; }
;         const unsigned old = xb_add(&bar[XB_XSUB(b.x)], 1u);
;         const unsigned gen = old / nloc;
;         if (old + 1u == (gen + 1u) * nloc) {
;             __builtin_amdgcn_fence(__ATOMIC_RELEASE, "agent");
;             asm volatile("s_waitcnt vmcnt(0)" ::: "memory");
;             const unsigned og = xb_add(&bar[XB_TOP], 1u);
;             const unsigned tg = og / nx;
;             if (og + 1u == (tg + 1u) * nx) xb_add(&bar[XB_TOPGEN], 1u);
;             else XB_SPIN(xb_ld(&bar[XB_TOPGEN]) == tg, bar);
;             __builtin_amdgcn_fence(__ATOMIC_ACQUIRE, "agent");
;             xb_add(&bar[XB_XGEN(b.x)], 1u);
;             asm volatile("s_waitcnt vmcnt(0)" ::: "memory");
;         } else {
;             XB_SPIN(xb_ld(&bar[XB_XGEN(b.x)]) == gen, bar);
;             __builtin_amdgcn_fence(__ATOMIC_ACQUIRE, "agent");
;             asm volatile("s_waitcnt vmcnt(0)" ::: "memory");
;         }
;     }
;     __syncthreads();
; }
; __global__ void __launch_bounds__(NWAVES * 64, 2) mk_fwd(Params P) {
;     ...
;         pg8::EpiRes2<true, true> E{H1B, H2B, SS2};
;         pg8::gemm_phase<pg8::EpiRes2<true, true>, pg8::StaticOrder, true, true>(lds, g, S, E, wave); }
;     SEAM(7);
.LBB0_1238:
	s_cmp_gt_i32 s75, 8
	s_cselect_b64 s[4:5], -1, 0
	s_and_b64 s[0:1], s[0:1], s[4:5]
	s_andn2_b64 vcc, exec, s[0:1]
	s_cbranch_vccnz .LBB0_1290
	v_readlane_b32 s0, v254, 4
	v_readlane_b32 s1, v254, 5
	s_and_b64 vcc, exec, s[0:1]
	s_mov_b64 s[6:7], 0
	s_cbranch_vccnz .LBB0_1241
	v_mov_b32_e32 v0, v212
	s_nop 0
	v_cmp_eq_u32_e32 vcc, 0, v0
	s_and_b64 s[6:7], vcc, exec
.LBB0_1241:
	s_waitcnt vmcnt(0)
	s_waitcnt vmcnt(0) lgkmcnt(0)
	s_barrier
	s_and_saveexec_b64 s[0:1], s[6:7]
	s_cbranch_execz .LBB0_1289
	v_readlane_b32 s8, v254, 2
	v_readlane_b32 s9, v254, 3
	s_and_b32 s2, s88, 7
	s_lshl_b32 s2, s2, 8
	s_add_u32 s2, s8, s2
	s_addc_u32 s3, s9, 0
	v_mov_b32_e32 v0, 0
	v_mov_b32_e32 v1, 1
	v_mov_b32_e32 v5, 0x1400
	global_load_dwordx4 v[6:9], v0, s[8:9] offset:768 sc1
	global_load_dwordx4 v[10:13], v0, s[8:9] offset:784 sc1
	global_atomic_add v3, v5, v1, s[2:3] offset:128 sc0
	s_waitcnt vmcnt(0)
	v_add_u32_e32 v14, -1, v6
	v_and_b32_e32 v2, v14, v6
	v_add_u32_e32 v14, -1, v7
	v_and_or_b32 v2, v14, v7, v2
	v_add_u32_e32 v14, -1, v8
	v_and_or_b32 v2, v14, v8, v2
	v_add_u32_e32 v14, -1, v9
	v_and_or_b32 v2, v14, v9, v2
	v_add_u32_e32 v14, -1, v10
	v_and_or_b32 v2, v14, v10, v2
	v_add_u32_e32 v14, -1, v11
	v_and_or_b32 v2, v14, v11, v2
	v_add_u32_e32 v14, -1, v12
	v_and_or_b32 v2, v14, v12, v2
	v_add_u32_e32 v14, -1, v13
	v_and_or_b32 v2, v14, v13, v2
	v_cmp_ne_u32_e32 vcc, 0, v2
	s_cbranch_vccnz .Lmy_glob_k7
	v_and_b32_e32 v4, 0xffffffe0, v3
	v_add_u32_e32 v4, 32, v4
	v_add_u32_e32 v3, 1, v3
	v_cmp_eq_u32_e32 vcc, v3, v4
	s_cbranch_vccnz .Lmy_done_k7
	s_mov_b32 s10, 0

; __device__ __forceinline__ unsigned xb_ld(unsigned* p)              { return __hip_atomic_load(p, __ATOMIC_RELAXED, __HIP_MEMORY_SCOPE_AGENT); }
; __device__ __forceinline__ unsigned xb_add(unsigned* p, unsigned v) { return __hip_atomic_fetch_add(p, v, __ATOMIC_RELAXED, __HIP_MEMORY_SCOPE_AGENT); }
; #define XB_SPIN(cond, bar) do { unsigned _sp = 0; while (cond) { __builtin_amdgcn_s_sleep(1); \
;     if ((++_sp & 255u) == 0u) { if (xb_ld(&(bar)[XB_TMO])) break; if (_sp > XB_SPIN_CAP) { atomicAdd(&(bar)[XB_TMO], 1u); break; } } } } while (0)
; #define SEAM(k) do { if (IN(k) && IN((k) + 1)) { xcd_barrier(bar, wave == 0 && mk_lane() == 0); } } while (0)
; __device__ __forceinline__ void xcd_barrier(const XcdBarrier& b, bool leader) {
;     asm volatile("s_waitcnt vmcnt(0)" ::: "memory");
;     __syncthreads();
;     if (leader) {
;         unsigned* bar = b.bar;
;         __builtin_amdgcn_s_waitcnt(0);
;         unsigned nloc = b.st[0], nx = b.st[1];
;         if (nloc == 0u) { xcd_barrier_complete(bar, b.x, nloc, nx); b.st[0] = nloc; b.st[1] = nx; }
;         const unsigned old = xb_add(&bar[XB_XSUB(b.x)], 1u);
;         const unsigned gen = old / nloc;
;         if (old + 1u == (gen + 1u) * nloc) {
;             __builtin_amdgcn_fence(__ATOMIC_RELEASE, "agent");
;             asm volatile("s_waitcnt vmcnt(0)" ::: "memory");
;             const unsigned og = xb_add(&bar[XB_TOP], 1u);
;             const unsigned tg = og / nx;
;             if (og + 1u == (tg + 1u) * nx) xb_add(&bar[XB_TOPGEN], 1u);
;             else XB_SPIN(xb_ld(&bar[XB_TOPGEN]) == tg, bar);
;             __builtin_amdgcn_fence(__ATOMIC_ACQUIRE, "agent");
;             xb_add(&bar[XB_XGEN(b.x)], 1u);
;             asm volatile("s_waitcnt vmcnt(0)" ::: "memory");
;         } else {
;             XB_SPIN(xb_ld(&bar[XB_XGEN(b.x)]) == gen, bar);
;             __builtin_amdgcn_fence(__ATOMIC_ACQUIRE, "agent");
;             asm volatile("s_waitcnt vmcnt(0)" ::: "memory");
;         }
;     }
;     __syncthreads();
; }
; __global__ void __launch_bounds__(NWAVES * 64, 2) mk_fwd(Params P) {
;     ...
;         pg8::EpiRes2<true, true> E{H1B, H2B, SS2};
;         pg8::gemm_phase<pg8::EpiRes2<true, true>, pg8::StaticOrder, true, true>(lds, g, S, E, wave); }
;     SEAM(7);
.Lmy_done_k7:
	s_and_b32 s11, s88, 7
	s_movk_i32 s12, 0x60
	s_movk_i32 s13, 0x60
	s_cmp_eq_u32 s11, 3
	s_cselect_b32 s12, 0xe0, s12
	s_cmp_eq_u32 s11, 4
	s_cselect_b32 s13, 0xe0, s13
	s_mov_b32 s10, 0
.Lmy_xw_k7:
	global_load_dword v6, v5, s[8:9] offset:128 sc1
	global_load_dword v7, v5, s[8:9] offset:384 sc1
	global_load_dword v8, v5, s[8:9] offset:640 sc1
	global_load_dword v9, v5, s[8:9] offset:896 sc1
	global_load_dword v10, v5, s[8:9] offset:1152 sc1
	global_load_dword v11, v5, s[8:9] offset:1408 sc1
	global_load_dword v12, v5, s[8:9] offset:1664 sc1
	global_load_dword v13, v5, s[8:9] offset:1920 sc1
	s_waitcnt vmcnt(0)
	v_min_u32_e32 v2, v6, v7
	v_min3_u32 v2, v2, v8, v9
	v_min_u32_e32 v3, v10, v11
	v_min3_u32 v3, v3, v12, v13
	v_cmp_gt_u32_e32 vcc, s12, v2
	s_cbranch_vccnz .Lmy_xr_k7
	v_cmp_gt_u32_e32 vcc, s13, v3
	s_cbranch_vccz .Lmy_xok_k7
.Lmy_xr_k7:
	s_sleep 1
	s_add_i32 s10, s10, 1
	s_cmp_lt_u32 s10, 0x100000
	s_cbranch_scc1 .Lmy_xw_k7
